# removed compiler-inserted vmcnt(0) before ds_reads inside the seven 8-phase GEMM K-loops (authors counted vmcnt(6) pipelining restored)
# speedup vs baseline: 1.0621x; 1.0621x over previous
.LBB0_34:
	ds_read_b128 v[164:167], v151
	ds_read_b128 v[168:171], v151 offset:1024
	ds_read_b128 v[172:175], v151 offset:2048
	ds_read_b128 v[176:179], v151 offset:3072
	v_add_u32_e32 v162, 0xc000, v147
	v_lshl_add_u64 v[204:205], v[138:139], 0, s[12:13]
	v_readfirstlane_b32 s1, v162
	v_lshl_add_u64 v[210:211], v[204:205], 0, s[60:61]
	s_mov_b32 m0, s1
	v_add_u32_e32 v163, 0xe000, v147
	ds_read_b128 v[180:183], v0
	ds_read_b128 v[184:187], v0 offset:1024
	ds_read_b128 v[188:191], v0 offset:2048
	ds_read_b128 v[192:195], v0 offset:3072
	ds_read_b128 v[196:199], v0 offset:4096
	ds_read_b128 v[200:203], v0 offset:5120
	ds_read_b128 v[222:225], v0 offset:6144
	ds_read_b128 v[232:235], v0 offset:7168
	global_load_lds_dwordx4 v[210:211], off
	v_lshl_add_u64 v[210:211], v[140:141], 0, s[12:13]
	v_readfirstlane_b32 s1, v163
	v_lshl_add_u64 v[216:217], v[210:211], 0, s[60:61]
	s_mov_b32 m0, s1
	s_nop 0
	global_load_lds_dwordx4 v[216:217], off
	s_waitcnt lgkmcnt(8)
	s_barrier
	s_waitcnt lgkmcnt(0)
	s_setprio 1
	s_waitcnt lgkmcnt(0)
	v_mfma_f32_16x16x32_bf16 v[126:129], v[164:167], v[180:183], v[126:129]
	v_mfma_f32_16x16x32_bf16 v[122:125], v[172:175], v[180:183], v[122:125]
	v_mfma_f32_16x16x32_bf16 v[118:121], v[164:167], v[188:191], v[118:121]
	v_mfma_f32_16x16x32_bf16 v[114:117], v[172:175], v[188:191], v[114:117]
	v_mfma_f32_16x16x32_bf16 v[110:113], v[164:167], v[196:199], v[110:113]
	v_mfma_f32_16x16x32_bf16 v[106:109], v[172:175], v[196:199], v[106:109]
	v_mfma_f32_16x16x32_bf16 v[102:105], v[164:167], v[222:225], v[102:105]
	v_mfma_f32_16x16x32_bf16 v[98:101], v[172:175], v[222:225], v[98:101]
	v_mfma_f32_16x16x32_bf16 v[126:129], v[168:171], v[184:187], v[126:129]
	v_mfma_f32_16x16x32_bf16 v[122:125], v[176:179], v[184:187], v[122:125]
	v_mfma_f32_16x16x32_bf16 v[118:121], v[168:171], v[192:195], v[118:121]
	v_mfma_f32_16x16x32_bf16 v[114:117], v[176:179], v[192:195], v[114:117]
	v_mfma_f32_16x16x32_bf16 v[110:113], v[168:171], v[200:203], v[110:113]
	v_mfma_f32_16x16x32_bf16 v[106:109], v[176:179], v[200:203], v[106:109]
	v_mfma_f32_16x16x32_bf16 v[102:105], v[168:171], v[232:235], v[102:105]
	v_mfma_f32_16x16x32_bf16 v[98:101], v[176:179], v[232:235], v[98:101]
	s_setprio 0
	s_barrier
	v_lshl_add_u64 v[216:217], v[134:135], 0, s[12:13]
	v_readfirstlane_b32 s1, v149
	v_lshl_add_u64 v[218:219], v[216:217], 0, s[74:75]
	s_mov_b32 m0, s1
	ds_read_b128 v[236:239], v151 offset:16384
	ds_read_b128 v[240:243], v151 offset:17408
	ds_read_b128 v[244:247], v151 offset:18432
	ds_read_b128 v[248:251], v151 offset:19456
	global_load_lds_dwordx4 v[218:219], off
	v_lshl_add_u64 v[218:219], v[136:137], 0, s[12:13]
	v_readfirstlane_b32 s1, v150
	v_lshl_add_u64 v[228:229], v[218:219], 0, s[74:75]
	s_mov_b32 m0, s1
	s_nop 0
	global_load_lds_dwordx4 v[228:229], off
	s_barrier
	s_waitcnt lgkmcnt(0)
	s_setprio 1
	s_waitcnt lgkmcnt(0)
	v_mfma_f32_16x16x32_bf16 v[94:97], v[236:239], v[180:183], v[94:97]
	v_mfma_f32_16x16x32_bf16 v[90:93], v[244:247], v[180:183], v[90:93]
	v_mfma_f32_16x16x32_bf16 v[86:89], v[236:239], v[188:191], v[86:89]
	v_mfma_f32_16x16x32_bf16 v[70:73], v[244:247], v[188:191], v[70:73]
	v_mfma_f32_16x16x32_bf16 v[62:65], v[236:239], v[196:199], v[62:65]
	v_mfma_f32_16x16x32_bf16 v[58:61], v[244:247], v[196:199], v[58:61]
	v_mfma_f32_16x16x32_bf16 v[54:57], v[236:239], v[222:225], v[54:57]
	v_mfma_f32_16x16x32_bf16 v[50:53], v[244:247], v[222:225], v[50:53]
	v_mfma_f32_16x16x32_bf16 v[94:97], v[240:243], v[184:187], v[94:97]
	v_mfma_f32_16x16x32_bf16 v[90:93], v[248:251], v[184:187], v[90:93]
	v_mfma_f32_16x16x32_bf16 v[86:89], v[240:243], v[192:195], v[86:89]
	v_mfma_f32_16x16x32_bf16 v[70:73], v[248:251], v[192:195], v[70:73]
	v_mfma_f32_16x16x32_bf16 v[62:65], v[240:243], v[200:203], v[62:65]
	v_mfma_f32_16x16x32_bf16 v[58:61], v[248:251], v[200:203], v[58:61]
	v_mfma_f32_16x16x32_bf16 v[54:57], v[240:243], v[232:235], v[54:57]
	v_mfma_f32_16x16x32_bf16 v[50:53], v[248:251], v[232:235], v[50:53]
	s_setprio 0
	v_readfirstlane_b32 s1, v147
	v_lshl_add_u64 v[228:229], v[204:205], 0, s[74:75]
	s_mov_b32 m0, s1
	v_readfirstlane_b32 s1, v148
	s_barrier
	ds_read_b128 v[180:183], v0 offset:16384
	ds_read_b128 v[184:187], v0 offset:17408
	ds_read_b128 v[188:191], v0 offset:18432
	ds_read_b128 v[192:195], v0 offset:19456
	ds_read_b128 v[196:199], v0 offset:20480
	ds_read_b128 v[200:203], v0 offset:21504
	ds_read_b128 v[222:225], v0 offset:22528
	ds_read_b128 v[232:235], v0 offset:23552
	global_load_lds_dwordx4 v[228:229], off
	v_lshl_add_u64 v[228:229], v[210:211], 0, s[74:75]
	s_mov_b32 m0, s1
	s_nop 0
	global_load_lds_dwordx4 v[228:229], off
	s_barrier
	s_waitcnt lgkmcnt(0)
	s_setprio 1
	s_waitcnt lgkmcnt(0)
	v_mfma_f32_16x16x32_bf16 v[46:49], v[164:167], v[180:183], v[46:49]
	v_mfma_f32_16x16x32_bf16 v[42:45], v[172:175], v[180:183], v[42:45]
	v_mfma_f32_16x16x32_bf16 v[38:41], v[164:167], v[188:191], v[38:41]
	v_mfma_f32_16x16x32_bf16 v[34:37], v[172:175], v[188:191], v[34:37]
	v_mfma_f32_16x16x32_bf16 v[30:33], v[164:167], v[196:199], v[30:33]
	v_mfma_f32_16x16x32_bf16 v[26:29], v[172:175], v[196:199], v[26:29]
	v_mfma_f32_16x16x32_bf16 v[22:25], v[164:167], v[222:225], v[22:25]
	v_mfma_f32_16x16x32_bf16 v[18:21], v[172:175], v[222:225], v[18:21]
	v_mfma_f32_16x16x32_bf16 v[46:49], v[168:171], v[184:187], v[46:49]
	v_mfma_f32_16x16x32_bf16 v[42:45], v[176:179], v[184:187], v[42:45]
	v_mfma_f32_16x16x32_bf16 v[38:41], v[168:171], v[192:195], v[38:41]
	v_mfma_f32_16x16x32_bf16 v[34:37], v[176:179], v[192:195], v[34:37]
	v_mfma_f32_16x16x32_bf16 v[30:33], v[168:171], v[200:203], v[30:33]
	v_mfma_f32_16x16x32_bf16 v[26:29], v[176:179], v[200:203], v[26:29]
	v_mfma_f32_16x16x32_bf16 v[22:25], v[168:171], v[232:235], v[22:25]
	v_mfma_f32_16x16x32_bf16 v[18:21], v[176:179], v[232:235], v[18:21]
	s_setprio 0
	s_barrier
	v_readfirstlane_b32 s1, v152
	v_lshl_add_u64 v[164:165], v[216:217], 0, s[18:19]
	s_mov_b32 m0, s1
	v_readfirstlane_b32 s1, v153
	global_load_lds_dwordx4 v[164:165], off
	v_lshl_add_u64 v[164:165], v[218:219], 0, s[18:19]
	s_mov_b32 m0, s1
	s_nop 0
	global_load_lds_dwordx4 v[164:165], off
	s_waitcnt vmcnt(6)
	s_barrier
	s_setprio 1
	v_mfma_f32_16x16x32_bf16 v[14:17], v[236:239], v[180:183], v[14:17]
	v_mfma_f32_16x16x32_bf16 v[10:13], v[244:247], v[180:183], v[10:13]
	v_mfma_f32_16x16x32_bf16 v[6:9], v[236:239], v[188:191], v[6:9]
	v_mfma_f32_16x16x32_bf16 v[2:5], v[244:247], v[188:191], v[2:5]
	v_mfma_f32_16x16x32_bf16 v[66:69], v[236:239], v[196:199], v[66:69]
	v_mfma_f32_16x16x32_bf16 v[74:77], v[244:247], v[196:199], v[74:77]
	v_mfma_f32_16x16x32_bf16 v[78:81], v[236:239], v[222:225], v[78:81]
	v_mfma_f32_16x16x32_bf16 v[82:85], v[244:247], v[222:225], v[82:85]
	v_mfma_f32_16x16x32_bf16 v[14:17], v[240:243], v[184:187], v[14:17]
	v_mfma_f32_16x16x32_bf16 v[10:13], v[248:251], v[184:187], v[10:13]
	v_mfma_f32_16x16x32_bf16 v[6:9], v[240:243], v[192:195], v[6:9]
	v_mfma_f32_16x16x32_bf16 v[2:5], v[248:251], v[192:195], v[2:5]
	v_mfma_f32_16x16x32_bf16 v[66:69], v[240:243], v[200:203], v[66:69]
	v_mfma_f32_16x16x32_bf16 v[74:77], v[248:251], v[200:203], v[74:77]
	v_mfma_f32_16x16x32_bf16 v[78:81], v[240:243], v[232:235], v[78:81]
	v_mfma_f32_16x16x32_bf16 v[82:85], v[248:251], v[232:235], v[82:85]
	s_setprio 0
	s_barrier
	ds_read_b128 v[164:167], v151 offset:32768
	ds_read_b128 v[168:171], v151 offset:33792
	ds_read_b128 v[172:175], v151 offset:34816
	ds_read_b128 v[176:179], v151 offset:35840
	v_readfirstlane_b32 s1, v154
	v_lshl_add_u64 v[228:229], v[204:205], 0, s[18:19]
	s_mov_b32 m0, s1
	v_readfirstlane_b32 s1, v155
	ds_read_b128 v[180:183], v0 offset:32768
	ds_read_b128 v[184:187], v0 offset:33792
	ds_read_b128 v[188:191], v0 offset:34816
	ds_read_b128 v[192:195], v0 offset:35840
	ds_read_b128 v[196:199], v0 offset:36864
	ds_read_b128 v[200:203], v0 offset:37888
	ds_read_b128 v[222:225], v0 offset:38912
	ds_read_b128 v[232:235], v0 offset:39936
	global_load_lds_dwordx4 v[228:229], off
	v_lshl_add_u64 v[228:229], v[210:211], 0, s[18:19]
	s_mov_b32 m0, s1
	s_nop 0
	global_load_lds_dwordx4 v[228:229], off
	s_waitcnt lgkmcnt(8)
	s_barrier
	s_waitcnt lgkmcnt(0)
	s_setprio 1
	s_waitcnt lgkmcnt(0)
	v_mfma_f32_16x16x32_bf16 v[126:129], v[164:167], v[180:183], v[126:129]
	v_mfma_f32_16x16x32_bf16 v[122:125], v[172:175], v[180:183], v[122:125]
	v_mfma_f32_16x16x32_bf16 v[118:121], v[164:167], v[188:191], v[118:121]
	v_mfma_f32_16x16x32_bf16 v[114:117], v[172:175], v[188:191], v[114:117]
	v_mfma_f32_16x16x32_bf16 v[110:113], v[164:167], v[196:199], v[110:113]
	v_mfma_f32_16x16x32_bf16 v[106:109], v[172:175], v[196:199], v[106:109]
	v_mfma_f32_16x16x32_bf16 v[102:105], v[164:167], v[222:225], v[102:105]
	v_mfma_f32_16x16x32_bf16 v[98:101], v[172:175], v[222:225], v[98:101]
	v_mfma_f32_16x16x32_bf16 v[126:129], v[168:171], v[184:187], v[126:129]
	v_mfma_f32_16x16x32_bf16 v[122:125], v[176:179], v[184:187], v[122:125]
	v_mfma_f32_16x16x32_bf16 v[118:121], v[168:171], v[192:195], v[118:121]
	v_mfma_f32_16x16x32_bf16 v[114:117], v[176:179], v[192:195], v[114:117]
	v_mfma_f32_16x16x32_bf16 v[110:113], v[168:171], v[200:203], v[110:113]
	v_mfma_f32_16x16x32_bf16 v[106:109], v[176:179], v[200:203], v[106:109]
	v_mfma_f32_16x16x32_bf16 v[102:105], v[168:171], v[232:235], v[102:105]
	v_mfma_f32_16x16x32_bf16 v[98:101], v[176:179], v[232:235], v[98:101]
	s_setprio 0
	s_barrier
	v_readfirstlane_b32 s1, v156
	v_lshl_add_u64 v[228:229], v[216:217], 0, s[28:29]
	s_mov_b32 m0, s1
	v_readfirstlane_b32 s1, v157
	ds_read_b128 v[236:239], v151 offset:49152
	ds_read_b128 v[240:243], v151 offset:50176
	ds_read_b128 v[244:247], v151 offset:51200
	ds_read_b128 v[248:251], v151 offset:52224
	global_load_lds_dwordx4 v[228:229], off
	v_lshl_add_u64 v[228:229], v[218:219], 0, s[28:29]
	s_mov_b32 m0, s1
	s_nop 0
	global_load_lds_dwordx4 v[228:229], off
	s_barrier
	s_waitcnt lgkmcnt(0)
	s_setprio 1
	s_waitcnt lgkmcnt(0)
	v_mfma_f32_16x16x32_bf16 v[94:97], v[236:239], v[180:183], v[94:97]
	v_mfma_f32_16x16x32_bf16 v[90:93], v[244:247], v[180:183], v[90:93]
	v_mfma_f32_16x16x32_bf16 v[86:89], v[236:239], v[188:191], v[86:89]
	v_mfma_f32_16x16x32_bf16 v[70:73], v[244:247], v[188:191], v[70:73]
	v_mfma_f32_16x16x32_bf16 v[62:65], v[236:239], v[196:199], v[62:65]
	v_mfma_f32_16x16x32_bf16 v[58:61], v[244:247], v[196:199], v[58:61]
	v_mfma_f32_16x16x32_bf16 v[54:57], v[236:239], v[222:225], v[54:57]
	v_mfma_f32_16x16x32_bf16 v[50:53], v[244:247], v[222:225], v[50:53]
	v_mfma_f32_16x16x32_bf16 v[94:97], v[240:243], v[184:187], v[94:97]
	v_mfma_f32_16x16x32_bf16 v[90:93], v[248:251], v[184:187], v[90:93]
	v_mfma_f32_16x16x32_bf16 v[86:89], v[240:243], v[192:195], v[86:89]
	v_mfma_f32_16x16x32_bf16 v[70:73], v[248:251], v[192:195], v[70:73]
	v_mfma_f32_16x16x32_bf16 v[62:65], v[240:243], v[200:203], v[62:65]
	v_mfma_f32_16x16x32_bf16 v[58:61], v[248:251], v[200:203], v[58:61]
	v_mfma_f32_16x16x32_bf16 v[54:57], v[240:243], v[232:235], v[54:57]
	v_mfma_f32_16x16x32_bf16 v[50:53], v[248:251], v[232:235], v[50:53]
	s_setprio 0
	v_readfirstlane_b32 s1, v158
	v_lshl_add_u64 v[204:205], v[204:205], 0, s[28:29]
	s_mov_b32 m0, s1
	v_readfirstlane_b32 s1, v159
	s_barrier
	ds_read_b128 v[180:183], v0 offset:49152
	ds_read_b128 v[184:187], v0 offset:50176
	ds_read_b128 v[188:191], v0 offset:51200
	ds_read_b128 v[192:195], v0 offset:52224
	ds_read_b128 v[196:199], v0 offset:53248
	ds_read_b128 v[200:203], v0 offset:54272
	ds_read_b128 v[222:225], v0 offset:55296
	ds_read_b128 v[232:235], v0 offset:56320
	global_load_lds_dwordx4 v[204:205], off
	v_lshl_add_u64 v[204:205], v[210:211], 0, s[28:29]
	s_mov_b32 m0, s1
	s_nop 0
	global_load_lds_dwordx4 v[204:205], off
	s_barrier
	s_waitcnt lgkmcnt(0)
	s_setprio 1
	s_waitcnt lgkmcnt(0)
	v_mfma_f32_16x16x32_bf16 v[46:49], v[164:167], v[180:183], v[46:49]
	v_mfma_f32_16x16x32_bf16 v[42:45], v[172:175], v[180:183], v[42:45]
	v_mfma_f32_16x16x32_bf16 v[38:41], v[164:167], v[188:191], v[38:41]
	v_mfma_f32_16x16x32_bf16 v[34:37], v[172:175], v[188:191], v[34:37]
	v_mfma_f32_16x16x32_bf16 v[30:33], v[164:167], v[196:199], v[30:33]
	v_mfma_f32_16x16x32_bf16 v[26:29], v[172:175], v[196:199], v[26:29]
	v_mfma_f32_16x16x32_bf16 v[22:25], v[164:167], v[222:225], v[22:25]
	v_mfma_f32_16x16x32_bf16 v[18:21], v[172:175], v[222:225], v[18:21]
	v_mfma_f32_16x16x32_bf16 v[46:49], v[168:171], v[184:187], v[46:49]
	v_mfma_f32_16x16x32_bf16 v[42:45], v[176:179], v[184:187], v[42:45]
	v_mfma_f32_16x16x32_bf16 v[38:41], v[168:171], v[192:195], v[38:41]
	v_mfma_f32_16x16x32_bf16 v[34:37], v[176:179], v[192:195], v[34:37]
	v_mfma_f32_16x16x32_bf16 v[30:33], v[168:171], v[200:203], v[30:33]
	v_mfma_f32_16x16x32_bf16 v[26:29], v[176:179], v[200:203], v[26:29]
	v_mfma_f32_16x16x32_bf16 v[22:25], v[168:171], v[232:235], v[22:25]
	v_mfma_f32_16x16x32_bf16 v[18:21], v[176:179], v[232:235], v[18:21]
	s_setprio 0
	s_barrier
	v_readfirstlane_b32 s1, v160
	v_lshl_add_u64 v[164:165], v[216:217], 0, s[30:31]
	s_mov_b32 m0, s1
	v_readfirstlane_b32 s1, v161
	global_load_lds_dwordx4 v[164:165], off
	v_lshl_add_u64 v[164:165], v[218:219], 0, s[30:31]
	s_mov_b32 m0, s1
	s_nop 0
	global_load_lds_dwordx4 v[164:165], off
	s_waitcnt vmcnt(6)
	s_barrier
	s_setprio 1
	v_mfma_f32_16x16x32_bf16 v[14:17], v[236:239], v[180:183], v[14:17]
	v_mfma_f32_16x16x32_bf16 v[10:13], v[244:247], v[180:183], v[10:13]
	v_mfma_f32_16x16x32_bf16 v[6:9], v[236:239], v[188:191], v[6:9]
	v_mfma_f32_16x16x32_bf16 v[2:5], v[244:247], v[188:191], v[2:5]
	v_mfma_f32_16x16x32_bf16 v[66:69], v[236:239], v[196:199], v[66:69]
	v_mfma_f32_16x16x32_bf16 v[74:77], v[244:247], v[196:199], v[74:77]
	v_mfma_f32_16x16x32_bf16 v[78:81], v[236:239], v[222:225], v[78:81]
	v_mfma_f32_16x16x32_bf16 v[82:85], v[244:247], v[222:225], v[82:85]
	v_mfma_f32_16x16x32_bf16 v[14:17], v[240:243], v[184:187], v[14:17]
	v_mfma_f32_16x16x32_bf16 v[10:13], v[248:251], v[184:187], v[10:13]
	v_mfma_f32_16x16x32_bf16 v[6:9], v[240:243], v[192:195], v[6:9]
	v_mfma_f32_16x16x32_bf16 v[2:5], v[248:251], v[192:195], v[2:5]
	v_mfma_f32_16x16x32_bf16 v[66:69], v[240:243], v[200:203], v[66:69]
	v_mfma_f32_16x16x32_bf16 v[74:77], v[248:251], v[200:203], v[74:77]
	v_mfma_f32_16x16x32_bf16 v[78:81], v[240:243], v[232:235], v[78:81]
	v_mfma_f32_16x16x32_bf16 v[82:85], v[248:251], v[232:235], v[82:85]
	s_setprio 0
	s_add_i32 s0, s0, 2
	s_add_u32 s12, s12, 0x100
	s_addc_u32 s13, s13, 0
	s_cmp_lt_u32 s0, 28
	s_barrier
	s_cbranch_scc1 .LBB0_34
	s_mov_b64 s[12:13], 0xf80
	v_readfirstlane_b32 s0, v162
	v_lshl_add_u64 v[132:133], v[132:133], 0, s[12:13]
	s_mov_b32 m0, s0
	v_readfirstlane_b32 s0, v163
	s_waitcnt vmcnt(0)
	ds_read_b128 v[134:137], v151
	ds_read_b128 v[138:141], v151 offset:1024
	ds_read_b128 v[152:155], v151 offset:2048
	ds_read_b128 v[156:159], v151 offset:3072
	ds_read_b128 v[164:167], v0
	ds_read_b128 v[168:171], v0 offset:1024
	ds_read_b128 v[172:175], v0 offset:2048
	ds_read_b128 v[176:179], v0 offset:3072
	ds_read_b128 v[180:183], v0 offset:4096
	ds_read_b128 v[184:187], v0 offset:5120
	ds_read_b128 v[188:191], v0 offset:6144
	ds_read_b128 v[192:195], v0 offset:7168
	global_load_lds_dwordx4 v[132:133], off
	v_lshl_add_u64 v[130:131], v[130:131], 0, s[12:13]
	s_mov_b32 m0, s0
	s_nop 0
	global_load_lds_dwordx4 v[130:131], off
	s_barrier
	s_waitcnt lgkmcnt(0)
	s_setprio 1
	s_waitcnt lgkmcnt(0)
	v_mfma_f32_16x16x32_bf16 v[122:125], v[152:155], v[164:167], v[122:125]
	v_mfma_f32_16x16x32_bf16 v[118:121], v[134:137], v[172:175], v[118:121]
	v_mfma_f32_16x16x32_bf16 v[114:117], v[152:155], v[172:175], v[114:117]
	v_mfma_f32_16x16x32_bf16 v[102:105], v[134:137], v[188:191], v[102:105]
	v_mfma_f32_16x16x32_bf16 v[98:101], v[152:155], v[188:191], v[98:101]
	v_mfma_f32_16x16x32_bf16 v[126:129], v[134:137], v[164:167], v[126:129]
	v_mfma_f32_16x16x32_bf16 v[122:125], v[156:159], v[168:171], v[122:125]
	v_mfma_f32_16x16x32_bf16 v[118:121], v[138:141], v[176:179], v[118:121]
	v_mfma_f32_16x16x32_bf16 v[114:117], v[156:159], v[176:179], v[114:117]
	v_mfma_f32_16x16x32_bf16 v[110:113], v[134:137], v[180:183], v[110:113]
	v_mfma_f32_16x16x32_bf16 v[106:109], v[152:155], v[180:183], v[106:109]
	v_mfma_f32_16x16x32_bf16 v[102:105], v[138:141], v[192:195], v[102:105]
	v_mfma_f32_16x16x32_bf16 v[98:101], v[156:159], v[192:195], v[98:101]
	v_mfma_f32_16x16x32_bf16 v[126:129], v[138:141], v[168:171], v[126:129]
	v_mfma_f32_16x16x32_bf16 v[130:133], v[138:141], v[184:187], v[110:113]
	v_mfma_f32_16x16x32_bf16 v[160:163], v[156:159], v[184:187], v[106:109]
	s_setprio 0
	s_barrier
	s_waitcnt vmcnt(0)
	ds_read_b128 v[106:109], v151 offset:16384
	ds_read_b128 v[110:113], v151 offset:17408
	ds_read_b128 v[196:199], v151 offset:18432
	ds_read_b128 v[200:203], v151 offset:19456
	s_barrier
	s_waitcnt lgkmcnt(0)
	s_setprio 1
	s_waitcnt lgkmcnt(3)
	v_mfma_f32_16x16x32_bf16 v[86:89], v[106:109], v[172:175], v[86:89]
	s_waitcnt lgkmcnt(1)
	v_mfma_f32_16x16x32_bf16 v[70:73], v[196:199], v[172:175], v[70:73]
	v_mfma_f32_16x16x32_bf16 v[62:65], v[106:109], v[180:183], v[62:65]
	v_mfma_f32_16x16x32_bf16 v[58:61], v[196:199], v[180:183], v[58:61]
	v_mfma_f32_16x16x32_bf16 v[54:57], v[106:109], v[188:191], v[54:57]
	v_mfma_f32_16x16x32_bf16 v[50:53], v[196:199], v[188:191], v[50:53]
	v_mfma_f32_16x16x32_bf16 v[94:97], v[106:109], v[164:167], v[94:97]
	v_mfma_f32_16x16x32_bf16 v[90:93], v[196:199], v[164:167], v[90:93]
	v_mfma_f32_16x16x32_bf16 v[86:89], v[110:113], v[176:179], v[86:89]
	s_waitcnt lgkmcnt(0)
	v_mfma_f32_16x16x32_bf16 v[70:73], v[200:203], v[176:179], v[70:73]
	v_mfma_f32_16x16x32_bf16 v[62:65], v[110:113], v[184:187], v[62:65]
	v_mfma_f32_16x16x32_bf16 v[58:61], v[200:203], v[184:187], v[58:61]
	v_mfma_f32_16x16x32_bf16 v[54:57], v[110:113], v[192:195], v[54:57]
	v_mfma_f32_16x16x32_bf16 v[50:53], v[200:203], v[192:195], v[50:53]
	v_mfma_f32_16x16x32_bf16 v[222:225], v[110:113], v[168:171], v[94:97]
	v_mfma_f32_16x16x32_bf16 v[164:167], v[200:203], v[168:171], v[90:93]
	s_setprio 0
	s_barrier
	s_nop 0
	ds_read_b128 v[90:93], v0 offset:16384
	ds_read_b128 v[94:97], v0 offset:17408
	ds_read_b128 v[168:171], v0 offset:18432
	ds_read_b128 v[172:175], v0 offset:19456
	ds_read_b128 v[176:179], v0 offset:20480
	ds_read_b128 v[180:183], v0 offset:21504
	ds_read_b128 v[184:187], v0 offset:22528
	ds_read_b128 v[188:191], v0 offset:23552
	s_waitcnt vmcnt(4)
	s_barrier
	s_waitcnt lgkmcnt(0)
	s_setprio 1
	s_waitcnt lgkmcnt(7)
	v_mfma_f32_16x16x32_bf16 v[46:49], v[134:137], v[90:93], v[46:49]
	v_mfma_f32_16x16x32_bf16 v[42:45], v[152:155], v[90:93], v[42:45]
	s_waitcnt lgkmcnt(5)
	v_mfma_f32_16x16x32_bf16 v[38:41], v[134:137], v[168:171], v[38:41]
	v_mfma_f32_16x16x32_bf16 v[34:37], v[152:155], v[168:171], v[34:37]
	s_waitcnt lgkmcnt(3)
	v_mfma_f32_16x16x32_bf16 v[30:33], v[134:137], v[176:179], v[30:33]
	v_mfma_f32_16x16x32_bf16 v[26:29], v[152:155], v[176:179], v[26:29]
	s_waitcnt lgkmcnt(1)
	v_mfma_f32_16x16x32_bf16 v[22:25], v[134:137], v[184:187], v[22:25]
	v_mfma_f32_16x16x32_bf16 v[18:21], v[152:155], v[184:187], v[18:21]
	v_mfma_f32_16x16x32_bf16 v[46:49], v[138:141], v[94:97], v[46:49]
	v_mfma_f32_16x16x32_bf16 v[42:45], v[156:159], v[94:97], v[42:45]
	v_mfma_f32_16x16x32_bf16 v[38:41], v[138:141], v[172:175], v[38:41]
	v_mfma_f32_16x16x32_bf16 v[34:37], v[156:159], v[172:175], v[34:37]
	v_mfma_f32_16x16x32_bf16 v[30:33], v[138:141], v[180:183], v[30:33]
	v_mfma_f32_16x16x32_bf16 v[26:29], v[156:159], v[180:183], v[26:29]
	s_waitcnt lgkmcnt(0)
	v_mfma_f32_16x16x32_bf16 v[22:25], v[138:141], v[188:191], v[22:25]
	v_mfma_f32_16x16x32_bf16 v[18:21], v[156:159], v[188:191], v[18:21]
	s_setprio 0
	s_setprio 1
	v_mfma_f32_16x16x32_bf16 v[10:13], v[196:199], v[90:93], v[10:13]
	v_mfma_f32_16x16x32_bf16 v[152:155], v[200:203], v[94:97], v[10:13]
	v_mfma_f32_16x16x32_bf16 v[10:13], v[106:109], v[176:179], v[66:69]
	v_mfma_f32_16x16x32_bf16 v[156:159], v[110:113], v[180:183], v[10:13]
	v_mfma_f32_16x16x32_bf16 v[10:13], v[196:199], v[176:179], v[74:77]
	v_mfma_f32_16x16x32_bf16 v[6:9], v[106:109], v[168:171], v[6:9]
	v_mfma_f32_16x16x32_bf16 v[2:5], v[196:199], v[168:171], v[2:5]
	v_mfma_f32_16x16x32_bf16 v[168:171], v[200:203], v[180:183], v[10:13]
	v_mfma_f32_16x16x32_bf16 v[10:13], v[106:109], v[184:187], v[78:81]
	v_mfma_f32_16x16x32_bf16 v[14:17], v[106:109], v[90:93], v[14:17]
	v_mfma_f32_16x16x32_bf16 v[6:9], v[110:113], v[172:175], v[6:9]
	v_mfma_f32_16x16x32_bf16 v[2:5], v[200:203], v[172:175], v[2:5]
	v_mfma_f32_16x16x32_bf16 v[172:175], v[110:113], v[188:191], v[10:13]
	v_mfma_f32_16x16x32_bf16 v[10:13], v[196:199], v[184:187], v[82:85]
	v_mfma_f32_16x16x32_bf16 v[134:137], v[110:113], v[94:97], v[14:17]
	v_mfma_f32_16x16x32_bf16 v[176:179], v[200:203], v[188:191], v[10:13]
	s_setprio 0
	s_barrier
	s_nop 3
	ds_read_b128 v[10:13], v151 offset:32768
	ds_read_b128 v[14:17], v151 offset:33792
	ds_read_b128 v[180:183], v151 offset:34816
	ds_read_b128 v[184:187], v151 offset:35840
	ds_read_b128 v[66:69], v0 offset:32768
	ds_read_b128 v[82:85], v0 offset:33792
	ds_read_b128 v[188:191], v0 offset:34816
	ds_read_b128 v[192:195], v0 offset:35840
	ds_read_b128 v[196:199], v0 offset:36864
	ds_read_b128 v[200:203], v0 offset:37888
	ds_read_b128 v[232:235], v0 offset:38912
	ds_read_b128 v[236:239], v0 offset:39936
	s_waitcnt vmcnt(2)
	s_barrier
	s_waitcnt lgkmcnt(0)
	s_setprio 1
	s_waitcnt lgkmcnt(7)
	v_mfma_f32_16x16x32_bf16 v[74:77], v[10:13], v[66:69], v[126:129]
	s_waitcnt lgkmcnt(6)
	v_mfma_f32_16x16x32_bf16 v[138:141], v[14:17], v[82:85], v[74:77]
	v_mfma_f32_16x16x32_bf16 v[74:77], v[180:183], v[66:69], v[122:125]
	v_mfma_f32_16x16x32_bf16 v[122:125], v[184:187], v[82:85], v[74:77]
	s_waitcnt lgkmcnt(5)
	v_mfma_f32_16x16x32_bf16 v[74:77], v[10:13], v[188:191], v[118:121]
	s_waitcnt lgkmcnt(4)
	v_mfma_f32_16x16x32_bf16 v[110:113], v[14:17], v[192:195], v[74:77]
	v_mfma_f32_16x16x32_bf16 v[74:77], v[180:183], v[188:191], v[114:117]
	v_mfma_f32_16x16x32_bf16 v[106:109], v[184:187], v[192:195], v[74:77]
	s_waitcnt lgkmcnt(3)
	v_mfma_f32_16x16x32_bf16 v[74:77], v[10:13], v[196:199], v[130:133]
	s_waitcnt lgkmcnt(2)
	v_mfma_f32_16x16x32_bf16 v[94:97], v[14:17], v[200:203], v[74:77]
	v_mfma_f32_16x16x32_bf16 v[74:77], v[180:183], v[196:199], v[160:163]
	v_mfma_f32_16x16x32_bf16 v[90:93], v[184:187], v[200:203], v[74:77]
	s_waitcnt lgkmcnt(1)
	v_mfma_f32_16x16x32_bf16 v[74:77], v[10:13], v[232:235], v[102:105]
	s_waitcnt lgkmcnt(0)
	v_mfma_f32_16x16x32_bf16 v[78:81], v[14:17], v[236:239], v[74:77]
	v_mfma_f32_16x16x32_bf16 v[74:77], v[180:183], v[232:235], v[98:101]
	v_mfma_f32_16x16x32_bf16 v[74:77], v[184:187], v[236:239], v[74:77]
	s_setprio 0
	s_barrier
	ds_read_b128 v[126:129], v151 offset:49152
	ds_read_b128 v[130:133], v151 offset:50176
	ds_read_b128 v[160:163], v151 offset:51200
	ds_read_b128 v[148:151], v151 offset:52224
	s_waitcnt vmcnt(0)
	s_barrier
	s_waitcnt lgkmcnt(0)
	s_setprio 1
	s_waitcnt lgkmcnt(3)
	v_mfma_f32_16x16x32_bf16 v[98:101], v[126:129], v[66:69], v[222:225]
	s_waitcnt lgkmcnt(1)
	v_mfma_f32_16x16x32_bf16 v[66:69], v[160:163], v[66:69], v[164:167]
	s_waitcnt lgkmcnt(0)
	v_mfma_f32_16x16x32_bf16 v[114:117], v[148:151], v[82:85], v[66:69]
	v_mfma_f32_16x16x32_bf16 v[66:69], v[126:129], v[188:191], v[86:89]
	v_mfma_f32_16x16x32_bf16 v[102:105], v[130:133], v[192:195], v[66:69]
	v_mfma_f32_16x16x32_bf16 v[66:69], v[160:163], v[188:191], v[70:73]
	v_mfma_f32_16x16x32_bf16 v[62:65], v[126:129], v[196:199], v[62:65]
	v_mfma_f32_16x16x32_bf16 v[58:61], v[160:163], v[196:199], v[58:61]
	v_mfma_f32_16x16x32_bf16 v[54:57], v[126:129], v[232:235], v[54:57]
	v_mfma_f32_16x16x32_bf16 v[50:53], v[160:163], v[232:235], v[50:53]
	v_mfma_f32_16x16x32_bf16 v[118:121], v[130:133], v[82:85], v[98:101]
	v_mfma_f32_16x16x32_bf16 v[98:101], v[148:151], v[192:195], v[66:69]
	v_mfma_f32_16x16x32_bf16 v[86:89], v[130:133], v[200:203], v[62:65]
	v_mfma_f32_16x16x32_bf16 v[82:85], v[148:151], v[200:203], v[58:61]
	v_mfma_f32_16x16x32_bf16 v[70:73], v[130:133], v[236:239], v[54:57]
	v_mfma_f32_16x16x32_bf16 v[66:69], v[148:151], v[236:239], v[50:53]
	s_setprio 0
	s_barrier
	s_nop 0
	ds_read_b128 v[50:53], v0 offset:49152
	ds_read_b128 v[164:167], v0 offset:50176
	ds_read_b128 v[188:191], v0 offset:51200
	ds_read_b128 v[192:195], v0 offset:52224
	ds_read_b128 v[196:199], v0 offset:53248
	ds_read_b128 v[200:203], v0 offset:54272
	ds_read_b128 v[222:225], v0 offset:55296
	ds_read_b128 v[232:235], v0 offset:56320
	s_barrier
	s_waitcnt lgkmcnt(0)
	s_setprio 1
	s_waitcnt lgkmcnt(7)
	v_mfma_f32_16x16x32_bf16 v[46:49], v[10:13], v[50:53], v[46:49]
	s_waitcnt lgkmcnt(5)
	v_mfma_f32_16x16x32_bf16 v[38:41], v[10:13], v[188:191], v[38:41]
	s_waitcnt lgkmcnt(3)
	v_mfma_f32_16x16x32_bf16 v[30:33], v[10:13], v[196:199], v[30:33]
	s_waitcnt lgkmcnt(1)
	v_mfma_f32_16x16x32_bf16 v[10:13], v[10:13], v[222:225], v[22:25]
	v_mfma_f32_16x16x32_bf16 v[62:65], v[14:17], v[164:167], v[46:49]
	v_mfma_f32_16x16x32_bf16 v[42:45], v[180:183], v[50:53], v[42:45]
	v_mfma_f32_16x16x32_bf16 v[46:49], v[14:17], v[192:195], v[38:41]
	v_mfma_f32_16x16x32_bf16 v[34:37], v[180:183], v[188:191], v[34:37]
	v_mfma_f32_16x16x32_bf16 v[30:33], v[14:17], v[200:203], v[30:33]
	v_mfma_f32_16x16x32_bf16 v[26:29], v[180:183], v[196:199], v[26:29]
	s_waitcnt lgkmcnt(0)
	v_mfma_f32_16x16x32_bf16 v[14:17], v[14:17], v[232:235], v[10:13]
	v_mfma_f32_16x16x32_bf16 v[10:13], v[180:183], v[222:225], v[18:21]
	v_mfma_f32_16x16x32_bf16 v[58:61], v[184:187], v[164:167], v[42:45]
	v_mfma_f32_16x16x32_bf16 v[42:45], v[184:187], v[192:195], v[34:37]
	v_mfma_f32_16x16x32_bf16 v[26:29], v[184:187], v[200:203], v[26:29]
	v_mfma_f32_16x16x32_bf16 v[10:13], v[184:187], v[232:235], v[10:13]
	s_setprio 0
	s_setprio 1
	v_mfma_f32_16x16x32_bf16 v[2:5], v[160:163], v[188:191], v[2:5]
	v_mfma_f32_16x16x32_bf16 v[18:21], v[126:129], v[50:53], v[134:137]
	v_mfma_f32_16x16x32_bf16 v[34:37], v[148:151], v[192:195], v[2:5]
	v_mfma_f32_16x16x32_bf16 v[2:5], v[126:129], v[196:199], v[156:159]
	v_mfma_f32_16x16x32_bf16 v[54:57], v[130:133], v[164:167], v[18:21]
	v_mfma_f32_16x16x32_bf16 v[18:21], v[160:163], v[50:53], v[152:155]
	v_mfma_f32_16x16x32_bf16 v[22:25], v[130:133], v[200:203], v[2:5]
	v_mfma_f32_16x16x32_bf16 v[2:5], v[160:163], v[196:199], v[168:171]
	v_mfma_f32_16x16x32_bf16 v[50:53], v[148:151], v[164:167], v[18:21]
	v_mfma_f32_16x16x32_bf16 v[6:9], v[126:129], v[188:191], v[6:9]
	v_mfma_f32_16x16x32_bf16 v[18:21], v[148:151], v[200:203], v[2:5]
	v_mfma_f32_16x16x32_bf16 v[2:5], v[126:129], v[222:225], v[172:175]
	v_mfma_f32_16x16x32_bf16 v[38:41], v[130:133], v[192:195], v[6:9]
	v_mfma_f32_16x16x32_bf16 v[6:9], v[130:133], v[232:235], v[2:5]
	v_mfma_f32_16x16x32_bf16 v[2:5], v[160:163], v[222:225], v[176:179]
	v_mfma_f32_16x16x32_bf16 v[2:5], v[148:151], v[232:235], v[2:5]
	s_setprio 0
	s_movk_i32 s0, 0x100
	v_cmp_gt_u32_e32 vcc, s0, v142
	s_barrier
	s_and_saveexec_b64 s[0:1], vcc
	s_cbranch_execz .LBB0_37
	s_barrier

.LBB0_85:
	ds_read_b128 v[164:167], v151
	ds_read_b128 v[168:171], v151 offset:1024
	ds_read_b128 v[172:175], v151 offset:2048
	ds_read_b128 v[176:179], v151 offset:3072
	v_add_u32_e32 v162, 0xc000, v147
	v_lshl_add_u64 v[204:205], v[138:139], 0, s[10:11]
	v_readfirstlane_b32 s1, v162
	v_lshl_add_u64 v[210:211], v[204:205], 0, s[60:61]
	s_mov_b32 m0, s1
	v_add_u32_e32 v163, 0xe000, v147
	ds_read_b128 v[180:183], v0
	ds_read_b128 v[184:187], v0 offset:1024
	ds_read_b128 v[188:191], v0 offset:2048
	ds_read_b128 v[192:195], v0 offset:3072
	ds_read_b128 v[196:199], v0 offset:4096
	ds_read_b128 v[200:203], v0 offset:5120
	ds_read_b128 v[222:225], v0 offset:6144
	ds_read_b128 v[232:235], v0 offset:7168
	global_load_lds_dwordx4 v[210:211], off
	v_lshl_add_u64 v[210:211], v[140:141], 0, s[10:11]
	v_readfirstlane_b32 s1, v163
	v_lshl_add_u64 v[216:217], v[210:211], 0, s[60:61]
	s_mov_b32 m0, s1
	s_nop 0
	global_load_lds_dwordx4 v[216:217], off
	s_waitcnt lgkmcnt(8)
	s_barrier
	s_waitcnt lgkmcnt(0)
	s_setprio 1
	s_waitcnt lgkmcnt(0)
	v_mfma_f32_16x16x32_bf16 v[126:129], v[164:167], v[180:183], v[126:129]
	v_mfma_f32_16x16x32_bf16 v[122:125], v[172:175], v[180:183], v[122:125]
	v_mfma_f32_16x16x32_bf16 v[118:121], v[164:167], v[188:191], v[118:121]
	v_mfma_f32_16x16x32_bf16 v[114:117], v[172:175], v[188:191], v[114:117]
	v_mfma_f32_16x16x32_bf16 v[110:113], v[164:167], v[196:199], v[110:113]
	v_mfma_f32_16x16x32_bf16 v[106:109], v[172:175], v[196:199], v[106:109]
	v_mfma_f32_16x16x32_bf16 v[102:105], v[164:167], v[222:225], v[102:105]
	v_mfma_f32_16x16x32_bf16 v[98:101], v[172:175], v[222:225], v[98:101]
	v_mfma_f32_16x16x32_bf16 v[126:129], v[168:171], v[184:187], v[126:129]
	v_mfma_f32_16x16x32_bf16 v[122:125], v[176:179], v[184:187], v[122:125]
	v_mfma_f32_16x16x32_bf16 v[118:121], v[168:171], v[192:195], v[118:121]
	v_mfma_f32_16x16x32_bf16 v[114:117], v[176:179], v[192:195], v[114:117]
	v_mfma_f32_16x16x32_bf16 v[110:113], v[168:171], v[200:203], v[110:113]
	v_mfma_f32_16x16x32_bf16 v[106:109], v[176:179], v[200:203], v[106:109]
	v_mfma_f32_16x16x32_bf16 v[102:105], v[168:171], v[232:235], v[102:105]
	v_mfma_f32_16x16x32_bf16 v[98:101], v[176:179], v[232:235], v[98:101]
	s_setprio 0
	s_barrier
	v_lshl_add_u64 v[216:217], v[134:135], 0, s[10:11]
	v_readfirstlane_b32 s1, v149
	v_lshl_add_u64 v[218:219], v[216:217], 0, s[74:75]
	s_mov_b32 m0, s1
	ds_read_b128 v[236:239], v151 offset:16384
	ds_read_b128 v[240:243], v151 offset:17408
	ds_read_b128 v[244:247], v151 offset:18432
	ds_read_b128 v[248:251], v151 offset:19456
	global_load_lds_dwordx4 v[218:219], off
	v_lshl_add_u64 v[218:219], v[136:137], 0, s[10:11]
	v_readfirstlane_b32 s1, v150
	v_lshl_add_u64 v[228:229], v[218:219], 0, s[74:75]
	s_mov_b32 m0, s1
	s_nop 0
	global_load_lds_dwordx4 v[228:229], off
	s_barrier
	s_waitcnt lgkmcnt(0)
	s_setprio 1
	s_waitcnt lgkmcnt(0)
	v_mfma_f32_16x16x32_bf16 v[94:97], v[236:239], v[180:183], v[94:97]
	v_mfma_f32_16x16x32_bf16 v[90:93], v[244:247], v[180:183], v[90:93]
	v_mfma_f32_16x16x32_bf16 v[86:89], v[236:239], v[188:191], v[86:89]
	v_mfma_f32_16x16x32_bf16 v[82:85], v[244:247], v[188:191], v[82:85]
	v_mfma_f32_16x16x32_bf16 v[78:81], v[236:239], v[196:199], v[78:81]
	v_mfma_f32_16x16x32_bf16 v[74:77], v[244:247], v[196:199], v[74:77]
	v_mfma_f32_16x16x32_bf16 v[70:73], v[236:239], v[222:225], v[70:73]
	v_mfma_f32_16x16x32_bf16 v[66:69], v[244:247], v[222:225], v[66:69]
	v_mfma_f32_16x16x32_bf16 v[94:97], v[240:243], v[184:187], v[94:97]
	v_mfma_f32_16x16x32_bf16 v[90:93], v[248:251], v[184:187], v[90:93]
	v_mfma_f32_16x16x32_bf16 v[86:89], v[240:243], v[192:195], v[86:89]
	v_mfma_f32_16x16x32_bf16 v[82:85], v[248:251], v[192:195], v[82:85]
	v_mfma_f32_16x16x32_bf16 v[78:81], v[240:243], v[200:203], v[78:81]
	v_mfma_f32_16x16x32_bf16 v[74:77], v[248:251], v[200:203], v[74:77]
	v_mfma_f32_16x16x32_bf16 v[70:73], v[240:243], v[232:235], v[70:73]
	v_mfma_f32_16x16x32_bf16 v[66:69], v[248:251], v[232:235], v[66:69]
	s_setprio 0
	v_readfirstlane_b32 s1, v147
	v_lshl_add_u64 v[228:229], v[204:205], 0, s[74:75]
	s_mov_b32 m0, s1
	v_readfirstlane_b32 s1, v148
	s_barrier
	ds_read_b128 v[180:183], v0 offset:16384
	ds_read_b128 v[184:187], v0 offset:17408
	ds_read_b128 v[188:191], v0 offset:18432
	ds_read_b128 v[192:195], v0 offset:19456
	ds_read_b128 v[196:199], v0 offset:20480
	ds_read_b128 v[200:203], v0 offset:21504
	ds_read_b128 v[222:225], v0 offset:22528
	ds_read_b128 v[232:235], v0 offset:23552
	global_load_lds_dwordx4 v[228:229], off
	v_lshl_add_u64 v[228:229], v[210:211], 0, s[74:75]
	s_mov_b32 m0, s1
	s_nop 0
	global_load_lds_dwordx4 v[228:229], off
	s_barrier
	s_waitcnt lgkmcnt(0)
	s_setprio 1
	s_waitcnt lgkmcnt(0)
	v_mfma_f32_16x16x32_bf16 v[62:65], v[164:167], v[180:183], v[62:65]
	v_mfma_f32_16x16x32_bf16 v[58:61], v[172:175], v[180:183], v[58:61]
	v_mfma_f32_16x16x32_bf16 v[54:57], v[164:167], v[188:191], v[54:57]
	v_mfma_f32_16x16x32_bf16 v[50:53], v[172:175], v[188:191], v[50:53]
	v_mfma_f32_16x16x32_bf16 v[46:49], v[164:167], v[196:199], v[46:49]
	v_mfma_f32_16x16x32_bf16 v[42:45], v[172:175], v[196:199], v[42:45]
	v_mfma_f32_16x16x32_bf16 v[38:41], v[164:167], v[222:225], v[38:41]
	v_mfma_f32_16x16x32_bf16 v[34:37], v[172:175], v[222:225], v[34:37]
	v_mfma_f32_16x16x32_bf16 v[62:65], v[168:171], v[184:187], v[62:65]
	v_mfma_f32_16x16x32_bf16 v[58:61], v[176:179], v[184:187], v[58:61]
	v_mfma_f32_16x16x32_bf16 v[54:57], v[168:171], v[192:195], v[54:57]
	v_mfma_f32_16x16x32_bf16 v[50:53], v[176:179], v[192:195], v[50:53]
	v_mfma_f32_16x16x32_bf16 v[46:49], v[168:171], v[200:203], v[46:49]
	v_mfma_f32_16x16x32_bf16 v[42:45], v[176:179], v[200:203], v[42:45]
	v_mfma_f32_16x16x32_bf16 v[38:41], v[168:171], v[232:235], v[38:41]
	v_mfma_f32_16x16x32_bf16 v[34:37], v[176:179], v[232:235], v[34:37]
	s_setprio 0
	s_barrier
	v_readfirstlane_b32 s1, v152
	v_lshl_add_u64 v[164:165], v[216:217], 0, s[18:19]
	s_mov_b32 m0, s1
	v_readfirstlane_b32 s1, v153
	global_load_lds_dwordx4 v[164:165], off
	v_lshl_add_u64 v[164:165], v[218:219], 0, s[18:19]
	s_mov_b32 m0, s1
	s_nop 0
	global_load_lds_dwordx4 v[164:165], off
	s_waitcnt vmcnt(6)
	s_barrier
	s_setprio 1
	v_mfma_f32_16x16x32_bf16 v[30:33], v[236:239], v[180:183], v[30:33]
	v_mfma_f32_16x16x32_bf16 v[26:29], v[244:247], v[180:183], v[26:29]
	v_mfma_f32_16x16x32_bf16 v[22:25], v[236:239], v[188:191], v[22:25]
	v_mfma_f32_16x16x32_bf16 v[18:21], v[244:247], v[188:191], v[18:21]
	v_mfma_f32_16x16x32_bf16 v[14:17], v[236:239], v[196:199], v[14:17]
	v_mfma_f32_16x16x32_bf16 v[10:13], v[244:247], v[196:199], v[10:13]
	v_mfma_f32_16x16x32_bf16 v[6:9], v[236:239], v[222:225], v[6:9]
	v_mfma_f32_16x16x32_bf16 v[2:5], v[244:247], v[222:225], v[2:5]
	v_mfma_f32_16x16x32_bf16 v[30:33], v[240:243], v[184:187], v[30:33]
	v_mfma_f32_16x16x32_bf16 v[26:29], v[248:251], v[184:187], v[26:29]
	v_mfma_f32_16x16x32_bf16 v[22:25], v[240:243], v[192:195], v[22:25]
	v_mfma_f32_16x16x32_bf16 v[18:21], v[248:251], v[192:195], v[18:21]
	v_mfma_f32_16x16x32_bf16 v[14:17], v[240:243], v[200:203], v[14:17]
	v_mfma_f32_16x16x32_bf16 v[10:13], v[248:251], v[200:203], v[10:13]
	v_mfma_f32_16x16x32_bf16 v[6:9], v[240:243], v[232:235], v[6:9]
	v_mfma_f32_16x16x32_bf16 v[2:5], v[248:251], v[232:235], v[2:5]
	s_setprio 0
	s_barrier
	ds_read_b128 v[164:167], v151 offset:32768
	ds_read_b128 v[168:171], v151 offset:33792
	ds_read_b128 v[172:175], v151 offset:34816
	ds_read_b128 v[176:179], v151 offset:35840
	v_readfirstlane_b32 s1, v154
	v_lshl_add_u64 v[228:229], v[204:205], 0, s[18:19]
	s_mov_b32 m0, s1
	v_readfirstlane_b32 s1, v155
	ds_read_b128 v[180:183], v0 offset:32768
	ds_read_b128 v[184:187], v0 offset:33792
	ds_read_b128 v[188:191], v0 offset:34816
	ds_read_b128 v[192:195], v0 offset:35840
	ds_read_b128 v[196:199], v0 offset:36864
	ds_read_b128 v[200:203], v0 offset:37888
	ds_read_b128 v[222:225], v0 offset:38912
	ds_read_b128 v[232:235], v0 offset:39936
	global_load_lds_dwordx4 v[228:229], off
	v_lshl_add_u64 v[228:229], v[210:211], 0, s[18:19]
	s_mov_b32 m0, s1
	s_nop 0
	global_load_lds_dwordx4 v[228:229], off
	s_waitcnt lgkmcnt(8)
	s_barrier
	s_waitcnt lgkmcnt(0)
	s_setprio 1
	s_waitcnt lgkmcnt(0)
	v_mfma_f32_16x16x32_bf16 v[126:129], v[164:167], v[180:183], v[126:129]
	v_mfma_f32_16x16x32_bf16 v[122:125], v[172:175], v[180:183], v[122:125]
	v_mfma_f32_16x16x32_bf16 v[118:121], v[164:167], v[188:191], v[118:121]
	v_mfma_f32_16x16x32_bf16 v[114:117], v[172:175], v[188:191], v[114:117]
	v_mfma_f32_16x16x32_bf16 v[110:113], v[164:167], v[196:199], v[110:113]
	v_mfma_f32_16x16x32_bf16 v[106:109], v[172:175], v[196:199], v[106:109]
	v_mfma_f32_16x16x32_bf16 v[102:105], v[164:167], v[222:225], v[102:105]
	v_mfma_f32_16x16x32_bf16 v[98:101], v[172:175], v[222:225], v[98:101]
	v_mfma_f32_16x16x32_bf16 v[126:129], v[168:171], v[184:187], v[126:129]
	v_mfma_f32_16x16x32_bf16 v[122:125], v[176:179], v[184:187], v[122:125]
	v_mfma_f32_16x16x32_bf16 v[118:121], v[168:171], v[192:195], v[118:121]
	v_mfma_f32_16x16x32_bf16 v[114:117], v[176:179], v[192:195], v[114:117]
	v_mfma_f32_16x16x32_bf16 v[110:113], v[168:171], v[200:203], v[110:113]
	v_mfma_f32_16x16x32_bf16 v[106:109], v[176:179], v[200:203], v[106:109]
	v_mfma_f32_16x16x32_bf16 v[102:105], v[168:171], v[232:235], v[102:105]
	v_mfma_f32_16x16x32_bf16 v[98:101], v[176:179], v[232:235], v[98:101]
	s_setprio 0
	s_barrier
	v_readfirstlane_b32 s1, v156
	v_lshl_add_u64 v[228:229], v[216:217], 0, s[28:29]
	s_mov_b32 m0, s1
	v_readfirstlane_b32 s1, v157
	ds_read_b128 v[236:239], v151 offset:49152
	ds_read_b128 v[240:243], v151 offset:50176
	ds_read_b128 v[244:247], v151 offset:51200
	ds_read_b128 v[248:251], v151 offset:52224
	global_load_lds_dwordx4 v[228:229], off
	v_lshl_add_u64 v[228:229], v[218:219], 0, s[28:29]
	s_mov_b32 m0, s1
	s_nop 0
	global_load_lds_dwordx4 v[228:229], off
	s_barrier
	s_waitcnt lgkmcnt(0)
	s_setprio 1
	s_waitcnt lgkmcnt(0)
	v_mfma_f32_16x16x32_bf16 v[94:97], v[236:239], v[180:183], v[94:97]
	v_mfma_f32_16x16x32_bf16 v[90:93], v[244:247], v[180:183], v[90:93]
	v_mfma_f32_16x16x32_bf16 v[86:89], v[236:239], v[188:191], v[86:89]
	v_mfma_f32_16x16x32_bf16 v[82:85], v[244:247], v[188:191], v[82:85]
	v_mfma_f32_16x16x32_bf16 v[78:81], v[236:239], v[196:199], v[78:81]
	v_mfma_f32_16x16x32_bf16 v[74:77], v[244:247], v[196:199], v[74:77]
	v_mfma_f32_16x16x32_bf16 v[70:73], v[236:239], v[222:225], v[70:73]
	v_mfma_f32_16x16x32_bf16 v[66:69], v[244:247], v[222:225], v[66:69]
	v_mfma_f32_16x16x32_bf16 v[94:97], v[240:243], v[184:187], v[94:97]
	v_mfma_f32_16x16x32_bf16 v[90:93], v[248:251], v[184:187], v[90:93]
	v_mfma_f32_16x16x32_bf16 v[86:89], v[240:243], v[192:195], v[86:89]
	v_mfma_f32_16x16x32_bf16 v[82:85], v[248:251], v[192:195], v[82:85]
	v_mfma_f32_16x16x32_bf16 v[78:81], v[240:243], v[200:203], v[78:81]
	v_mfma_f32_16x16x32_bf16 v[74:77], v[248:251], v[200:203], v[74:77]
	v_mfma_f32_16x16x32_bf16 v[70:73], v[240:243], v[232:235], v[70:73]
	v_mfma_f32_16x16x32_bf16 v[66:69], v[248:251], v[232:235], v[66:69]
	s_setprio 0
	v_readfirstlane_b32 s1, v158
	v_lshl_add_u64 v[204:205], v[204:205], 0, s[28:29]
	s_mov_b32 m0, s1
	v_readfirstlane_b32 s1, v159
	s_barrier
	ds_read_b128 v[180:183], v0 offset:49152
	ds_read_b128 v[184:187], v0 offset:50176
	ds_read_b128 v[188:191], v0 offset:51200
	ds_read_b128 v[192:195], v0 offset:52224
	ds_read_b128 v[196:199], v0 offset:53248
	ds_read_b128 v[200:203], v0 offset:54272
	ds_read_b128 v[222:225], v0 offset:55296
	ds_read_b128 v[232:235], v0 offset:56320
	global_load_lds_dwordx4 v[204:205], off
	v_lshl_add_u64 v[204:205], v[210:211], 0, s[28:29]
	s_mov_b32 m0, s1
	s_nop 0
	global_load_lds_dwordx4 v[204:205], off
	s_barrier
	s_waitcnt lgkmcnt(0)
	s_setprio 1
	s_waitcnt lgkmcnt(0)
	v_mfma_f32_16x16x32_bf16 v[62:65], v[164:167], v[180:183], v[62:65]
	v_mfma_f32_16x16x32_bf16 v[58:61], v[172:175], v[180:183], v[58:61]
	v_mfma_f32_16x16x32_bf16 v[54:57], v[164:167], v[188:191], v[54:57]
	v_mfma_f32_16x16x32_bf16 v[50:53], v[172:175], v[188:191], v[50:53]
	v_mfma_f32_16x16x32_bf16 v[46:49], v[164:167], v[196:199], v[46:49]
	v_mfma_f32_16x16x32_bf16 v[42:45], v[172:175], v[196:199], v[42:45]
	v_mfma_f32_16x16x32_bf16 v[38:41], v[164:167], v[222:225], v[38:41]
	v_mfma_f32_16x16x32_bf16 v[34:37], v[172:175], v[222:225], v[34:37]
	v_mfma_f32_16x16x32_bf16 v[62:65], v[168:171], v[184:187], v[62:65]
	v_mfma_f32_16x16x32_bf16 v[58:61], v[176:179], v[184:187], v[58:61]
	v_mfma_f32_16x16x32_bf16 v[54:57], v[168:171], v[192:195], v[54:57]
	v_mfma_f32_16x16x32_bf16 v[50:53], v[176:179], v[192:195], v[50:53]
	v_mfma_f32_16x16x32_bf16 v[46:49], v[168:171], v[200:203], v[46:49]
	v_mfma_f32_16x16x32_bf16 v[42:45], v[176:179], v[200:203], v[42:45]
	v_mfma_f32_16x16x32_bf16 v[38:41], v[168:171], v[232:235], v[38:41]
	v_mfma_f32_16x16x32_bf16 v[34:37], v[176:179], v[232:235], v[34:37]
	s_setprio 0
	s_barrier
	v_readfirstlane_b32 s1, v160
	v_lshl_add_u64 v[164:165], v[216:217], 0, s[30:31]
	s_mov_b32 m0, s1
	v_readfirstlane_b32 s1, v161
	global_load_lds_dwordx4 v[164:165], off
	v_lshl_add_u64 v[164:165], v[218:219], 0, s[30:31]
	s_mov_b32 m0, s1
	s_nop 0
	global_load_lds_dwordx4 v[164:165], off
	s_waitcnt vmcnt(6)
	s_barrier
	s_setprio 1
	v_mfma_f32_16x16x32_bf16 v[30:33], v[236:239], v[180:183], v[30:33]
	v_mfma_f32_16x16x32_bf16 v[26:29], v[244:247], v[180:183], v[26:29]
	v_mfma_f32_16x16x32_bf16 v[22:25], v[236:239], v[188:191], v[22:25]
	v_mfma_f32_16x16x32_bf16 v[18:21], v[244:247], v[188:191], v[18:21]
	v_mfma_f32_16x16x32_bf16 v[14:17], v[236:239], v[196:199], v[14:17]
	v_mfma_f32_16x16x32_bf16 v[10:13], v[244:247], v[196:199], v[10:13]
	v_mfma_f32_16x16x32_bf16 v[6:9], v[236:239], v[222:225], v[6:9]
	v_mfma_f32_16x16x32_bf16 v[2:5], v[244:247], v[222:225], v[2:5]
	v_mfma_f32_16x16x32_bf16 v[30:33], v[240:243], v[184:187], v[30:33]
	v_mfma_f32_16x16x32_bf16 v[26:29], v[248:251], v[184:187], v[26:29]
	v_mfma_f32_16x16x32_bf16 v[22:25], v[240:243], v[192:195], v[22:25]
	v_mfma_f32_16x16x32_bf16 v[18:21], v[248:251], v[192:195], v[18:21]
	v_mfma_f32_16x16x32_bf16 v[14:17], v[240:243], v[200:203], v[14:17]
	v_mfma_f32_16x16x32_bf16 v[10:13], v[248:251], v[200:203], v[10:13]
	v_mfma_f32_16x16x32_bf16 v[6:9], v[240:243], v[232:235], v[6:9]
	v_mfma_f32_16x16x32_bf16 v[2:5], v[248:251], v[232:235], v[2:5]
	s_setprio 0
	s_add_i32 s0, s0, 2
	s_add_u32 s10, s10, 0x100
	s_addc_u32 s11, s11, 0
	s_cmp_lt_u32 s0, 28
	s_barrier
	s_cbranch_scc1 .LBB0_85
	s_mov_b64 s[10:11], 0xf80
	v_readfirstlane_b32 s0, v162
	v_lshl_add_u64 v[132:133], v[132:133], 0, s[10:11]
	s_mov_b32 m0, s0
	v_readfirstlane_b32 s0, v163
	s_waitcnt vmcnt(0)
	ds_read_b128 v[134:137], v151
	ds_read_b128 v[138:141], v151 offset:1024
	ds_read_b128 v[152:155], v151 offset:2048
	ds_read_b128 v[156:159], v151 offset:3072
	ds_read_b128 v[164:167], v0
	ds_read_b128 v[168:171], v0 offset:1024
	ds_read_b128 v[172:175], v0 offset:2048
	ds_read_b128 v[176:179], v0 offset:3072
	ds_read_b128 v[180:183], v0 offset:4096
	ds_read_b128 v[184:187], v0 offset:5120
	ds_read_b128 v[188:191], v0 offset:6144
	ds_read_b128 v[192:195], v0 offset:7168
	global_load_lds_dwordx4 v[132:133], off
	v_lshl_add_u64 v[130:131], v[130:131], 0, s[10:11]
	s_mov_b32 m0, s0
	s_nop 0
	global_load_lds_dwordx4 v[130:131], off
	s_barrier
	s_waitcnt lgkmcnt(0)
	s_setprio 1
	s_waitcnt lgkmcnt(0)
	v_mfma_f32_16x16x32_bf16 v[126:129], v[134:137], v[164:167], v[126:129]
	v_mfma_f32_16x16x32_bf16 v[122:125], v[152:155], v[164:167], v[122:125]
	v_mfma_f32_16x16x32_bf16 v[114:117], v[152:155], v[172:175], v[114:117]
	v_mfma_f32_16x16x32_bf16 v[106:109], v[152:155], v[180:183], v[106:109]
	v_mfma_f32_16x16x32_bf16 v[98:101], v[152:155], v[188:191], v[98:101]
	v_mfma_f32_16x16x32_bf16 v[126:129], v[138:141], v[168:171], v[126:129]
	v_mfma_f32_16x16x32_bf16 v[122:125], v[156:159], v[168:171], v[122:125]
	v_mfma_f32_16x16x32_bf16 v[118:121], v[134:137], v[172:175], v[118:121]
	v_mfma_f32_16x16x32_bf16 v[114:117], v[156:159], v[176:179], v[114:117]
	v_mfma_f32_16x16x32_bf16 v[110:113], v[134:137], v[180:183], v[110:113]
	v_mfma_f32_16x16x32_bf16 v[106:109], v[156:159], v[184:187], v[106:109]
	v_mfma_f32_16x16x32_bf16 v[102:105], v[134:137], v[188:191], v[102:105]
	v_mfma_f32_16x16x32_bf16 v[98:101], v[156:159], v[192:195], v[98:101]
	v_mfma_f32_16x16x32_bf16 v[130:133], v[138:141], v[176:179], v[118:121]
	v_mfma_f32_16x16x32_bf16 v[160:163], v[138:141], v[184:187], v[110:113]
	v_mfma_f32_16x16x32_bf16 v[196:199], v[138:141], v[192:195], v[102:105]
	s_setprio 0
	s_barrier
	s_waitcnt vmcnt(0)
	s_nop 0
	ds_read_b128 v[102:105], v151 offset:16384
	ds_read_b128 v[110:113], v151 offset:17408
	ds_read_b128 v[118:121], v151 offset:18432
	ds_read_b128 v[200:203], v151 offset:19456
	s_barrier
	s_waitcnt lgkmcnt(0)
	s_setprio 1
	s_waitcnt lgkmcnt(1)
	v_mfma_f32_16x16x32_bf16 v[90:93], v[118:121], v[164:167], v[90:93]
	v_mfma_f32_16x16x32_bf16 v[86:89], v[102:105], v[172:175], v[86:89]
	v_mfma_f32_16x16x32_bf16 v[82:85], v[118:121], v[172:175], v[82:85]
	v_mfma_f32_16x16x32_bf16 v[78:81], v[102:105], v[180:183], v[78:81]
	v_mfma_f32_16x16x32_bf16 v[70:73], v[102:105], v[188:191], v[70:73]
	v_mfma_f32_16x16x32_bf16 v[94:97], v[102:105], v[164:167], v[94:97]
	s_waitcnt lgkmcnt(0)
	v_mfma_f32_16x16x32_bf16 v[90:93], v[200:203], v[168:171], v[90:93]
	v_mfma_f32_16x16x32_bf16 v[86:89], v[110:113], v[176:179], v[86:89]
	v_mfma_f32_16x16x32_bf16 v[82:85], v[200:203], v[176:179], v[82:85]
	v_mfma_f32_16x16x32_bf16 v[78:81], v[110:113], v[184:187], v[78:81]
	v_mfma_f32_16x16x32_bf16 v[74:77], v[118:121], v[180:183], v[74:77]
	v_mfma_f32_16x16x32_bf16 v[70:73], v[110:113], v[192:195], v[70:73]
	v_mfma_f32_16x16x32_bf16 v[66:69], v[118:121], v[188:191], v[66:69]
	v_mfma_f32_16x16x32_bf16 v[222:225], v[110:113], v[168:171], v[94:97]
	v_mfma_f32_16x16x32_bf16 v[164:167], v[200:203], v[184:187], v[74:77]
	v_mfma_f32_16x16x32_bf16 v[168:171], v[200:203], v[192:195], v[66:69]
	s_setprio 0
	s_barrier
	s_nop 2
	ds_read_b128 v[66:69], v0 offset:16384
	ds_read_b128 v[74:77], v0 offset:17408
	ds_read_b128 v[94:97], v0 offset:18432
	ds_read_b128 v[172:175], v0 offset:19456
	ds_read_b128 v[176:179], v0 offset:20480
	ds_read_b128 v[180:183], v0 offset:21504
	ds_read_b128 v[184:187], v0 offset:22528
	ds_read_b128 v[188:191], v0 offset:23552
	s_waitcnt vmcnt(4)
	s_barrier
	s_waitcnt lgkmcnt(0)
	s_setprio 1
	s_waitcnt lgkmcnt(5)
	v_mfma_f32_16x16x32_bf16 v[54:57], v[134:137], v[94:97], v[54:57]
	v_mfma_f32_16x16x32_bf16 v[50:53], v[152:155], v[94:97], v[50:53]
	v_mfma_f32_16x16x32_bf16 v[62:65], v[134:137], v[66:69], v[62:65]
	v_mfma_f32_16x16x32_bf16 v[58:61], v[152:155], v[66:69], v[58:61]
	s_waitcnt lgkmcnt(4)
	v_mfma_f32_16x16x32_bf16 v[54:57], v[138:141], v[172:175], v[54:57]
	v_mfma_f32_16x16x32_bf16 v[50:53], v[156:159], v[172:175], v[50:53]
	s_waitcnt lgkmcnt(3)
	v_mfma_f32_16x16x32_bf16 v[46:49], v[134:137], v[176:179], v[46:49]
	v_mfma_f32_16x16x32_bf16 v[42:45], v[152:155], v[176:179], v[42:45]
	s_waitcnt lgkmcnt(1)
	v_mfma_f32_16x16x32_bf16 v[38:41], v[134:137], v[184:187], v[38:41]
	v_mfma_f32_16x16x32_bf16 v[34:37], v[152:155], v[184:187], v[34:37]
	v_mfma_f32_16x16x32_bf16 v[192:195], v[138:141], v[74:77], v[62:65]
	v_mfma_f32_16x16x32_bf16 v[232:235], v[156:159], v[74:77], v[58:61]
	v_mfma_f32_16x16x32_bf16 v[236:239], v[138:141], v[180:183], v[46:49]
	v_mfma_f32_16x16x32_bf16 v[240:243], v[156:159], v[180:183], v[42:45]
	s_waitcnt lgkmcnt(0)
	v_mfma_f32_16x16x32_bf16 v[134:137], v[138:141], v[188:191], v[38:41]
	v_mfma_f32_16x16x32_bf16 v[138:141], v[156:159], v[188:191], v[34:37]
	s_setprio 0
	s_setprio 1
	v_mfma_f32_16x16x32_bf16 v[30:33], v[102:105], v[66:69], v[30:33]
	v_mfma_f32_16x16x32_bf16 v[26:29], v[118:121], v[66:69], v[26:29]
	v_mfma_f32_16x16x32_bf16 v[14:17], v[102:105], v[176:179], v[14:17]
	v_mfma_f32_16x16x32_bf16 v[10:13], v[118:121], v[176:179], v[10:13]
	v_mfma_f32_16x16x32_bf16 v[30:33], v[110:113], v[74:77], v[30:33]
	v_mfma_f32_16x16x32_bf16 v[26:29], v[200:203], v[74:77], v[26:29]
	v_mfma_f32_16x16x32_bf16 v[22:25], v[102:105], v[94:97], v[22:25]
	v_mfma_f32_16x16x32_bf16 v[18:21], v[118:121], v[94:97], v[18:21]
	v_mfma_f32_16x16x32_bf16 v[14:17], v[110:113], v[180:183], v[14:17]
	v_mfma_f32_16x16x32_bf16 v[10:13], v[200:203], v[180:183], v[10:13]
	v_mfma_f32_16x16x32_bf16 v[6:9], v[102:105], v[184:187], v[6:9]
	v_mfma_f32_16x16x32_bf16 v[2:5], v[118:121], v[184:187], v[2:5]
	v_mfma_f32_16x16x32_bf16 v[152:155], v[110:113], v[172:175], v[22:25]
	v_mfma_f32_16x16x32_bf16 v[156:159], v[200:203], v[172:175], v[18:21]
	v_mfma_f32_16x16x32_bf16 v[172:175], v[110:113], v[188:191], v[6:9]
	v_mfma_f32_16x16x32_bf16 v[176:179], v[200:203], v[188:191], v[2:5]
	s_setprio 0
	s_barrier
	s_nop 1
	ds_read_b128 v[2:5], v151 offset:32768
	ds_read_b128 v[6:9], v151 offset:33792
	ds_read_b128 v[180:183], v151 offset:34816
	ds_read_b128 v[184:187], v151 offset:35840
	ds_read_b128 v[18:21], v0 offset:32768
	ds_read_b128 v[22:25], v0 offset:33792
	ds_read_b128 v[38:41], v0 offset:34816
	ds_read_b128 v[46:49], v0 offset:35840
	ds_read_b128 v[58:61], v0 offset:36864
	ds_read_b128 v[66:69], v0 offset:37888
	ds_read_b128 v[188:191], v0 offset:38912
	ds_read_b128 v[200:203], v0 offset:39936
	s_waitcnt vmcnt(2)
	s_barrier
	s_waitcnt lgkmcnt(0)
	s_setprio 1
	s_waitcnt lgkmcnt(7)
	v_mfma_f32_16x16x32_bf16 v[34:37], v[2:5], v[18:21], v[126:129]
	s_waitcnt lgkmcnt(6)
	v_mfma_f32_16x16x32_bf16 v[118:121], v[6:9], v[22:25], v[34:37]
	v_mfma_f32_16x16x32_bf16 v[34:37], v[180:183], v[18:21], v[122:125]
	v_mfma_f32_16x16x32_bf16 v[110:113], v[184:187], v[22:25], v[34:37]
	s_waitcnt lgkmcnt(5)
	v_mfma_f32_16x16x32_bf16 v[34:37], v[2:5], v[38:41], v[130:133]
	s_waitcnt lgkmcnt(4)
	v_mfma_f32_16x16x32_bf16 v[102:105], v[6:9], v[46:49], v[34:37]
	v_mfma_f32_16x16x32_bf16 v[34:37], v[180:183], v[38:41], v[114:117]
	v_mfma_f32_16x16x32_bf16 v[94:97], v[184:187], v[46:49], v[34:37]
	s_waitcnt lgkmcnt(3)
	v_mfma_f32_16x16x32_bf16 v[34:37], v[2:5], v[58:61], v[160:163]
	s_waitcnt lgkmcnt(2)
	v_mfma_f32_16x16x32_bf16 v[74:77], v[6:9], v[66:69], v[34:37]
	v_mfma_f32_16x16x32_bf16 v[34:37], v[180:183], v[58:61], v[106:109]
	v_mfma_f32_16x16x32_bf16 v[62:65], v[184:187], v[66:69], v[34:37]
	s_waitcnt lgkmcnt(1)
	v_mfma_f32_16x16x32_bf16 v[34:37], v[2:5], v[188:191], v[196:199]
	s_waitcnt lgkmcnt(0)
	v_mfma_f32_16x16x32_bf16 v[42:45], v[6:9], v[200:203], v[34:37]
	v_mfma_f32_16x16x32_bf16 v[34:37], v[180:183], v[188:191], v[98:101]
	v_mfma_f32_16x16x32_bf16 v[34:37], v[184:187], v[200:203], v[34:37]
	s_setprio 0
	s_barrier
	ds_read_b128 v[130:133], v151 offset:49152
	ds_read_b128 v[160:163], v151 offset:50176
	ds_read_b128 v[196:199], v151 offset:51200
	ds_read_b128 v[148:151], v151 offset:52224
	s_waitcnt vmcnt(0)
	s_barrier
	s_waitcnt lgkmcnt(0)
	s_setprio 1
	s_waitcnt lgkmcnt(3)
	v_mfma_f32_16x16x32_bf16 v[98:101], v[130:133], v[18:21], v[222:225]
	s_waitcnt lgkmcnt(1)
	v_mfma_f32_16x16x32_bf16 v[18:21], v[196:199], v[18:21], v[90:93]
	s_waitcnt lgkmcnt(0)
	v_mfma_f32_16x16x32_bf16 v[122:125], v[148:151], v[22:25], v[18:21]
	v_mfma_f32_16x16x32_bf16 v[18:21], v[130:133], v[38:41], v[86:89]
	v_mfma_f32_16x16x32_bf16 v[114:117], v[160:163], v[46:49], v[18:21]
	v_mfma_f32_16x16x32_bf16 v[18:21], v[196:199], v[38:41], v[82:85]
	v_mfma_f32_16x16x32_bf16 v[106:109], v[148:151], v[46:49], v[18:21]
	v_mfma_f32_16x16x32_bf16 v[18:21], v[130:133], v[58:61], v[78:81]
	v_mfma_f32_16x16x32_bf16 v[126:129], v[160:163], v[22:25], v[98:101]
	v_mfma_f32_16x16x32_bf16 v[98:101], v[160:163], v[66:69], v[18:21]
	v_mfma_f32_16x16x32_bf16 v[18:21], v[196:199], v[58:61], v[164:167]
	v_mfma_f32_16x16x32_bf16 v[90:93], v[148:151], v[66:69], v[18:21]
	v_mfma_f32_16x16x32_bf16 v[18:21], v[130:133], v[188:191], v[70:73]
	v_mfma_f32_16x16x32_bf16 v[66:69], v[160:163], v[200:203], v[18:21]
	v_mfma_f32_16x16x32_bf16 v[18:21], v[196:199], v[188:191], v[168:171]
	v_mfma_f32_16x16x32_bf16 v[58:61], v[148:151], v[200:203], v[18:21]
	s_setprio 0
	s_barrier
	ds_read_b128 v[82:85], v0 offset:49152
	ds_read_b128 v[164:167], v0 offset:50176
	ds_read_b128 v[168:171], v0 offset:51200
	ds_read_b128 v[188:191], v0 offset:52224
	ds_read_b128 v[200:203], v0 offset:53248
	ds_read_b128 v[222:225], v0 offset:54272
	ds_read_b128 v[244:247], v0 offset:55296
	ds_read_b128 v[248:251], v0 offset:56320
	s_barrier
	s_waitcnt lgkmcnt(0)
	s_setprio 1
	s_waitcnt lgkmcnt(7)
	v_mfma_f32_16x16x32_bf16 v[18:21], v[2:5], v[82:85], v[192:195]
	s_waitcnt lgkmcnt(6)
	v_mfma_f32_16x16x32_bf16 v[78:81], v[6:9], v[164:167], v[18:21]
	v_mfma_f32_16x16x32_bf16 v[18:21], v[180:183], v[82:85], v[232:235]
	v_mfma_f32_16x16x32_bf16 v[70:73], v[184:187], v[164:167], v[18:21]
	s_waitcnt lgkmcnt(5)
	v_mfma_f32_16x16x32_bf16 v[18:21], v[2:5], v[168:171], v[54:57]
	s_waitcnt lgkmcnt(4)
	v_mfma_f32_16x16x32_bf16 v[46:49], v[6:9], v[188:191], v[18:21]
	v_mfma_f32_16x16x32_bf16 v[18:21], v[180:183], v[168:171], v[50:53]
	v_mfma_f32_16x16x32_bf16 v[38:41], v[184:187], v[188:191], v[18:21]
	s_waitcnt lgkmcnt(3)
	v_mfma_f32_16x16x32_bf16 v[18:21], v[2:5], v[200:203], v[236:239]
	s_waitcnt lgkmcnt(1)
	v_mfma_f32_16x16x32_bf16 v[2:5], v[2:5], v[244:247], v[134:137]
	v_mfma_f32_16x16x32_bf16 v[22:25], v[6:9], v[222:225], v[18:21]
	v_mfma_f32_16x16x32_bf16 v[18:21], v[180:183], v[200:203], v[240:243]
	s_waitcnt lgkmcnt(0)
	v_mfma_f32_16x16x32_bf16 v[6:9], v[6:9], v[248:251], v[2:5]
	v_mfma_f32_16x16x32_bf16 v[2:5], v[180:183], v[244:247], v[138:141]
	v_mfma_f32_16x16x32_bf16 v[18:21], v[184:187], v[222:225], v[18:21]
	v_mfma_f32_16x16x32_bf16 v[2:5], v[184:187], v[248:251], v[2:5]
	s_setprio 0
	s_setprio 1
	v_mfma_f32_16x16x32_bf16 v[26:29], v[196:199], v[82:85], v[26:29]
	v_mfma_f32_16x16x32_bf16 v[30:33], v[130:133], v[82:85], v[30:33]
	v_mfma_f32_16x16x32_bf16 v[82:85], v[148:151], v[164:167], v[26:29]
	v_mfma_f32_16x16x32_bf16 v[26:29], v[130:133], v[168:171], v[152:155]
	v_mfma_f32_16x16x32_bf16 v[54:57], v[160:163], v[188:191], v[26:29]
	v_mfma_f32_16x16x32_bf16 v[26:29], v[196:199], v[168:171], v[156:159]
	v_mfma_f32_16x16x32_bf16 v[10:13], v[196:199], v[200:203], v[10:13]
	v_mfma_f32_16x16x32_bf16 v[50:53], v[148:151], v[188:191], v[26:29]
	v_mfma_f32_16x16x32_bf16 v[14:17], v[130:133], v[200:203], v[14:17]
	v_mfma_f32_16x16x32_bf16 v[26:29], v[148:151], v[222:225], v[10:13]
	v_mfma_f32_16x16x32_bf16 v[10:13], v[130:133], v[244:247], v[172:175]
	v_mfma_f32_16x16x32_bf16 v[86:89], v[160:163], v[164:167], v[30:33]
	v_mfma_f32_16x16x32_bf16 v[30:33], v[160:163], v[222:225], v[14:17]
	v_mfma_f32_16x16x32_bf16 v[14:17], v[160:163], v[248:251], v[10:13]
	v_mfma_f32_16x16x32_bf16 v[10:13], v[196:199], v[244:247], v[176:179]
	v_mfma_f32_16x16x32_bf16 v[10:13], v[148:151], v[248:251], v[10:13]
	s_setprio 0
	s_movk_i32 s0, 0x100
	v_cmp_gt_u32_e32 vcc, s0, v142
	s_barrier
	s_and_saveexec_b64 s[0:1], vcc
	s_cbranch_execz .LBB0_81
	s_barrier
	s_branch .LBB0_81

.LBB0_108:
	ds_read_b128 v[104:107], v99
	ds_read_b128 v[108:111], v99 offset:1024
	ds_read_b128 v[112:115], v99 offset:2048
	ds_read_b128 v[116:119], v99 offset:3072
	v_add_u32_e32 v102, 0xc000, v87
	v_lshl_add_u64 v[152:153], v[74:75], 0, s[10:11]
	v_readfirstlane_b32 s1, v102
	v_lshl_add_u64 v[154:155], v[152:153], 0, s[60:61]
	s_mov_b32 m0, s1
	v_add_u32_e32 v103, 0xe000, v87
	ds_read_b128 v[120:123], v0
	ds_read_b128 v[124:127], v0 offset:1024
	ds_read_b128 v[128:131], v0 offset:2048
	ds_read_b128 v[132:135], v0 offset:3072
	ds_read_b128 v[136:139], v0 offset:4096
	ds_read_b128 v[140:143], v0 offset:5120
	ds_read_b128 v[144:147], v0 offset:6144
	ds_read_b128 v[148:151], v0 offset:7168
	global_load_lds_dwordx4 v[154:155], off
	v_lshl_add_u64 v[154:155], v[76:77], 0, s[10:11]
	v_readfirstlane_b32 s1, v103
	v_lshl_add_u64 v[156:157], v[154:155], 0, s[60:61]
	s_mov_b32 m0, s1
	s_nop 0
	global_load_lds_dwordx4 v[156:157], off
	s_waitcnt lgkmcnt(8)
	s_barrier
	s_waitcnt lgkmcnt(0)
	s_setprio 1
	s_waitcnt lgkmcnt(0)
	v_mfma_f32_16x16x32_bf16 v[62:65], v[104:107], v[120:123], v[62:65]
	v_mfma_f32_16x16x32_bf16 v[58:61], v[112:115], v[120:123], v[58:61]
	v_mfma_f32_16x16x32_bf16 v[54:57], v[104:107], v[128:131], v[54:57]
	v_mfma_f32_16x16x32_bf16 v[50:53], v[112:115], v[128:131], v[50:53]
	v_mfma_f32_16x16x32_bf16 v[46:49], v[104:107], v[136:139], v[46:49]
	v_mfma_f32_16x16x32_bf16 v[42:45], v[112:115], v[136:139], v[42:45]
	v_mfma_f32_16x16x32_bf16 v[38:41], v[104:107], v[144:147], v[38:41]
	v_mfma_f32_16x16x32_bf16 v[34:37], v[112:115], v[144:147], v[34:37]
	v_mfma_f32_16x16x32_bf16 v[62:65], v[108:111], v[124:127], v[62:65]
	v_mfma_f32_16x16x32_bf16 v[58:61], v[116:119], v[124:127], v[58:61]
	v_mfma_f32_16x16x32_bf16 v[54:57], v[108:111], v[132:135], v[54:57]
	v_mfma_f32_16x16x32_bf16 v[50:53], v[116:119], v[132:135], v[50:53]
	v_mfma_f32_16x16x32_bf16 v[46:49], v[108:111], v[140:143], v[46:49]
	v_mfma_f32_16x16x32_bf16 v[42:45], v[116:119], v[140:143], v[42:45]
	v_mfma_f32_16x16x32_bf16 v[38:41], v[108:111], v[148:151], v[38:41]
	v_mfma_f32_16x16x32_bf16 v[34:37], v[116:119], v[148:151], v[34:37]
	s_setprio 0
	s_barrier
	v_lshl_add_u64 v[156:157], v[70:71], 0, s[10:11]
	v_readfirstlane_b32 s1, v89
	v_lshl_add_u64 v[120:121], v[156:157], 0, s[74:75]
	s_mov_b32 m0, s1
	v_lshl_add_u64 v[158:159], v[72:73], 0, s[10:11]
	v_readfirstlane_b32 s1, v90
	global_load_lds_dwordx4 v[120:121], off
	v_lshl_add_u64 v[120:121], v[158:159], 0, s[74:75]
	s_mov_b32 m0, s1
	v_readfirstlane_b32 s1, v87
	global_load_lds_dwordx4 v[120:121], off
	v_lshl_add_u64 v[160:161], v[152:153], 0, s[74:75]
	s_mov_b32 m0, s1
	v_readfirstlane_b32 s1, v88
	s_barrier
	s_waitcnt lgkmcnt(0)
	s_barrier
	ds_read_b128 v[120:123], v0 offset:16384
	ds_read_b128 v[124:127], v0 offset:17408
	ds_read_b128 v[128:131], v0 offset:18432
	ds_read_b128 v[132:135], v0 offset:19456
	ds_read_b128 v[136:139], v0 offset:20480
	ds_read_b128 v[140:143], v0 offset:21504
	ds_read_b128 v[144:147], v0 offset:22528
	ds_read_b128 v[148:151], v0 offset:23552
	global_load_lds_dwordx4 v[160:161], off
	v_lshl_add_u64 v[160:161], v[154:155], 0, s[74:75]
	s_mov_b32 m0, s1
	s_nop 0
	global_load_lds_dwordx4 v[160:161], off
	s_barrier
	s_waitcnt lgkmcnt(0)
	s_setprio 1
	s_waitcnt lgkmcnt(0)
	v_mfma_f32_16x16x32_bf16 v[2:5], v[104:107], v[120:123], v[2:5]
	v_mfma_f32_16x16x32_bf16 v[6:9], v[112:115], v[120:123], v[6:9]
	v_mfma_f32_16x16x32_bf16 v[10:13], v[104:107], v[128:131], v[10:13]
	v_mfma_f32_16x16x32_bf16 v[14:17], v[112:115], v[128:131], v[14:17]
	v_mfma_f32_16x16x32_bf16 v[18:21], v[104:107], v[136:139], v[18:21]
	v_mfma_f32_16x16x32_bf16 v[22:25], v[112:115], v[136:139], v[22:25]
	v_mfma_f32_16x16x32_bf16 v[26:29], v[104:107], v[144:147], v[26:29]
	v_mfma_f32_16x16x32_bf16 v[30:33], v[112:115], v[144:147], v[30:33]
	v_mfma_f32_16x16x32_bf16 v[2:5], v[108:111], v[124:127], v[2:5]
	v_mfma_f32_16x16x32_bf16 v[6:9], v[116:119], v[124:127], v[6:9]
	v_mfma_f32_16x16x32_bf16 v[10:13], v[108:111], v[132:135], v[10:13]
	v_mfma_f32_16x16x32_bf16 v[14:17], v[116:119], v[132:135], v[14:17]
	v_mfma_f32_16x16x32_bf16 v[18:21], v[108:111], v[140:143], v[18:21]
	v_mfma_f32_16x16x32_bf16 v[22:25], v[116:119], v[140:143], v[22:25]
	v_mfma_f32_16x16x32_bf16 v[26:29], v[108:111], v[148:151], v[26:29]
	v_mfma_f32_16x16x32_bf16 v[30:33], v[116:119], v[148:151], v[30:33]
	s_setprio 0
	s_barrier
	v_lshl_add_u64 v[160:161], v[78:79], 0, s[10:11]
	v_readfirstlane_b32 s1, v91
	v_lshl_add_u64 v[104:105], v[160:161], 0, s[74:75]
	s_mov_b32 m0, s1
	v_lshl_add_u64 v[162:163], v[80:81], 0, s[10:11]
	v_readfirstlane_b32 s1, v92
	global_load_lds_dwordx4 v[104:105], off
	v_lshl_add_u64 v[104:105], v[162:163], 0, s[74:75]
	s_mov_b32 m0, s1
	s_nop 0
	global_load_lds_dwordx4 v[104:105], off
	s_waitcnt vmcnt(6)
	s_barrier
	s_barrier
	ds_read_b128 v[104:107], v99 offset:32768
	ds_read_b128 v[108:111], v99 offset:33792
	ds_read_b128 v[112:115], v99 offset:34816
	ds_read_b128 v[116:119], v99 offset:35840
	v_readfirstlane_b32 s1, v93
	v_lshl_add_u64 v[164:165], v[152:153], 0, s[18:19]
	s_mov_b32 m0, s1
	v_readfirstlane_b32 s1, v94
	ds_read_b128 v[120:123], v0 offset:32768
	ds_read_b128 v[124:127], v0 offset:33792
	ds_read_b128 v[128:131], v0 offset:34816
	ds_read_b128 v[132:135], v0 offset:35840
	ds_read_b128 v[136:139], v0 offset:36864
	ds_read_b128 v[140:143], v0 offset:37888
	ds_read_b128 v[144:147], v0 offset:38912
	ds_read_b128 v[148:151], v0 offset:39936
	global_load_lds_dwordx4 v[164:165], off
	v_lshl_add_u64 v[164:165], v[154:155], 0, s[18:19]
	s_mov_b32 m0, s1
	s_nop 0
	global_load_lds_dwordx4 v[164:165], off
	s_waitcnt lgkmcnt(8)
	s_barrier
	s_waitcnt lgkmcnt(0)
	s_setprio 1
	s_waitcnt lgkmcnt(0)
	v_mfma_f32_16x16x32_bf16 v[62:65], v[104:107], v[120:123], v[62:65]
	v_mfma_f32_16x16x32_bf16 v[58:61], v[112:115], v[120:123], v[58:61]
	v_mfma_f32_16x16x32_bf16 v[54:57], v[104:107], v[128:131], v[54:57]
	v_mfma_f32_16x16x32_bf16 v[50:53], v[112:115], v[128:131], v[50:53]
	v_mfma_f32_16x16x32_bf16 v[46:49], v[104:107], v[136:139], v[46:49]
	v_mfma_f32_16x16x32_bf16 v[42:45], v[112:115], v[136:139], v[42:45]
	v_mfma_f32_16x16x32_bf16 v[38:41], v[104:107], v[144:147], v[38:41]
	v_mfma_f32_16x16x32_bf16 v[34:37], v[112:115], v[144:147], v[34:37]
	v_mfma_f32_16x16x32_bf16 v[62:65], v[108:111], v[124:127], v[62:65]
	v_mfma_f32_16x16x32_bf16 v[58:61], v[116:119], v[124:127], v[58:61]
	v_mfma_f32_16x16x32_bf16 v[54:57], v[108:111], v[132:135], v[54:57]
	v_mfma_f32_16x16x32_bf16 v[50:53], v[116:119], v[132:135], v[50:53]
	v_mfma_f32_16x16x32_bf16 v[46:49], v[108:111], v[140:143], v[46:49]
	v_mfma_f32_16x16x32_bf16 v[42:45], v[116:119], v[140:143], v[42:45]
	v_mfma_f32_16x16x32_bf16 v[38:41], v[108:111], v[148:151], v[38:41]
	v_mfma_f32_16x16x32_bf16 v[34:37], v[116:119], v[148:151], v[34:37]
	s_setprio 0
	s_barrier
	v_readfirstlane_b32 s1, v95
	v_lshl_add_u64 v[120:121], v[156:157], 0, s[28:29]
	s_mov_b32 m0, s1
	v_readfirstlane_b32 s1, v96
	global_load_lds_dwordx4 v[120:121], off
	v_lshl_add_u64 v[120:121], v[158:159], 0, s[28:29]
	s_mov_b32 m0, s1
	v_readfirstlane_b32 s1, v97
	global_load_lds_dwordx4 v[120:121], off
	v_lshl_add_u64 v[152:153], v[152:153], 0, s[28:29]
	s_mov_b32 m0, s1
	v_readfirstlane_b32 s1, v98
	s_barrier
	s_waitcnt lgkmcnt(0)
	s_barrier
	ds_read_b128 v[120:123], v0 offset:49152
	ds_read_b128 v[124:127], v0 offset:50176
	ds_read_b128 v[128:131], v0 offset:51200
	ds_read_b128 v[132:135], v0 offset:52224
	ds_read_b128 v[136:139], v0 offset:53248
	ds_read_b128 v[140:143], v0 offset:54272
	ds_read_b128 v[144:147], v0 offset:55296
	ds_read_b128 v[148:151], v0 offset:56320
	global_load_lds_dwordx4 v[152:153], off
	v_lshl_add_u64 v[152:153], v[154:155], 0, s[28:29]
	s_mov_b32 m0, s1
	s_nop 0
	global_load_lds_dwordx4 v[152:153], off
	s_barrier
	s_waitcnt lgkmcnt(0)
	s_setprio 1
	s_waitcnt lgkmcnt(0)
	v_mfma_f32_16x16x32_bf16 v[2:5], v[104:107], v[120:123], v[2:5]
	v_mfma_f32_16x16x32_bf16 v[6:9], v[112:115], v[120:123], v[6:9]
	v_mfma_f32_16x16x32_bf16 v[10:13], v[104:107], v[128:131], v[10:13]
	v_mfma_f32_16x16x32_bf16 v[14:17], v[112:115], v[128:131], v[14:17]
	v_mfma_f32_16x16x32_bf16 v[18:21], v[104:107], v[136:139], v[18:21]
	v_mfma_f32_16x16x32_bf16 v[22:25], v[112:115], v[136:139], v[22:25]
	v_mfma_f32_16x16x32_bf16 v[26:29], v[104:107], v[144:147], v[26:29]
	v_mfma_f32_16x16x32_bf16 v[30:33], v[112:115], v[144:147], v[30:33]
	v_mfma_f32_16x16x32_bf16 v[2:5], v[108:111], v[124:127], v[2:5]
	v_mfma_f32_16x16x32_bf16 v[6:9], v[116:119], v[124:127], v[6:9]
	v_mfma_f32_16x16x32_bf16 v[10:13], v[108:111], v[132:135], v[10:13]
	v_mfma_f32_16x16x32_bf16 v[14:17], v[116:119], v[132:135], v[14:17]
	v_mfma_f32_16x16x32_bf16 v[18:21], v[108:111], v[140:143], v[18:21]
	v_mfma_f32_16x16x32_bf16 v[22:25], v[116:119], v[140:143], v[22:25]
	v_mfma_f32_16x16x32_bf16 v[26:29], v[108:111], v[148:151], v[26:29]
	v_mfma_f32_16x16x32_bf16 v[30:33], v[116:119], v[148:151], v[30:33]
	s_setprio 0
	s_barrier
	v_readfirstlane_b32 s1, v100
	v_lshl_add_u64 v[104:105], v[160:161], 0, s[28:29]
	s_mov_b32 m0, s1
	v_readfirstlane_b32 s1, v101
	global_load_lds_dwordx4 v[104:105], off
	v_lshl_add_u64 v[104:105], v[162:163], 0, s[28:29]
	s_mov_b32 m0, s1
	s_add_i32 s0, s0, 2
	global_load_lds_dwordx4 v[104:105], off
	s_waitcnt vmcnt(6)
	s_add_u32 s10, s10, 0x100
	s_addc_u32 s11, s11, 0
	s_cmp_lt_u32 s0, 28
	s_barrier
	s_barrier
	s_cbranch_scc1 .LBB0_108
	s_mov_b64 s[10:11], 0xf80
	v_readfirstlane_b32 s0, v102
	v_lshl_add_u64 v[68:69], v[68:69], 0, s[10:11]
	s_mov_b32 m0, s0
	v_readfirstlane_b32 s0, v103
	s_waitcnt vmcnt(0)
	ds_read_b128 v[70:73], v99
	ds_read_b128 v[74:77], v99 offset:1024
	ds_read_b128 v[78:81], v99 offset:2048
	ds_read_b128 v[88:91], v99 offset:3072
	ds_read_b128 v[92:95], v0
	ds_read_b128 v[104:107], v0 offset:1024
	ds_read_b128 v[108:111], v0 offset:2048
	ds_read_b128 v[112:115], v0 offset:3072
	ds_read_b128 v[116:119], v0 offset:4096
	ds_read_b128 v[120:123], v0 offset:5120
	ds_read_b128 v[124:127], v0 offset:6144
	ds_read_b128 v[128:131], v0 offset:7168
	global_load_lds_dwordx4 v[68:69], off
	v_lshl_add_u64 v[66:67], v[66:67], 0, s[10:11]
	s_mov_b32 m0, s0
	s_nop 0
	global_load_lds_dwordx4 v[66:67], off
	s_barrier
	s_waitcnt lgkmcnt(0)
	s_setprio 1
	s_waitcnt lgkmcnt(0)
	v_mfma_f32_16x16x32_bf16 v[62:65], v[70:73], v[92:95], v[62:65]
	v_mfma_f32_16x16x32_bf16 v[58:61], v[78:81], v[92:95], v[58:61]
	v_mfma_f32_16x16x32_bf16 v[54:57], v[70:73], v[108:111], v[54:57]
	v_mfma_f32_16x16x32_bf16 v[50:53], v[78:81], v[108:111], v[50:53]
	v_mfma_f32_16x16x32_bf16 v[46:49], v[70:73], v[116:119], v[46:49]
	v_mfma_f32_16x16x32_bf16 v[42:45], v[78:81], v[116:119], v[42:45]
	v_mfma_f32_16x16x32_bf16 v[38:41], v[70:73], v[124:127], v[38:41]
	v_mfma_f32_16x16x32_bf16 v[34:37], v[78:81], v[124:127], v[34:37]
	v_mfma_f32_16x16x32_bf16 v[62:65], v[74:77], v[104:107], v[62:65]
	v_mfma_f32_16x16x32_bf16 v[58:61], v[88:91], v[104:107], v[58:61]
	v_mfma_f32_16x16x32_bf16 v[54:57], v[74:77], v[112:115], v[54:57]
	v_mfma_f32_16x16x32_bf16 v[50:53], v[88:91], v[112:115], v[50:53]
	v_mfma_f32_16x16x32_bf16 v[46:49], v[74:77], v[120:123], v[46:49]
	v_mfma_f32_16x16x32_bf16 v[42:45], v[88:91], v[120:123], v[42:45]
	v_mfma_f32_16x16x32_bf16 v[38:41], v[74:77], v[128:131], v[38:41]
	v_mfma_f32_16x16x32_bf16 v[34:37], v[88:91], v[128:131], v[34:37]
	s_setprio 0
	s_barrier
	s_barrier
	s_waitcnt lgkmcnt(0)
	s_barrier
	s_waitcnt vmcnt(0)
	ds_read_b128 v[66:69], v0 offset:16384
	ds_read_b128 v[92:95], v0 offset:17408
	ds_read_b128 v[100:103], v0 offset:18432
	ds_read_b128 v[104:107], v0 offset:19456
	ds_read_b128 v[108:111], v0 offset:20480
	ds_read_b128 v[112:115], v0 offset:21504
	ds_read_b128 v[116:119], v0 offset:22528
	ds_read_b128 v[120:123], v0 offset:23552
	s_waitcnt vmcnt(4)
	s_barrier
	s_waitcnt lgkmcnt(0)
	s_setprio 1
	s_waitcnt lgkmcnt(3)
	v_mfma_f32_16x16x32_bf16 v[18:21], v[70:73], v[108:111], v[18:21]
	v_mfma_f32_16x16x32_bf16 v[2:5], v[70:73], v[66:69], v[2:5]
	v_mfma_f32_16x16x32_bf16 v[6:9], v[78:81], v[66:69], v[6:9]
	s_waitcnt lgkmcnt(2)
	v_mfma_f32_16x16x32_bf16 v[66:69], v[74:77], v[112:115], v[18:21]
	v_mfma_f32_16x16x32_bf16 v[18:21], v[78:81], v[108:111], v[22:25]
	v_mfma_f32_16x16x32_bf16 v[2:5], v[74:77], v[92:95], v[2:5]
	v_mfma_f32_16x16x32_bf16 v[6:9], v[88:91], v[92:95], v[6:9]
	v_mfma_f32_16x16x32_bf16 v[10:13], v[70:73], v[100:103], v[10:13]
	v_mfma_f32_16x16x32_bf16 v[14:17], v[78:81], v[100:103], v[14:17]
	v_mfma_f32_16x16x32_bf16 v[92:95], v[88:91], v[112:115], v[18:21]
	s_waitcnt lgkmcnt(1)
	v_mfma_f32_16x16x32_bf16 v[18:21], v[70:73], v[116:119], v[26:29]
	v_mfma_f32_16x16x32_bf16 v[10:13], v[74:77], v[104:107], v[10:13]
	v_mfma_f32_16x16x32_bf16 v[14:17], v[88:91], v[104:107], v[14:17]
	s_waitcnt lgkmcnt(0)
	v_mfma_f32_16x16x32_bf16 v[70:73], v[74:77], v[120:123], v[18:21]
	v_mfma_f32_16x16x32_bf16 v[18:21], v[78:81], v[116:119], v[30:33]
	v_mfma_f32_16x16x32_bf16 v[74:77], v[88:91], v[120:123], v[18:21]
	s_setprio 0
	s_barrier
	ds_read_b128 v[78:81], v99 offset:32768
	ds_read_b128 v[88:91], v99 offset:33792
	ds_read_b128 v[100:103], v99 offset:34816
	ds_read_b128 v[96:99], v99 offset:35840
	s_nop 0
	ds_read_b128 v[18:21], v0 offset:32768
	ds_read_b128 v[22:25], v0 offset:33792
	ds_read_b128 v[26:29], v0 offset:34816
	ds_read_b128 v[30:33], v0 offset:35840
	ds_read_b128 v[104:107], v0 offset:36864
	ds_read_b128 v[108:111], v0 offset:37888
	ds_read_b128 v[112:115], v0 offset:38912
	ds_read_b128 v[116:119], v0 offset:39936
	s_waitcnt vmcnt(2)
	s_barrier
	s_waitcnt lgkmcnt(0)
	s_setprio 1
	s_waitcnt lgkmcnt(7)
	v_mfma_f32_16x16x32_bf16 v[62:65], v[78:81], v[18:21], v[62:65]
	v_mfma_f32_16x16x32_bf16 v[18:21], v[100:103], v[18:21], v[58:61]
	s_waitcnt lgkmcnt(6)
	v_mfma_f32_16x16x32_bf16 v[58:61], v[96:99], v[22:25], v[18:21]
	s_waitcnt lgkmcnt(5)
	v_mfma_f32_16x16x32_bf16 v[18:21], v[78:81], v[26:29], v[54:57]
	s_waitcnt lgkmcnt(4)
	v_mfma_f32_16x16x32_bf16 v[54:57], v[88:91], v[30:33], v[18:21]
	v_mfma_f32_16x16x32_bf16 v[18:21], v[100:103], v[26:29], v[50:53]
	v_mfma_f32_16x16x32_bf16 v[50:53], v[96:99], v[30:33], v[18:21]
	s_waitcnt lgkmcnt(3)
	v_mfma_f32_16x16x32_bf16 v[18:21], v[78:81], v[104:107], v[46:49]
	s_waitcnt lgkmcnt(2)
	v_mfma_f32_16x16x32_bf16 v[46:49], v[88:91], v[108:111], v[18:21]
	v_mfma_f32_16x16x32_bf16 v[18:21], v[100:103], v[104:107], v[42:45]
	v_mfma_f32_16x16x32_bf16 v[42:45], v[96:99], v[108:111], v[18:21]
	s_waitcnt lgkmcnt(1)
	v_mfma_f32_16x16x32_bf16 v[18:21], v[78:81], v[112:115], v[38:41]
	s_waitcnt lgkmcnt(0)
	v_mfma_f32_16x16x32_bf16 v[38:41], v[88:91], v[116:119], v[18:21]
	v_mfma_f32_16x16x32_bf16 v[18:21], v[100:103], v[112:115], v[34:37]
	v_mfma_f32_16x16x32_bf16 v[62:65], v[88:91], v[22:25], v[62:65]
	v_mfma_f32_16x16x32_bf16 v[34:37], v[96:99], v[116:119], v[18:21]
	s_setprio 0
	s_barrier
	s_waitcnt vmcnt(0)
	s_barrier
	s_waitcnt lgkmcnt(0)
	s_barrier
	s_nop 1
	ds_read_b128 v[18:21], v0 offset:49152
	ds_read_b128 v[22:25], v0 offset:50176
	ds_read_b128 v[104:107], v0 offset:51200
	ds_read_b128 v[108:111], v0 offset:52224
	ds_read_b128 v[112:115], v0 offset:53248
	ds_read_b128 v[116:119], v0 offset:54272
	ds_read_b128 v[120:123], v0 offset:55296
	ds_read_b128 v[124:127], v0 offset:56320
	s_barrier
	s_waitcnt lgkmcnt(0)
	s_setprio 1
	s_waitcnt lgkmcnt(7)
	v_mfma_f32_16x16x32_bf16 v[2:5], v[78:81], v[18:21], v[2:5]
	s_waitcnt lgkmcnt(6)
	v_mfma_f32_16x16x32_bf16 v[30:33], v[88:91], v[22:25], v[2:5]
	v_mfma_f32_16x16x32_bf16 v[2:5], v[100:103], v[18:21], v[6:9]
	v_mfma_f32_16x16x32_bf16 v[26:29], v[96:99], v[22:25], v[2:5]
	s_waitcnt lgkmcnt(5)
	v_mfma_f32_16x16x32_bf16 v[2:5], v[78:81], v[104:107], v[10:13]
	s_waitcnt lgkmcnt(4)
	v_mfma_f32_16x16x32_bf16 v[22:25], v[88:91], v[108:111], v[2:5]
	v_mfma_f32_16x16x32_bf16 v[2:5], v[100:103], v[104:107], v[14:17]
	v_mfma_f32_16x16x32_bf16 v[18:21], v[96:99], v[108:111], v[2:5]
	s_waitcnt lgkmcnt(3)
	v_mfma_f32_16x16x32_bf16 v[2:5], v[78:81], v[112:115], v[66:69]
	s_waitcnt lgkmcnt(2)
	v_mfma_f32_16x16x32_bf16 v[14:17], v[88:91], v[116:119], v[2:5]
	v_mfma_f32_16x16x32_bf16 v[2:5], v[100:103], v[112:115], v[92:95]
	v_mfma_f32_16x16x32_bf16 v[10:13], v[96:99], v[116:119], v[2:5]
	s_waitcnt lgkmcnt(1)
	v_mfma_f32_16x16x32_bf16 v[2:5], v[78:81], v[120:123], v[70:73]
	s_waitcnt lgkmcnt(0)
	v_mfma_f32_16x16x32_bf16 v[6:9], v[88:91], v[124:127], v[2:5]
	v_mfma_f32_16x16x32_bf16 v[2:5], v[100:103], v[120:123], v[74:77]
	v_mfma_f32_16x16x32_bf16 v[2:5], v[96:99], v[124:127], v[2:5]
	s_setprio 0
	s_movk_i32 s0, 0x100
	v_cmp_gt_u32_e32 vcc, s0, v82
	s_barrier
	s_and_saveexec_b64 s[0:1], vcc
	s_cbranch_execz .LBB0_111
	s_barrier

.LBB0_180:
	ds_read_b128 v[164:167], v151
	ds_read_b128 v[168:171], v151 offset:1024
	ds_read_b128 v[172:175], v151 offset:2048
	ds_read_b128 v[176:179], v151 offset:3072
	v_add_u32_e32 v162, 0xc000, v147
	v_lshl_add_u64 v[204:205], v[138:139], 0, s[12:13]
	v_readfirstlane_b32 s1, v162
	v_lshl_add_u64 v[210:211], v[204:205], 0, s[60:61]
	s_mov_b32 m0, s1
	v_add_u32_e32 v163, 0xe000, v147
	ds_read_b128 v[180:183], v0
	ds_read_b128 v[184:187], v0 offset:1024
	ds_read_b128 v[188:191], v0 offset:2048
	ds_read_b128 v[192:195], v0 offset:3072
	ds_read_b128 v[196:199], v0 offset:4096
	ds_read_b128 v[200:203], v0 offset:5120
	ds_read_b128 v[222:225], v0 offset:6144
	ds_read_b128 v[232:235], v0 offset:7168
	global_load_lds_dwordx4 v[210:211], off
	v_lshl_add_u64 v[210:211], v[140:141], 0, s[12:13]
	v_readfirstlane_b32 s1, v163
	v_lshl_add_u64 v[216:217], v[210:211], 0, s[60:61]
	s_mov_b32 m0, s1
	s_nop 0
	global_load_lds_dwordx4 v[216:217], off
	s_waitcnt lgkmcnt(8)
	s_barrier
	s_waitcnt lgkmcnt(0)
	s_setprio 1
	s_waitcnt lgkmcnt(0)
	v_mfma_f32_16x16x32_bf16 v[126:129], v[164:167], v[180:183], v[126:129]
	v_mfma_f32_16x16x32_bf16 v[122:125], v[172:175], v[180:183], v[122:125]
	v_mfma_f32_16x16x32_bf16 v[118:121], v[164:167], v[188:191], v[118:121]
	v_mfma_f32_16x16x32_bf16 v[114:117], v[172:175], v[188:191], v[114:117]
	v_mfma_f32_16x16x32_bf16 v[110:113], v[164:167], v[196:199], v[110:113]
	v_mfma_f32_16x16x32_bf16 v[106:109], v[172:175], v[196:199], v[106:109]
	v_mfma_f32_16x16x32_bf16 v[102:105], v[164:167], v[222:225], v[102:105]
	v_mfma_f32_16x16x32_bf16 v[98:101], v[172:175], v[222:225], v[98:101]
	v_mfma_f32_16x16x32_bf16 v[126:129], v[168:171], v[184:187], v[126:129]
	v_mfma_f32_16x16x32_bf16 v[122:125], v[176:179], v[184:187], v[122:125]
	v_mfma_f32_16x16x32_bf16 v[118:121], v[168:171], v[192:195], v[118:121]
	v_mfma_f32_16x16x32_bf16 v[114:117], v[176:179], v[192:195], v[114:117]
	v_mfma_f32_16x16x32_bf16 v[110:113], v[168:171], v[200:203], v[110:113]
	v_mfma_f32_16x16x32_bf16 v[106:109], v[176:179], v[200:203], v[106:109]
	v_mfma_f32_16x16x32_bf16 v[102:105], v[168:171], v[232:235], v[102:105]
	v_mfma_f32_16x16x32_bf16 v[98:101], v[176:179], v[232:235], v[98:101]
	s_setprio 0
	s_barrier
	v_lshl_add_u64 v[216:217], v[134:135], 0, s[12:13]
	v_readfirstlane_b32 s1, v149
	v_lshl_add_u64 v[218:219], v[216:217], 0, s[74:75]
	s_mov_b32 m0, s1
	ds_read_b128 v[236:239], v151 offset:16384
	ds_read_b128 v[240:243], v151 offset:17408
	ds_read_b128 v[244:247], v151 offset:18432
	ds_read_b128 v[248:251], v151 offset:19456
	global_load_lds_dwordx4 v[218:219], off
	v_lshl_add_u64 v[218:219], v[136:137], 0, s[12:13]
	v_readfirstlane_b32 s1, v150
	v_lshl_add_u64 v[228:229], v[218:219], 0, s[74:75]
	s_mov_b32 m0, s1
	s_nop 0
	global_load_lds_dwordx4 v[228:229], off
	s_barrier
	s_waitcnt lgkmcnt(0)
	s_setprio 1
	s_waitcnt lgkmcnt(0)
	v_mfma_f32_16x16x32_bf16 v[94:97], v[236:239], v[180:183], v[94:97]
	v_mfma_f32_16x16x32_bf16 v[90:93], v[244:247], v[180:183], v[90:93]
	v_mfma_f32_16x16x32_bf16 v[86:89], v[236:239], v[188:191], v[86:89]
	v_mfma_f32_16x16x32_bf16 v[82:85], v[244:247], v[188:191], v[82:85]
	v_mfma_f32_16x16x32_bf16 v[78:81], v[236:239], v[196:199], v[78:81]
	v_mfma_f32_16x16x32_bf16 v[74:77], v[244:247], v[196:199], v[74:77]
	v_mfma_f32_16x16x32_bf16 v[70:73], v[236:239], v[222:225], v[70:73]
	v_mfma_f32_16x16x32_bf16 v[66:69], v[244:247], v[222:225], v[66:69]
	v_mfma_f32_16x16x32_bf16 v[94:97], v[240:243], v[184:187], v[94:97]
	v_mfma_f32_16x16x32_bf16 v[90:93], v[248:251], v[184:187], v[90:93]
	v_mfma_f32_16x16x32_bf16 v[86:89], v[240:243], v[192:195], v[86:89]
	v_mfma_f32_16x16x32_bf16 v[82:85], v[248:251], v[192:195], v[82:85]
	v_mfma_f32_16x16x32_bf16 v[78:81], v[240:243], v[200:203], v[78:81]
	v_mfma_f32_16x16x32_bf16 v[74:77], v[248:251], v[200:203], v[74:77]
	v_mfma_f32_16x16x32_bf16 v[70:73], v[240:243], v[232:235], v[70:73]
	v_mfma_f32_16x16x32_bf16 v[66:69], v[248:251], v[232:235], v[66:69]
	s_setprio 0
	v_readfirstlane_b32 s1, v147
	v_lshl_add_u64 v[228:229], v[204:205], 0, s[74:75]
	s_mov_b32 m0, s1
	v_readfirstlane_b32 s1, v148
	s_barrier
	ds_read_b128 v[180:183], v0 offset:16384
	ds_read_b128 v[184:187], v0 offset:17408
	ds_read_b128 v[188:191], v0 offset:18432
	ds_read_b128 v[192:195], v0 offset:19456
	ds_read_b128 v[196:199], v0 offset:20480
	ds_read_b128 v[200:203], v0 offset:21504
	ds_read_b128 v[222:225], v0 offset:22528
	ds_read_b128 v[232:235], v0 offset:23552
	global_load_lds_dwordx4 v[228:229], off
	v_lshl_add_u64 v[228:229], v[210:211], 0, s[74:75]
	s_mov_b32 m0, s1
	s_nop 0
	global_load_lds_dwordx4 v[228:229], off
	s_barrier
	s_waitcnt lgkmcnt(0)
	s_setprio 1
	s_waitcnt lgkmcnt(0)
	v_mfma_f32_16x16x32_bf16 v[62:65], v[164:167], v[180:183], v[62:65]
	v_mfma_f32_16x16x32_bf16 v[58:61], v[172:175], v[180:183], v[58:61]
	v_mfma_f32_16x16x32_bf16 v[54:57], v[164:167], v[188:191], v[54:57]
	v_mfma_f32_16x16x32_bf16 v[50:53], v[172:175], v[188:191], v[50:53]
	v_mfma_f32_16x16x32_bf16 v[46:49], v[164:167], v[196:199], v[46:49]
	v_mfma_f32_16x16x32_bf16 v[42:45], v[172:175], v[196:199], v[42:45]
	v_mfma_f32_16x16x32_bf16 v[38:41], v[164:167], v[222:225], v[38:41]
	v_mfma_f32_16x16x32_bf16 v[34:37], v[172:175], v[222:225], v[34:37]
	v_mfma_f32_16x16x32_bf16 v[62:65], v[168:171], v[184:187], v[62:65]
	v_mfma_f32_16x16x32_bf16 v[58:61], v[176:179], v[184:187], v[58:61]
	v_mfma_f32_16x16x32_bf16 v[54:57], v[168:171], v[192:195], v[54:57]
	v_mfma_f32_16x16x32_bf16 v[50:53], v[176:179], v[192:195], v[50:53]
	v_mfma_f32_16x16x32_bf16 v[46:49], v[168:171], v[200:203], v[46:49]
	v_mfma_f32_16x16x32_bf16 v[42:45], v[176:179], v[200:203], v[42:45]
	v_mfma_f32_16x16x32_bf16 v[38:41], v[168:171], v[232:235], v[38:41]
	v_mfma_f32_16x16x32_bf16 v[34:37], v[176:179], v[232:235], v[34:37]
	s_setprio 0
	s_barrier
	v_readfirstlane_b32 s1, v152
	v_lshl_add_u64 v[164:165], v[216:217], 0, s[18:19]
	s_mov_b32 m0, s1
	v_readfirstlane_b32 s1, v153
	global_load_lds_dwordx4 v[164:165], off
	v_lshl_add_u64 v[164:165], v[218:219], 0, s[18:19]
	s_mov_b32 m0, s1
	s_nop 0
	global_load_lds_dwordx4 v[164:165], off
	s_waitcnt vmcnt(6)
	s_barrier
	s_setprio 1
	v_mfma_f32_16x16x32_bf16 v[30:33], v[236:239], v[180:183], v[30:33]
	v_mfma_f32_16x16x32_bf16 v[26:29], v[244:247], v[180:183], v[26:29]
	v_mfma_f32_16x16x32_bf16 v[22:25], v[236:239], v[188:191], v[22:25]
	v_mfma_f32_16x16x32_bf16 v[18:21], v[244:247], v[188:191], v[18:21]
	v_mfma_f32_16x16x32_bf16 v[14:17], v[236:239], v[196:199], v[14:17]
	v_mfma_f32_16x16x32_bf16 v[10:13], v[244:247], v[196:199], v[10:13]
	v_mfma_f32_16x16x32_bf16 v[6:9], v[236:239], v[222:225], v[6:9]
	v_mfma_f32_16x16x32_bf16 v[2:5], v[244:247], v[222:225], v[2:5]
	v_mfma_f32_16x16x32_bf16 v[30:33], v[240:243], v[184:187], v[30:33]
	v_mfma_f32_16x16x32_bf16 v[26:29], v[248:251], v[184:187], v[26:29]
	v_mfma_f32_16x16x32_bf16 v[22:25], v[240:243], v[192:195], v[22:25]
	v_mfma_f32_16x16x32_bf16 v[18:21], v[248:251], v[192:195], v[18:21]
	v_mfma_f32_16x16x32_bf16 v[14:17], v[240:243], v[200:203], v[14:17]
	v_mfma_f32_16x16x32_bf16 v[10:13], v[248:251], v[200:203], v[10:13]
	v_mfma_f32_16x16x32_bf16 v[6:9], v[240:243], v[232:235], v[6:9]
	v_mfma_f32_16x16x32_bf16 v[2:5], v[248:251], v[232:235], v[2:5]
	s_setprio 0
	s_barrier
	ds_read_b128 v[164:167], v151 offset:32768
	ds_read_b128 v[168:171], v151 offset:33792
	ds_read_b128 v[172:175], v151 offset:34816
	ds_read_b128 v[176:179], v151 offset:35840
	v_readfirstlane_b32 s1, v154
	v_lshl_add_u64 v[228:229], v[204:205], 0, s[18:19]
	s_mov_b32 m0, s1
	v_readfirstlane_b32 s1, v155
	ds_read_b128 v[180:183], v0 offset:32768
	ds_read_b128 v[184:187], v0 offset:33792
	ds_read_b128 v[188:191], v0 offset:34816
	ds_read_b128 v[192:195], v0 offset:35840
	ds_read_b128 v[196:199], v0 offset:36864
	ds_read_b128 v[200:203], v0 offset:37888
	ds_read_b128 v[222:225], v0 offset:38912
	ds_read_b128 v[232:235], v0 offset:39936
	global_load_lds_dwordx4 v[228:229], off
	v_lshl_add_u64 v[228:229], v[210:211], 0, s[18:19]
	s_mov_b32 m0, s1
	s_nop 0
	global_load_lds_dwordx4 v[228:229], off
	s_waitcnt lgkmcnt(8)
	s_barrier
	s_waitcnt lgkmcnt(0)
	s_setprio 1
	s_waitcnt lgkmcnt(0)
	v_mfma_f32_16x16x32_bf16 v[126:129], v[164:167], v[180:183], v[126:129]
	v_mfma_f32_16x16x32_bf16 v[122:125], v[172:175], v[180:183], v[122:125]
	v_mfma_f32_16x16x32_bf16 v[118:121], v[164:167], v[188:191], v[118:121]
	v_mfma_f32_16x16x32_bf16 v[114:117], v[172:175], v[188:191], v[114:117]
	v_mfma_f32_16x16x32_bf16 v[110:113], v[164:167], v[196:199], v[110:113]
	v_mfma_f32_16x16x32_bf16 v[106:109], v[172:175], v[196:199], v[106:109]
	v_mfma_f32_16x16x32_bf16 v[102:105], v[164:167], v[222:225], v[102:105]
	v_mfma_f32_16x16x32_bf16 v[98:101], v[172:175], v[222:225], v[98:101]
	v_mfma_f32_16x16x32_bf16 v[126:129], v[168:171], v[184:187], v[126:129]
	v_mfma_f32_16x16x32_bf16 v[122:125], v[176:179], v[184:187], v[122:125]
	v_mfma_f32_16x16x32_bf16 v[118:121], v[168:171], v[192:195], v[118:121]
	v_mfma_f32_16x16x32_bf16 v[114:117], v[176:179], v[192:195], v[114:117]
	v_mfma_f32_16x16x32_bf16 v[110:113], v[168:171], v[200:203], v[110:113]
	v_mfma_f32_16x16x32_bf16 v[106:109], v[176:179], v[200:203], v[106:109]
	v_mfma_f32_16x16x32_bf16 v[102:105], v[168:171], v[232:235], v[102:105]
	v_mfma_f32_16x16x32_bf16 v[98:101], v[176:179], v[232:235], v[98:101]
	s_setprio 0
	s_barrier
	v_readfirstlane_b32 s1, v156
	v_lshl_add_u64 v[228:229], v[216:217], 0, s[28:29]
	s_mov_b32 m0, s1
	v_readfirstlane_b32 s1, v157
	ds_read_b128 v[236:239], v151 offset:49152
	ds_read_b128 v[240:243], v151 offset:50176
	ds_read_b128 v[244:247], v151 offset:51200
	ds_read_b128 v[248:251], v151 offset:52224
	global_load_lds_dwordx4 v[228:229], off
	v_lshl_add_u64 v[228:229], v[218:219], 0, s[28:29]
	s_mov_b32 m0, s1
	s_nop 0
	global_load_lds_dwordx4 v[228:229], off
	s_barrier
	s_waitcnt lgkmcnt(0)
	s_setprio 1
	s_waitcnt lgkmcnt(0)
	v_mfma_f32_16x16x32_bf16 v[94:97], v[236:239], v[180:183], v[94:97]
	v_mfma_f32_16x16x32_bf16 v[90:93], v[244:247], v[180:183], v[90:93]
	v_mfma_f32_16x16x32_bf16 v[86:89], v[236:239], v[188:191], v[86:89]
	v_mfma_f32_16x16x32_bf16 v[82:85], v[244:247], v[188:191], v[82:85]
	v_mfma_f32_16x16x32_bf16 v[78:81], v[236:239], v[196:199], v[78:81]
	v_mfma_f32_16x16x32_bf16 v[74:77], v[244:247], v[196:199], v[74:77]
	v_mfma_f32_16x16x32_bf16 v[70:73], v[236:239], v[222:225], v[70:73]
	v_mfma_f32_16x16x32_bf16 v[66:69], v[244:247], v[222:225], v[66:69]
	v_mfma_f32_16x16x32_bf16 v[94:97], v[240:243], v[184:187], v[94:97]
	v_mfma_f32_16x16x32_bf16 v[90:93], v[248:251], v[184:187], v[90:93]
	v_mfma_f32_16x16x32_bf16 v[86:89], v[240:243], v[192:195], v[86:89]
	v_mfma_f32_16x16x32_bf16 v[82:85], v[248:251], v[192:195], v[82:85]
	v_mfma_f32_16x16x32_bf16 v[78:81], v[240:243], v[200:203], v[78:81]
	v_mfma_f32_16x16x32_bf16 v[74:77], v[248:251], v[200:203], v[74:77]
	v_mfma_f32_16x16x32_bf16 v[70:73], v[240:243], v[232:235], v[70:73]
	v_mfma_f32_16x16x32_bf16 v[66:69], v[248:251], v[232:235], v[66:69]
	s_setprio 0
	v_readfirstlane_b32 s1, v158
	v_lshl_add_u64 v[204:205], v[204:205], 0, s[28:29]
	s_mov_b32 m0, s1
	v_readfirstlane_b32 s1, v159
	s_barrier
	ds_read_b128 v[180:183], v0 offset:49152
	ds_read_b128 v[184:187], v0 offset:50176
	ds_read_b128 v[188:191], v0 offset:51200
	ds_read_b128 v[192:195], v0 offset:52224
	ds_read_b128 v[196:199], v0 offset:53248
	ds_read_b128 v[200:203], v0 offset:54272
	ds_read_b128 v[222:225], v0 offset:55296
	ds_read_b128 v[232:235], v0 offset:56320
	global_load_lds_dwordx4 v[204:205], off
	v_lshl_add_u64 v[204:205], v[210:211], 0, s[28:29]
	s_mov_b32 m0, s1
	s_nop 0
	global_load_lds_dwordx4 v[204:205], off
	s_barrier
	s_waitcnt lgkmcnt(0)
	s_setprio 1
	s_waitcnt lgkmcnt(0)
	v_mfma_f32_16x16x32_bf16 v[62:65], v[164:167], v[180:183], v[62:65]
	v_mfma_f32_16x16x32_bf16 v[58:61], v[172:175], v[180:183], v[58:61]
	v_mfma_f32_16x16x32_bf16 v[54:57], v[164:167], v[188:191], v[54:57]
	v_mfma_f32_16x16x32_bf16 v[50:53], v[172:175], v[188:191], v[50:53]
	v_mfma_f32_16x16x32_bf16 v[46:49], v[164:167], v[196:199], v[46:49]
	v_mfma_f32_16x16x32_bf16 v[42:45], v[172:175], v[196:199], v[42:45]
	v_mfma_f32_16x16x32_bf16 v[38:41], v[164:167], v[222:225], v[38:41]
	v_mfma_f32_16x16x32_bf16 v[34:37], v[172:175], v[222:225], v[34:37]
	v_mfma_f32_16x16x32_bf16 v[62:65], v[168:171], v[184:187], v[62:65]
	v_mfma_f32_16x16x32_bf16 v[58:61], v[176:179], v[184:187], v[58:61]
	v_mfma_f32_16x16x32_bf16 v[54:57], v[168:171], v[192:195], v[54:57]
	v_mfma_f32_16x16x32_bf16 v[50:53], v[176:179], v[192:195], v[50:53]
	v_mfma_f32_16x16x32_bf16 v[46:49], v[168:171], v[200:203], v[46:49]
	v_mfma_f32_16x16x32_bf16 v[42:45], v[176:179], v[200:203], v[42:45]
	v_mfma_f32_16x16x32_bf16 v[38:41], v[168:171], v[232:235], v[38:41]
	v_mfma_f32_16x16x32_bf16 v[34:37], v[176:179], v[232:235], v[34:37]
	s_setprio 0
	s_barrier
	v_readfirstlane_b32 s1, v160
	v_lshl_add_u64 v[164:165], v[216:217], 0, s[30:31]
	s_mov_b32 m0, s1
	v_readfirstlane_b32 s1, v161
	global_load_lds_dwordx4 v[164:165], off
	v_lshl_add_u64 v[164:165], v[218:219], 0, s[30:31]
	s_mov_b32 m0, s1
	s_nop 0
	global_load_lds_dwordx4 v[164:165], off
	s_waitcnt vmcnt(6)
	s_barrier
	s_setprio 1
	v_mfma_f32_16x16x32_bf16 v[30:33], v[236:239], v[180:183], v[30:33]
	v_mfma_f32_16x16x32_bf16 v[26:29], v[244:247], v[180:183], v[26:29]
	v_mfma_f32_16x16x32_bf16 v[22:25], v[236:239], v[188:191], v[22:25]
	v_mfma_f32_16x16x32_bf16 v[18:21], v[244:247], v[188:191], v[18:21]
	v_mfma_f32_16x16x32_bf16 v[14:17], v[236:239], v[196:199], v[14:17]
	v_mfma_f32_16x16x32_bf16 v[10:13], v[244:247], v[196:199], v[10:13]
	v_mfma_f32_16x16x32_bf16 v[6:9], v[236:239], v[222:225], v[6:9]
	v_mfma_f32_16x16x32_bf16 v[2:5], v[244:247], v[222:225], v[2:5]
	v_mfma_f32_16x16x32_bf16 v[30:33], v[240:243], v[184:187], v[30:33]
	v_mfma_f32_16x16x32_bf16 v[26:29], v[248:251], v[184:187], v[26:29]
	v_mfma_f32_16x16x32_bf16 v[22:25], v[240:243], v[192:195], v[22:25]
	v_mfma_f32_16x16x32_bf16 v[18:21], v[248:251], v[192:195], v[18:21]
	v_mfma_f32_16x16x32_bf16 v[14:17], v[240:243], v[200:203], v[14:17]
	v_mfma_f32_16x16x32_bf16 v[10:13], v[248:251], v[200:203], v[10:13]
	v_mfma_f32_16x16x32_bf16 v[6:9], v[240:243], v[232:235], v[6:9]
	v_mfma_f32_16x16x32_bf16 v[2:5], v[248:251], v[232:235], v[2:5]
	s_setprio 0
	s_add_i32 s0, s0, 2
	s_add_u32 s12, s12, 0x100
	s_addc_u32 s13, s13, 0
	s_cmp_lt_u32 s0, 28
	s_barrier
	s_cbranch_scc1 .LBB0_180
	s_mov_b64 s[12:13], 0xf80
	v_readfirstlane_b32 s0, v162
	v_lshl_add_u64 v[132:133], v[132:133], 0, s[12:13]
	s_mov_b32 m0, s0
	v_readfirstlane_b32 s0, v163
	s_waitcnt vmcnt(0)
	ds_read_b128 v[134:137], v151
	ds_read_b128 v[138:141], v151 offset:1024
	ds_read_b128 v[152:155], v151 offset:2048
	ds_read_b128 v[156:159], v151 offset:3072
	ds_read_b128 v[164:167], v0
	ds_read_b128 v[168:171], v0 offset:1024
	ds_read_b128 v[172:175], v0 offset:2048
	ds_read_b128 v[176:179], v0 offset:3072
	ds_read_b128 v[180:183], v0 offset:4096
	ds_read_b128 v[184:187], v0 offset:5120
	ds_read_b128 v[188:191], v0 offset:6144
	ds_read_b128 v[192:195], v0 offset:7168
	global_load_lds_dwordx4 v[132:133], off
	v_lshl_add_u64 v[130:131], v[130:131], 0, s[12:13]
	s_mov_b32 m0, s0
	s_nop 0
	global_load_lds_dwordx4 v[130:131], off
	s_barrier
	s_waitcnt lgkmcnt(0)
	s_setprio 1
	s_waitcnt lgkmcnt(0)
	v_mfma_f32_16x16x32_bf16 v[126:129], v[134:137], v[164:167], v[126:129]
	v_mfma_f32_16x16x32_bf16 v[122:125], v[152:155], v[164:167], v[122:125]
	v_mfma_f32_16x16x32_bf16 v[114:117], v[152:155], v[172:175], v[114:117]
	v_mfma_f32_16x16x32_bf16 v[106:109], v[152:155], v[180:183], v[106:109]
	v_mfma_f32_16x16x32_bf16 v[98:101], v[152:155], v[188:191], v[98:101]
	v_mfma_f32_16x16x32_bf16 v[126:129], v[138:141], v[168:171], v[126:129]
	v_mfma_f32_16x16x32_bf16 v[122:125], v[156:159], v[168:171], v[122:125]
	v_mfma_f32_16x16x32_bf16 v[118:121], v[134:137], v[172:175], v[118:121]
	v_mfma_f32_16x16x32_bf16 v[114:117], v[156:159], v[176:179], v[114:117]
	v_mfma_f32_16x16x32_bf16 v[110:113], v[134:137], v[180:183], v[110:113]
	v_mfma_f32_16x16x32_bf16 v[106:109], v[156:159], v[184:187], v[106:109]
	v_mfma_f32_16x16x32_bf16 v[102:105], v[134:137], v[188:191], v[102:105]
	v_mfma_f32_16x16x32_bf16 v[98:101], v[156:159], v[192:195], v[98:101]
	v_mfma_f32_16x16x32_bf16 v[130:133], v[138:141], v[176:179], v[118:121]
	v_mfma_f32_16x16x32_bf16 v[160:163], v[138:141], v[184:187], v[110:113]
	v_mfma_f32_16x16x32_bf16 v[196:199], v[138:141], v[192:195], v[102:105]
	s_setprio 0
	s_barrier
	s_waitcnt vmcnt(0)
	s_nop 0
	ds_read_b128 v[102:105], v151 offset:16384
	ds_read_b128 v[110:113], v151 offset:17408
	ds_read_b128 v[118:121], v151 offset:18432
	ds_read_b128 v[200:203], v151 offset:19456
	s_barrier
	s_waitcnt lgkmcnt(0)
	s_setprio 1
	s_waitcnt lgkmcnt(1)
	v_mfma_f32_16x16x32_bf16 v[90:93], v[118:121], v[164:167], v[90:93]
	v_mfma_f32_16x16x32_bf16 v[82:85], v[118:121], v[172:175], v[82:85]
	v_mfma_f32_16x16x32_bf16 v[74:77], v[118:121], v[180:183], v[74:77]
	v_mfma_f32_16x16x32_bf16 v[66:69], v[118:121], v[188:191], v[66:69]
	v_mfma_f32_16x16x32_bf16 v[94:97], v[102:105], v[164:167], v[94:97]
	s_waitcnt lgkmcnt(0)
	v_mfma_f32_16x16x32_bf16 v[90:93], v[200:203], v[168:171], v[90:93]
	v_mfma_f32_16x16x32_bf16 v[86:89], v[102:105], v[172:175], v[86:89]
	v_mfma_f32_16x16x32_bf16 v[82:85], v[200:203], v[176:179], v[82:85]
	v_mfma_f32_16x16x32_bf16 v[78:81], v[102:105], v[180:183], v[78:81]
	v_mfma_f32_16x16x32_bf16 v[74:77], v[200:203], v[184:187], v[74:77]
	v_mfma_f32_16x16x32_bf16 v[70:73], v[102:105], v[188:191], v[70:73]
	v_mfma_f32_16x16x32_bf16 v[66:69], v[200:203], v[192:195], v[66:69]
	v_mfma_f32_16x16x32_bf16 v[222:225], v[110:113], v[168:171], v[94:97]
	v_mfma_f32_16x16x32_bf16 v[164:167], v[110:113], v[176:179], v[86:89]
	v_mfma_f32_16x16x32_bf16 v[168:171], v[110:113], v[184:187], v[78:81]
	v_mfma_f32_16x16x32_bf16 v[172:175], v[110:113], v[192:195], v[70:73]
	s_setprio 0
	s_barrier
	s_nop 0
	ds_read_b128 v[70:73], v0 offset:16384
	ds_read_b128 v[78:81], v0 offset:17408
	ds_read_b128 v[86:89], v0 offset:18432
	ds_read_b128 v[94:97], v0 offset:19456
	ds_read_b128 v[176:179], v0 offset:20480
	ds_read_b128 v[180:183], v0 offset:21504
	ds_read_b128 v[184:187], v0 offset:22528
	ds_read_b128 v[188:191], v0 offset:23552
	s_waitcnt vmcnt(4)
	s_barrier
	s_waitcnt lgkmcnt(0)
	s_setprio 1
	s_waitcnt lgkmcnt(7)
	v_mfma_f32_16x16x32_bf16 v[62:65], v[134:137], v[70:73], v[62:65]
	v_mfma_f32_16x16x32_bf16 v[58:61], v[152:155], v[70:73], v[58:61]
	s_waitcnt lgkmcnt(5)
	v_mfma_f32_16x16x32_bf16 v[50:53], v[152:155], v[86:89], v[50:53]
	s_waitcnt lgkmcnt(3)
	v_mfma_f32_16x16x32_bf16 v[42:45], v[152:155], v[176:179], v[42:45]
	s_waitcnt lgkmcnt(1)
	v_mfma_f32_16x16x32_bf16 v[34:37], v[152:155], v[184:187], v[34:37]
	v_mfma_f32_16x16x32_bf16 v[62:65], v[138:141], v[78:81], v[62:65]
	v_mfma_f32_16x16x32_bf16 v[58:61], v[156:159], v[78:81], v[58:61]
	v_mfma_f32_16x16x32_bf16 v[54:57], v[134:137], v[86:89], v[54:57]
	v_mfma_f32_16x16x32_bf16 v[50:53], v[156:159], v[94:97], v[50:53]
	v_mfma_f32_16x16x32_bf16 v[46:49], v[134:137], v[176:179], v[46:49]
	v_mfma_f32_16x16x32_bf16 v[42:45], v[156:159], v[180:183], v[42:45]
	v_mfma_f32_16x16x32_bf16 v[38:41], v[134:137], v[184:187], v[38:41]
	s_waitcnt lgkmcnt(0)
	v_mfma_f32_16x16x32_bf16 v[34:37], v[156:159], v[188:191], v[34:37]
	v_mfma_f32_16x16x32_bf16 v[192:195], v[138:141], v[94:97], v[54:57]
	v_mfma_f32_16x16x32_bf16 v[232:235], v[138:141], v[180:183], v[46:49]
	v_mfma_f32_16x16x32_bf16 v[134:137], v[138:141], v[188:191], v[38:41]
	s_setprio 0
	s_setprio 1
	v_mfma_f32_16x16x32_bf16 v[26:29], v[118:121], v[70:73], v[26:29]
	v_mfma_f32_16x16x32_bf16 v[18:21], v[118:121], v[86:89], v[18:21]
	v_mfma_f32_16x16x32_bf16 v[10:13], v[118:121], v[176:179], v[10:13]
	v_mfma_f32_16x16x32_bf16 v[2:5], v[118:121], v[184:187], v[2:5]
	v_mfma_f32_16x16x32_bf16 v[30:33], v[102:105], v[70:73], v[30:33]
	v_mfma_f32_16x16x32_bf16 v[26:29], v[200:203], v[78:81], v[26:29]
	v_mfma_f32_16x16x32_bf16 v[22:25], v[102:105], v[86:89], v[22:25]
	v_mfma_f32_16x16x32_bf16 v[18:21], v[200:203], v[94:97], v[18:21]
	v_mfma_f32_16x16x32_bf16 v[14:17], v[102:105], v[176:179], v[14:17]
	v_mfma_f32_16x16x32_bf16 v[10:13], v[200:203], v[180:183], v[10:13]
	v_mfma_f32_16x16x32_bf16 v[6:9], v[102:105], v[184:187], v[6:9]
	v_mfma_f32_16x16x32_bf16 v[2:5], v[200:203], v[188:191], v[2:5]
	v_mfma_f32_16x16x32_bf16 v[138:141], v[110:113], v[78:81], v[30:33]
	v_mfma_f32_16x16x32_bf16 v[152:155], v[110:113], v[94:97], v[22:25]
	v_mfma_f32_16x16x32_bf16 v[156:159], v[110:113], v[180:183], v[14:17]
	v_mfma_f32_16x16x32_bf16 v[176:179], v[110:113], v[188:191], v[6:9]
	s_setprio 0
	s_barrier
	s_nop 0
	ds_read_b128 v[6:9], v151 offset:32768
	ds_read_b128 v[14:17], v151 offset:33792
	ds_read_b128 v[180:183], v151 offset:34816
	ds_read_b128 v[184:187], v151 offset:35840
	ds_read_b128 v[22:25], v0 offset:32768
	ds_read_b128 v[30:33], v0 offset:33792
	ds_read_b128 v[38:41], v0 offset:34816
	ds_read_b128 v[46:49], v0 offset:35840
	ds_read_b128 v[54:57], v0 offset:36864
	ds_read_b128 v[188:191], v0 offset:37888
	ds_read_b128 v[200:203], v0 offset:38912
	ds_read_b128 v[236:239], v0 offset:39936
	s_waitcnt vmcnt(2)
	s_barrier
	s_waitcnt lgkmcnt(0)
	s_setprio 1
	s_waitcnt lgkmcnt(7)
	v_mfma_f32_16x16x32_bf16 v[70:73], v[6:9], v[22:25], v[126:129]
	s_waitcnt lgkmcnt(6)
	v_mfma_f32_16x16x32_bf16 v[126:129], v[14:17], v[30:33], v[70:73]
	v_mfma_f32_16x16x32_bf16 v[70:73], v[180:183], v[22:25], v[122:125]
	v_mfma_f32_16x16x32_bf16 v[118:121], v[184:187], v[30:33], v[70:73]
	s_waitcnt lgkmcnt(5)
	v_mfma_f32_16x16x32_bf16 v[70:73], v[6:9], v[38:41], v[130:133]
	s_waitcnt lgkmcnt(4)
	v_mfma_f32_16x16x32_bf16 v[110:113], v[14:17], v[46:49], v[70:73]
	v_mfma_f32_16x16x32_bf16 v[70:73], v[180:183], v[38:41], v[114:117]
	v_mfma_f32_16x16x32_bf16 v[102:105], v[184:187], v[46:49], v[70:73]
	s_waitcnt lgkmcnt(3)
	v_mfma_f32_16x16x32_bf16 v[70:73], v[6:9], v[54:57], v[160:163]
	s_waitcnt lgkmcnt(2)
	v_mfma_f32_16x16x32_bf16 v[94:97], v[14:17], v[188:191], v[70:73]
	v_mfma_f32_16x16x32_bf16 v[70:73], v[180:183], v[54:57], v[106:109]
	v_mfma_f32_16x16x32_bf16 v[86:89], v[184:187], v[188:191], v[70:73]
	s_waitcnt lgkmcnt(1)
	v_mfma_f32_16x16x32_bf16 v[70:73], v[6:9], v[200:203], v[196:199]
	s_waitcnt lgkmcnt(0)
	v_mfma_f32_16x16x32_bf16 v[78:81], v[14:17], v[236:239], v[70:73]
	v_mfma_f32_16x16x32_bf16 v[70:73], v[180:183], v[200:203], v[98:101]
	v_mfma_f32_16x16x32_bf16 v[70:73], v[184:187], v[236:239], v[70:73]
	s_setprio 0
	s_barrier
	ds_read_b128 v[130:133], v151 offset:49152
	ds_read_b128 v[160:163], v151 offset:50176
	ds_read_b128 v[196:199], v151 offset:51200
	ds_read_b128 v[148:151], v151 offset:52224
	s_waitcnt vmcnt(0)
	s_barrier
	s_waitcnt lgkmcnt(0)
	s_setprio 1
	s_waitcnt lgkmcnt(3)
	v_mfma_f32_16x16x32_bf16 v[98:101], v[130:133], v[22:25], v[222:225]
	s_waitcnt lgkmcnt(1)
	v_mfma_f32_16x16x32_bf16 v[22:25], v[196:199], v[22:25], v[90:93]
	s_waitcnt lgkmcnt(0)
	v_mfma_f32_16x16x32_bf16 v[114:117], v[148:151], v[30:33], v[22:25]
	v_mfma_f32_16x16x32_bf16 v[22:25], v[130:133], v[38:41], v[164:167]
	v_mfma_f32_16x16x32_bf16 v[106:109], v[160:163], v[46:49], v[22:25]
	v_mfma_f32_16x16x32_bf16 v[22:25], v[196:199], v[38:41], v[82:85]
	v_mfma_f32_16x16x32_bf16 v[122:125], v[160:163], v[30:33], v[98:101]
	v_mfma_f32_16x16x32_bf16 v[98:101], v[148:151], v[46:49], v[22:25]
	v_mfma_f32_16x16x32_bf16 v[22:25], v[130:133], v[54:57], v[168:171]
	v_mfma_f32_16x16x32_bf16 v[90:93], v[160:163], v[188:191], v[22:25]
	v_mfma_f32_16x16x32_bf16 v[22:25], v[196:199], v[54:57], v[74:77]
	v_mfma_f32_16x16x32_bf16 v[82:85], v[148:151], v[188:191], v[22:25]
	v_mfma_f32_16x16x32_bf16 v[22:25], v[130:133], v[200:203], v[172:175]
	v_mfma_f32_16x16x32_bf16 v[74:77], v[160:163], v[236:239], v[22:25]
	v_mfma_f32_16x16x32_bf16 v[22:25], v[196:199], v[200:203], v[66:69]
	v_mfma_f32_16x16x32_bf16 v[66:69], v[148:151], v[236:239], v[22:25]
	s_setprio 0
	s_barrier
	ds_read_b128 v[164:167], v0 offset:49152
	ds_read_b128 v[168:171], v0 offset:50176
	ds_read_b128 v[172:175], v0 offset:51200
	ds_read_b128 v[188:191], v0 offset:52224
	ds_read_b128 v[200:203], v0 offset:53248
	ds_read_b128 v[222:225], v0 offset:54272
	ds_read_b128 v[236:239], v0 offset:55296
	ds_read_b128 v[240:243], v0 offset:56320
	s_barrier
	s_waitcnt lgkmcnt(0)
	s_setprio 1
	s_waitcnt lgkmcnt(7)
	v_mfma_f32_16x16x32_bf16 v[22:25], v[6:9], v[164:167], v[62:65]
	s_waitcnt lgkmcnt(6)
	v_mfma_f32_16x16x32_bf16 v[62:65], v[14:17], v[168:171], v[22:25]
	v_mfma_f32_16x16x32_bf16 v[22:25], v[180:183], v[164:167], v[58:61]
	v_mfma_f32_16x16x32_bf16 v[54:57], v[184:187], v[168:171], v[22:25]
	s_waitcnt lgkmcnt(5)
	v_mfma_f32_16x16x32_bf16 v[22:25], v[6:9], v[172:175], v[192:195]
	s_waitcnt lgkmcnt(4)
	v_mfma_f32_16x16x32_bf16 v[46:49], v[14:17], v[188:191], v[22:25]
	v_mfma_f32_16x16x32_bf16 v[22:25], v[180:183], v[172:175], v[50:53]
	v_mfma_f32_16x16x32_bf16 v[38:41], v[184:187], v[188:191], v[22:25]
	s_waitcnt lgkmcnt(3)
	v_mfma_f32_16x16x32_bf16 v[22:25], v[6:9], v[200:203], v[232:235]
	s_waitcnt lgkmcnt(1)
	v_mfma_f32_16x16x32_bf16 v[6:9], v[6:9], v[236:239], v[134:137]
	v_mfma_f32_16x16x32_bf16 v[30:33], v[14:17], v[222:225], v[22:25]
	v_mfma_f32_16x16x32_bf16 v[22:25], v[180:183], v[200:203], v[42:45]
	s_waitcnt lgkmcnt(0)
	v_mfma_f32_16x16x32_bf16 v[14:17], v[14:17], v[240:243], v[6:9]
	v_mfma_f32_16x16x32_bf16 v[6:9], v[180:183], v[236:239], v[34:37]
	v_mfma_f32_16x16x32_bf16 v[22:25], v[184:187], v[222:225], v[22:25]
	v_mfma_f32_16x16x32_bf16 v[6:9], v[184:187], v[240:243], v[6:9]
	s_setprio 0
	s_setprio 1
	v_mfma_f32_16x16x32_bf16 v[34:37], v[130:133], v[164:167], v[138:141]
	v_mfma_f32_16x16x32_bf16 v[26:29], v[196:199], v[164:167], v[26:29]
	v_mfma_f32_16x16x32_bf16 v[18:21], v[196:199], v[172:175], v[18:21]
	v_mfma_f32_16x16x32_bf16 v[58:61], v[160:163], v[168:171], v[34:37]
	v_mfma_f32_16x16x32_bf16 v[50:53], v[148:151], v[168:171], v[26:29]
	v_mfma_f32_16x16x32_bf16 v[26:29], v[130:133], v[172:175], v[152:155]
	v_mfma_f32_16x16x32_bf16 v[34:37], v[148:151], v[188:191], v[18:21]
	v_mfma_f32_16x16x32_bf16 v[18:21], v[130:133], v[200:203], v[156:159]
	v_mfma_f32_16x16x32_bf16 v[10:13], v[196:199], v[200:203], v[10:13]
	v_mfma_f32_16x16x32_bf16 v[42:45], v[160:163], v[188:191], v[26:29]
	v_mfma_f32_16x16x32_bf16 v[26:29], v[160:163], v[222:225], v[18:21]
	v_mfma_f32_16x16x32_bf16 v[18:21], v[148:151], v[222:225], v[10:13]
	v_mfma_f32_16x16x32_bf16 v[10:13], v[130:133], v[236:239], v[176:179]
	v_mfma_f32_16x16x32_bf16 v[2:5], v[196:199], v[236:239], v[2:5]
	v_mfma_f32_16x16x32_bf16 v[10:13], v[160:163], v[240:243], v[10:13]
	v_mfma_f32_16x16x32_bf16 v[2:5], v[148:151], v[240:243], v[2:5]
	s_setprio 0
	s_movk_i32 s0, 0x100
	v_cmp_gt_u32_e32 vcc, s0, v142
	s_barrier
	s_and_saveexec_b64 s[0:1], vcc
	s_cbranch_execz .LBB0_183
	s_barrier

.LBB0_678:
	ds_read_b128 v[164:167], v151
	ds_read_b128 v[168:171], v151 offset:1024
	ds_read_b128 v[172:175], v151 offset:2048
	ds_read_b128 v[176:179], v151 offset:3072
	v_add_u32_e32 v162, 0xc000, v147
	v_lshl_add_u64 v[204:205], v[138:139], 0, s[8:9]
	v_readfirstlane_b32 s1, v162
	v_add_u32_e32 v163, 0xe000, v147
	v_lshl_add_u64 v[222:223], v[204:205], 0, s[60:61]
	s_mov_b32 m0, s1
	v_lshl_add_u64 v[216:217], v[140:141], 0, s[8:9]
	v_readfirstlane_b32 s1, v163
	ds_read_b128 v[180:183], v0
	ds_read_b128 v[184:187], v0 offset:1024
	ds_read_b128 v[188:191], v0 offset:2048
	ds_read_b128 v[192:195], v0 offset:3072
	ds_read_b128 v[196:199], v0 offset:4096
	ds_read_b128 v[200:203], v0 offset:5120
	ds_read_b128 v[232:235], v0 offset:6144
	ds_read_b128 v[236:239], v0 offset:7168
	global_load_lds_dwordx4 v[222:223], off
	v_lshl_add_u64 v[222:223], v[216:217], 0, s[60:61]
	s_mov_b32 m0, s1
	s_nop 0
	global_load_lds_dwordx4 v[222:223], off
	s_waitcnt lgkmcnt(8)
	s_barrier
	s_waitcnt lgkmcnt(0)
	s_setprio 1
	s_waitcnt lgkmcnt(0)
	v_mfma_f32_16x16x32_bf16 v[126:129], v[164:167], v[180:183], v[126:129]
	v_mfma_f32_16x16x32_bf16 v[122:125], v[172:175], v[180:183], v[122:125]
	v_mfma_f32_16x16x32_bf16 v[118:121], v[164:167], v[188:191], v[118:121]
	v_mfma_f32_16x16x32_bf16 v[114:117], v[172:175], v[188:191], v[114:117]
	v_mfma_f32_16x16x32_bf16 v[110:113], v[164:167], v[196:199], v[110:113]
	v_mfma_f32_16x16x32_bf16 v[106:109], v[172:175], v[196:199], v[106:109]
	v_mfma_f32_16x16x32_bf16 v[102:105], v[164:167], v[232:235], v[102:105]
	v_mfma_f32_16x16x32_bf16 v[98:101], v[172:175], v[232:235], v[98:101]
	v_mfma_f32_16x16x32_bf16 v[126:129], v[168:171], v[184:187], v[126:129]
	v_mfma_f32_16x16x32_bf16 v[122:125], v[176:179], v[184:187], v[122:125]
	v_mfma_f32_16x16x32_bf16 v[118:121], v[168:171], v[192:195], v[118:121]
	v_mfma_f32_16x16x32_bf16 v[114:117], v[176:179], v[192:195], v[114:117]
	v_mfma_f32_16x16x32_bf16 v[110:113], v[168:171], v[200:203], v[110:113]
	v_mfma_f32_16x16x32_bf16 v[106:109], v[176:179], v[200:203], v[106:109]
	v_mfma_f32_16x16x32_bf16 v[102:105], v[168:171], v[236:239], v[102:105]
	v_mfma_f32_16x16x32_bf16 v[98:101], v[176:179], v[236:239], v[98:101]
	s_setprio 0
	s_barrier
	v_lshl_add_u64 v[210:211], v[134:135], 0, s[8:9]
	v_readfirstlane_b32 s1, v149
	v_lshl_add_u64 v[228:229], v[210:211], 0, s[74:75]
	s_mov_b32 m0, s1
	ds_read_b128 v[240:243], v151 offset:16384
	ds_read_b128 v[244:247], v151 offset:17408
	ds_read_b128 v[248:251], v151 offset:18432
	ds_read_b128 v[222:225], v151 offset:19456
	global_load_lds_dwordx4 v[228:229], off
	v_lshl_add_u64 v[228:229], v[136:137], 0, s[8:9]
	v_readfirstlane_b32 s1, v150
	v_lshl_add_u64 v[218:219], v[228:229], 0, s[74:75]
	s_mov_b32 m0, s1
	s_nop 0
	global_load_lds_dwordx4 v[218:219], off
	s_barrier
	s_waitcnt lgkmcnt(0)
	s_setprio 1
	s_waitcnt lgkmcnt(0)
	v_mfma_f32_16x16x32_bf16 v[94:97], v[240:243], v[180:183], v[94:97]
	v_mfma_f32_16x16x32_bf16 v[90:93], v[248:251], v[180:183], v[90:93]
	v_mfma_f32_16x16x32_bf16 v[86:89], v[240:243], v[188:191], v[86:89]
	v_mfma_f32_16x16x32_bf16 v[82:85], v[248:251], v[188:191], v[82:85]
	v_mfma_f32_16x16x32_bf16 v[78:81], v[240:243], v[196:199], v[78:81]
	v_mfma_f32_16x16x32_bf16 v[74:77], v[248:251], v[196:199], v[74:77]
	v_mfma_f32_16x16x32_bf16 v[70:73], v[240:243], v[232:235], v[70:73]
	v_mfma_f32_16x16x32_bf16 v[66:69], v[248:251], v[232:235], v[66:69]
	v_mfma_f32_16x16x32_bf16 v[94:97], v[244:247], v[184:187], v[94:97]
	v_mfma_f32_16x16x32_bf16 v[90:93], v[222:225], v[184:187], v[90:93]
	v_mfma_f32_16x16x32_bf16 v[86:89], v[244:247], v[192:195], v[86:89]
	v_mfma_f32_16x16x32_bf16 v[82:85], v[222:225], v[192:195], v[82:85]
	v_mfma_f32_16x16x32_bf16 v[78:81], v[244:247], v[200:203], v[78:81]
	v_mfma_f32_16x16x32_bf16 v[74:77], v[222:225], v[200:203], v[74:77]
	v_mfma_f32_16x16x32_bf16 v[70:73], v[244:247], v[236:239], v[70:73]
	v_mfma_f32_16x16x32_bf16 v[66:69], v[222:225], v[236:239], v[66:69]
	s_setprio 0
	v_readfirstlane_b32 s1, v147
	v_lshl_add_u64 v[218:219], v[204:205], 0, s[74:75]
	s_mov_b32 m0, s1
	v_readfirstlane_b32 s1, v148
	s_barrier
	ds_read_b128 v[180:183], v0 offset:16384
	ds_read_b128 v[184:187], v0 offset:17408
	ds_read_b128 v[188:191], v0 offset:18432
	ds_read_b128 v[192:195], v0 offset:19456
	ds_read_b128 v[196:199], v0 offset:20480
	ds_read_b128 v[200:203], v0 offset:21504
	ds_read_b128 v[232:235], v0 offset:22528
	ds_read_b128 v[236:239], v0 offset:23552
	global_load_lds_dwordx4 v[218:219], off
	v_lshl_add_u64 v[218:219], v[216:217], 0, s[74:75]
	s_mov_b32 m0, s1
	s_nop 0
	global_load_lds_dwordx4 v[218:219], off
	s_barrier
	s_waitcnt lgkmcnt(0)
	s_setprio 1
	s_waitcnt lgkmcnt(0)
	v_mfma_f32_16x16x32_bf16 v[62:65], v[164:167], v[180:183], v[62:65]
	v_mfma_f32_16x16x32_bf16 v[58:61], v[172:175], v[180:183], v[58:61]
	v_mfma_f32_16x16x32_bf16 v[54:57], v[164:167], v[188:191], v[54:57]
	v_mfma_f32_16x16x32_bf16 v[50:53], v[172:175], v[188:191], v[50:53]
	v_mfma_f32_16x16x32_bf16 v[46:49], v[164:167], v[196:199], v[46:49]
	v_mfma_f32_16x16x32_bf16 v[42:45], v[172:175], v[196:199], v[42:45]
	v_mfma_f32_16x16x32_bf16 v[38:41], v[164:167], v[232:235], v[38:41]
	v_mfma_f32_16x16x32_bf16 v[34:37], v[172:175], v[232:235], v[34:37]
	v_mfma_f32_16x16x32_bf16 v[62:65], v[168:171], v[184:187], v[62:65]
	v_mfma_f32_16x16x32_bf16 v[58:61], v[176:179], v[184:187], v[58:61]
	v_mfma_f32_16x16x32_bf16 v[54:57], v[168:171], v[192:195], v[54:57]
	v_mfma_f32_16x16x32_bf16 v[50:53], v[176:179], v[192:195], v[50:53]
	v_mfma_f32_16x16x32_bf16 v[46:49], v[168:171], v[200:203], v[46:49]
	v_mfma_f32_16x16x32_bf16 v[42:45], v[176:179], v[200:203], v[42:45]
	v_mfma_f32_16x16x32_bf16 v[38:41], v[168:171], v[236:239], v[38:41]
	v_mfma_f32_16x16x32_bf16 v[34:37], v[176:179], v[236:239], v[34:37]
	s_setprio 0
	s_barrier
	v_readfirstlane_b32 s1, v152
	v_lshl_add_u64 v[164:165], v[210:211], 0, s[18:19]
	s_mov_b32 m0, s1
	v_readfirstlane_b32 s1, v153
	global_load_lds_dwordx4 v[164:165], off
	v_lshl_add_u64 v[164:165], v[228:229], 0, s[18:19]
	s_mov_b32 m0, s1
	s_nop 0
	global_load_lds_dwordx4 v[164:165], off
	s_waitcnt vmcnt(6)
	s_barrier
	s_setprio 1
	v_mfma_f32_16x16x32_bf16 v[30:33], v[240:243], v[180:183], v[30:33]
	v_mfma_f32_16x16x32_bf16 v[26:29], v[248:251], v[180:183], v[26:29]
	v_mfma_f32_16x16x32_bf16 v[22:25], v[240:243], v[188:191], v[22:25]
	v_mfma_f32_16x16x32_bf16 v[18:21], v[248:251], v[188:191], v[18:21]
	v_mfma_f32_16x16x32_bf16 v[14:17], v[240:243], v[196:199], v[14:17]
	v_mfma_f32_16x16x32_bf16 v[10:13], v[248:251], v[196:199], v[10:13]
	v_mfma_f32_16x16x32_bf16 v[6:9], v[240:243], v[232:235], v[6:9]
	v_mfma_f32_16x16x32_bf16 v[2:5], v[248:251], v[232:235], v[2:5]
	v_mfma_f32_16x16x32_bf16 v[30:33], v[244:247], v[184:187], v[30:33]
	v_mfma_f32_16x16x32_bf16 v[26:29], v[222:225], v[184:187], v[26:29]
	v_mfma_f32_16x16x32_bf16 v[22:25], v[244:247], v[192:195], v[22:25]
	v_mfma_f32_16x16x32_bf16 v[18:21], v[222:225], v[192:195], v[18:21]
	v_mfma_f32_16x16x32_bf16 v[14:17], v[244:247], v[200:203], v[14:17]
	v_mfma_f32_16x16x32_bf16 v[10:13], v[222:225], v[200:203], v[10:13]
	v_mfma_f32_16x16x32_bf16 v[6:9], v[244:247], v[236:239], v[6:9]
	v_mfma_f32_16x16x32_bf16 v[2:5], v[222:225], v[236:239], v[2:5]
	s_setprio 0
	s_barrier
	ds_read_b128 v[164:167], v151 offset:32768
	ds_read_b128 v[168:171], v151 offset:33792
	ds_read_b128 v[172:175], v151 offset:34816
	ds_read_b128 v[176:179], v151 offset:35840
	v_readfirstlane_b32 s1, v154
	v_lshl_add_u64 v[218:219], v[204:205], 0, s[18:19]
	s_mov_b32 m0, s1
	v_readfirstlane_b32 s1, v155
	ds_read_b128 v[180:183], v0 offset:32768
	ds_read_b128 v[184:187], v0 offset:33792
	ds_read_b128 v[188:191], v0 offset:34816
	ds_read_b128 v[192:195], v0 offset:35840
	ds_read_b128 v[196:199], v0 offset:36864
	ds_read_b128 v[200:203], v0 offset:37888
	ds_read_b128 v[222:225], v0 offset:38912
	ds_read_b128 v[232:235], v0 offset:39936
	global_load_lds_dwordx4 v[218:219], off
	v_lshl_add_u64 v[218:219], v[216:217], 0, s[18:19]
	s_mov_b32 m0, s1
	s_nop 0
	global_load_lds_dwordx4 v[218:219], off
	s_waitcnt lgkmcnt(8)
	s_barrier
	s_waitcnt lgkmcnt(0)
	s_setprio 1
	s_waitcnt lgkmcnt(0)
	v_mfma_f32_16x16x32_bf16 v[126:129], v[164:167], v[180:183], v[126:129]
	v_mfma_f32_16x16x32_bf16 v[122:125], v[172:175], v[180:183], v[122:125]
	v_mfma_f32_16x16x32_bf16 v[118:121], v[164:167], v[188:191], v[118:121]
	v_mfma_f32_16x16x32_bf16 v[114:117], v[172:175], v[188:191], v[114:117]
	v_mfma_f32_16x16x32_bf16 v[110:113], v[164:167], v[196:199], v[110:113]
	v_mfma_f32_16x16x32_bf16 v[106:109], v[172:175], v[196:199], v[106:109]
	v_mfma_f32_16x16x32_bf16 v[102:105], v[164:167], v[222:225], v[102:105]
	v_mfma_f32_16x16x32_bf16 v[98:101], v[172:175], v[222:225], v[98:101]
	v_mfma_f32_16x16x32_bf16 v[126:129], v[168:171], v[184:187], v[126:129]
	v_mfma_f32_16x16x32_bf16 v[122:125], v[176:179], v[184:187], v[122:125]
	v_mfma_f32_16x16x32_bf16 v[118:121], v[168:171], v[192:195], v[118:121]
	v_mfma_f32_16x16x32_bf16 v[114:117], v[176:179], v[192:195], v[114:117]
	v_mfma_f32_16x16x32_bf16 v[110:113], v[168:171], v[200:203], v[110:113]
	v_mfma_f32_16x16x32_bf16 v[106:109], v[176:179], v[200:203], v[106:109]
	v_mfma_f32_16x16x32_bf16 v[102:105], v[168:171], v[232:235], v[102:105]
	v_mfma_f32_16x16x32_bf16 v[98:101], v[176:179], v[232:235], v[98:101]
	s_setprio 0
	s_barrier
	v_readfirstlane_b32 s1, v156
	v_lshl_add_u64 v[218:219], v[210:211], 0, s[28:29]
	s_mov_b32 m0, s1
	v_readfirstlane_b32 s1, v157
	ds_read_b128 v[236:239], v151 offset:49152
	ds_read_b128 v[240:243], v151 offset:50176
	ds_read_b128 v[244:247], v151 offset:51200
	ds_read_b128 v[248:251], v151 offset:52224
	global_load_lds_dwordx4 v[218:219], off
	v_lshl_add_u64 v[218:219], v[228:229], 0, s[28:29]
	s_mov_b32 m0, s1
	s_nop 0
	global_load_lds_dwordx4 v[218:219], off
	s_barrier
	s_waitcnt lgkmcnt(0)
	s_setprio 1
	s_waitcnt lgkmcnt(0)
	v_mfma_f32_16x16x32_bf16 v[94:97], v[236:239], v[180:183], v[94:97]
	v_mfma_f32_16x16x32_bf16 v[90:93], v[244:247], v[180:183], v[90:93]
	v_mfma_f32_16x16x32_bf16 v[86:89], v[236:239], v[188:191], v[86:89]
	v_mfma_f32_16x16x32_bf16 v[82:85], v[244:247], v[188:191], v[82:85]
	v_mfma_f32_16x16x32_bf16 v[78:81], v[236:239], v[196:199], v[78:81]
	v_mfma_f32_16x16x32_bf16 v[74:77], v[244:247], v[196:199], v[74:77]
	v_mfma_f32_16x16x32_bf16 v[70:73], v[236:239], v[222:225], v[70:73]
	v_mfma_f32_16x16x32_bf16 v[66:69], v[244:247], v[222:225], v[66:69]
	v_mfma_f32_16x16x32_bf16 v[94:97], v[240:243], v[184:187], v[94:97]
	v_mfma_f32_16x16x32_bf16 v[90:93], v[248:251], v[184:187], v[90:93]
	v_mfma_f32_16x16x32_bf16 v[86:89], v[240:243], v[192:195], v[86:89]
	v_mfma_f32_16x16x32_bf16 v[82:85], v[248:251], v[192:195], v[82:85]
	v_mfma_f32_16x16x32_bf16 v[78:81], v[240:243], v[200:203], v[78:81]
	v_mfma_f32_16x16x32_bf16 v[74:77], v[248:251], v[200:203], v[74:77]
	v_mfma_f32_16x16x32_bf16 v[70:73], v[240:243], v[232:235], v[70:73]
	v_mfma_f32_16x16x32_bf16 v[66:69], v[248:251], v[232:235], v[66:69]
	s_setprio 0
	v_readfirstlane_b32 s1, v158
	v_lshl_add_u64 v[204:205], v[204:205], 0, s[28:29]
	s_mov_b32 m0, s1
	v_readfirstlane_b32 s1, v159
	s_barrier
	ds_read_b128 v[180:183], v0 offset:49152
	ds_read_b128 v[184:187], v0 offset:50176
	ds_read_b128 v[188:191], v0 offset:51200
	ds_read_b128 v[192:195], v0 offset:52224
	ds_read_b128 v[196:199], v0 offset:53248
	ds_read_b128 v[200:203], v0 offset:54272
	ds_read_b128 v[222:225], v0 offset:55296
	ds_read_b128 v[232:235], v0 offset:56320
	global_load_lds_dwordx4 v[204:205], off
	v_lshl_add_u64 v[204:205], v[216:217], 0, s[28:29]
	s_mov_b32 m0, s1
	s_nop 0
	global_load_lds_dwordx4 v[204:205], off
	s_barrier
	s_waitcnt lgkmcnt(0)
	s_setprio 1
	s_waitcnt lgkmcnt(0)
	v_mfma_f32_16x16x32_bf16 v[62:65], v[164:167], v[180:183], v[62:65]
	v_mfma_f32_16x16x32_bf16 v[58:61], v[172:175], v[180:183], v[58:61]
	v_mfma_f32_16x16x32_bf16 v[54:57], v[164:167], v[188:191], v[54:57]
	v_mfma_f32_16x16x32_bf16 v[50:53], v[172:175], v[188:191], v[50:53]
	v_mfma_f32_16x16x32_bf16 v[46:49], v[164:167], v[196:199], v[46:49]
	v_mfma_f32_16x16x32_bf16 v[42:45], v[172:175], v[196:199], v[42:45]
	v_mfma_f32_16x16x32_bf16 v[38:41], v[164:167], v[222:225], v[38:41]
	v_mfma_f32_16x16x32_bf16 v[34:37], v[172:175], v[222:225], v[34:37]
	v_mfma_f32_16x16x32_bf16 v[62:65], v[168:171], v[184:187], v[62:65]
	v_mfma_f32_16x16x32_bf16 v[58:61], v[176:179], v[184:187], v[58:61]
	v_mfma_f32_16x16x32_bf16 v[54:57], v[168:171], v[192:195], v[54:57]
	v_mfma_f32_16x16x32_bf16 v[50:53], v[176:179], v[192:195], v[50:53]
	v_mfma_f32_16x16x32_bf16 v[46:49], v[168:171], v[200:203], v[46:49]
	v_mfma_f32_16x16x32_bf16 v[42:45], v[176:179], v[200:203], v[42:45]
	v_mfma_f32_16x16x32_bf16 v[38:41], v[168:171], v[232:235], v[38:41]
	v_mfma_f32_16x16x32_bf16 v[34:37], v[176:179], v[232:235], v[34:37]
	s_setprio 0
	s_barrier
	v_readfirstlane_b32 s1, v160
	v_lshl_add_u64 v[164:165], v[210:211], 0, s[30:31]
	s_mov_b32 m0, s1
	v_readfirstlane_b32 s1, v161
	global_load_lds_dwordx4 v[164:165], off
	v_lshl_add_u64 v[164:165], v[228:229], 0, s[30:31]
	s_mov_b32 m0, s1
	s_nop 0
	global_load_lds_dwordx4 v[164:165], off
	s_waitcnt vmcnt(6)
	s_barrier
	s_setprio 1
	v_mfma_f32_16x16x32_bf16 v[30:33], v[236:239], v[180:183], v[30:33]
	v_mfma_f32_16x16x32_bf16 v[26:29], v[244:247], v[180:183], v[26:29]
	v_mfma_f32_16x16x32_bf16 v[22:25], v[236:239], v[188:191], v[22:25]
	v_mfma_f32_16x16x32_bf16 v[18:21], v[244:247], v[188:191], v[18:21]
	v_mfma_f32_16x16x32_bf16 v[14:17], v[236:239], v[196:199], v[14:17]
	v_mfma_f32_16x16x32_bf16 v[10:13], v[244:247], v[196:199], v[10:13]
	v_mfma_f32_16x16x32_bf16 v[6:9], v[236:239], v[222:225], v[6:9]
	v_mfma_f32_16x16x32_bf16 v[2:5], v[244:247], v[222:225], v[2:5]
	v_mfma_f32_16x16x32_bf16 v[30:33], v[240:243], v[184:187], v[30:33]
	v_mfma_f32_16x16x32_bf16 v[26:29], v[248:251], v[184:187], v[26:29]
	v_mfma_f32_16x16x32_bf16 v[22:25], v[240:243], v[192:195], v[22:25]
	v_mfma_f32_16x16x32_bf16 v[18:21], v[248:251], v[192:195], v[18:21]
	v_mfma_f32_16x16x32_bf16 v[14:17], v[240:243], v[200:203], v[14:17]
	v_mfma_f32_16x16x32_bf16 v[10:13], v[248:251], v[200:203], v[10:13]
	v_mfma_f32_16x16x32_bf16 v[6:9], v[240:243], v[232:235], v[6:9]
	v_mfma_f32_16x16x32_bf16 v[2:5], v[248:251], v[232:235], v[2:5]
	s_setprio 0
	s_add_i32 s0, s0, 2
	s_add_u32 s8, s8, 0x100
	s_addc_u32 s9, s9, 0
	s_cmp_lt_u32 s0, 28
	s_barrier
	s_cbranch_scc1 .LBB0_678
	s_mov_b64 s[8:9], 0xf80
	v_readfirstlane_b32 s0, v162
	v_lshl_add_u64 v[132:133], v[132:133], 0, s[8:9]
	s_mov_b32 m0, s0
	v_readfirstlane_b32 s0, v163
	s_waitcnt vmcnt(0)
	ds_read_b128 v[134:137], v151
	ds_read_b128 v[138:141], v151 offset:1024
	ds_read_b128 v[152:155], v151 offset:2048
	ds_read_b128 v[156:159], v151 offset:3072
	ds_read_b128 v[164:167], v0
	ds_read_b128 v[168:171], v0 offset:1024
	ds_read_b128 v[172:175], v0 offset:2048
	ds_read_b128 v[176:179], v0 offset:3072
	ds_read_b128 v[180:183], v0 offset:4096
	ds_read_b128 v[184:187], v0 offset:5120
	ds_read_b128 v[188:191], v0 offset:6144
	ds_read_b128 v[192:195], v0 offset:7168
	global_load_lds_dwordx4 v[132:133], off
	v_lshl_add_u64 v[130:131], v[130:131], 0, s[8:9]
	s_mov_b32 m0, s0
	s_nop 0
	global_load_lds_dwordx4 v[130:131], off
	s_barrier
	s_waitcnt lgkmcnt(0)
	s_setprio 1
	s_waitcnt lgkmcnt(0)
	v_mfma_f32_16x16x32_bf16 v[126:129], v[134:137], v[164:167], v[126:129]
	v_mfma_f32_16x16x32_bf16 v[122:125], v[152:155], v[164:167], v[122:125]
	v_mfma_f32_16x16x32_bf16 v[114:117], v[152:155], v[172:175], v[114:117]
	v_mfma_f32_16x16x32_bf16 v[106:109], v[152:155], v[180:183], v[106:109]
	v_mfma_f32_16x16x32_bf16 v[98:101], v[152:155], v[188:191], v[98:101]
	v_mfma_f32_16x16x32_bf16 v[126:129], v[138:141], v[168:171], v[126:129]
	v_mfma_f32_16x16x32_bf16 v[122:125], v[156:159], v[168:171], v[122:125]
	v_mfma_f32_16x16x32_bf16 v[118:121], v[134:137], v[172:175], v[118:121]
	v_mfma_f32_16x16x32_bf16 v[114:117], v[156:159], v[176:179], v[114:117]
	v_mfma_f32_16x16x32_bf16 v[110:113], v[134:137], v[180:183], v[110:113]
	v_mfma_f32_16x16x32_bf16 v[106:109], v[156:159], v[184:187], v[106:109]
	v_mfma_f32_16x16x32_bf16 v[102:105], v[134:137], v[188:191], v[102:105]
	v_mfma_f32_16x16x32_bf16 v[98:101], v[156:159], v[192:195], v[98:101]
	v_mfma_f32_16x16x32_bf16 v[130:133], v[138:141], v[176:179], v[118:121]
	v_mfma_f32_16x16x32_bf16 v[160:163], v[138:141], v[184:187], v[110:113]
	v_mfma_f32_16x16x32_bf16 v[196:199], v[138:141], v[192:195], v[102:105]
	s_setprio 0
	s_barrier
	s_waitcnt vmcnt(0)
	s_nop 0
	ds_read_b128 v[102:105], v151 offset:16384
	ds_read_b128 v[110:113], v151 offset:17408
	ds_read_b128 v[118:121], v151 offset:18432
	ds_read_b128 v[200:203], v151 offset:19456
	s_barrier
	s_waitcnt lgkmcnt(0)
	s_setprio 1
	s_waitcnt lgkmcnt(1)
	v_mfma_f32_16x16x32_bf16 v[90:93], v[118:121], v[164:167], v[90:93]
	v_mfma_f32_16x16x32_bf16 v[86:89], v[102:105], v[172:175], v[86:89]
	v_mfma_f32_16x16x32_bf16 v[82:85], v[118:121], v[172:175], v[82:85]
	v_mfma_f32_16x16x32_bf16 v[78:81], v[102:105], v[180:183], v[78:81]
	v_mfma_f32_16x16x32_bf16 v[70:73], v[102:105], v[188:191], v[70:73]
	v_mfma_f32_16x16x32_bf16 v[94:97], v[102:105], v[164:167], v[94:97]
	s_waitcnt lgkmcnt(0)
	v_mfma_f32_16x16x32_bf16 v[90:93], v[200:203], v[168:171], v[90:93]
	v_mfma_f32_16x16x32_bf16 v[86:89], v[110:113], v[176:179], v[86:89]
	v_mfma_f32_16x16x32_bf16 v[82:85], v[200:203], v[176:179], v[82:85]
	v_mfma_f32_16x16x32_bf16 v[78:81], v[110:113], v[184:187], v[78:81]
	v_mfma_f32_16x16x32_bf16 v[74:77], v[118:121], v[180:183], v[74:77]
	v_mfma_f32_16x16x32_bf16 v[70:73], v[110:113], v[192:195], v[70:73]
	v_mfma_f32_16x16x32_bf16 v[66:69], v[118:121], v[188:191], v[66:69]
	v_mfma_f32_16x16x32_bf16 v[222:225], v[110:113], v[168:171], v[94:97]
	v_mfma_f32_16x16x32_bf16 v[164:167], v[200:203], v[184:187], v[74:77]
	v_mfma_f32_16x16x32_bf16 v[168:171], v[200:203], v[192:195], v[66:69]
	s_setprio 0
	s_barrier
	s_nop 2
	ds_read_b128 v[66:69], v0 offset:16384
	ds_read_b128 v[74:77], v0 offset:17408
	ds_read_b128 v[94:97], v0 offset:18432
	ds_read_b128 v[172:175], v0 offset:19456
	ds_read_b128 v[176:179], v0 offset:20480
	ds_read_b128 v[180:183], v0 offset:21504
	ds_read_b128 v[184:187], v0 offset:22528
	ds_read_b128 v[188:191], v0 offset:23552
	s_waitcnt vmcnt(4)
	s_barrier
	s_waitcnt lgkmcnt(0)
	s_setprio 1
	s_waitcnt lgkmcnt(5)
	v_mfma_f32_16x16x32_bf16 v[54:57], v[134:137], v[94:97], v[54:57]
	v_mfma_f32_16x16x32_bf16 v[50:53], v[152:155], v[94:97], v[50:53]
	v_mfma_f32_16x16x32_bf16 v[62:65], v[134:137], v[66:69], v[62:65]
	v_mfma_f32_16x16x32_bf16 v[58:61], v[152:155], v[66:69], v[58:61]
	s_waitcnt lgkmcnt(4)
	v_mfma_f32_16x16x32_bf16 v[54:57], v[138:141], v[172:175], v[54:57]
	v_mfma_f32_16x16x32_bf16 v[50:53], v[156:159], v[172:175], v[50:53]
	s_waitcnt lgkmcnt(3)
	v_mfma_f32_16x16x32_bf16 v[46:49], v[134:137], v[176:179], v[46:49]
	v_mfma_f32_16x16x32_bf16 v[42:45], v[152:155], v[176:179], v[42:45]
	s_waitcnt lgkmcnt(1)
	v_mfma_f32_16x16x32_bf16 v[38:41], v[134:137], v[184:187], v[38:41]
	v_mfma_f32_16x16x32_bf16 v[34:37], v[152:155], v[184:187], v[34:37]
	v_mfma_f32_16x16x32_bf16 v[192:195], v[138:141], v[74:77], v[62:65]
	v_mfma_f32_16x16x32_bf16 v[232:235], v[156:159], v[74:77], v[58:61]
	v_mfma_f32_16x16x32_bf16 v[236:239], v[138:141], v[180:183], v[46:49]
	v_mfma_f32_16x16x32_bf16 v[240:243], v[156:159], v[180:183], v[42:45]
	s_waitcnt lgkmcnt(0)
	v_mfma_f32_16x16x32_bf16 v[134:137], v[138:141], v[188:191], v[38:41]
	v_mfma_f32_16x16x32_bf16 v[138:141], v[156:159], v[188:191], v[34:37]
	s_setprio 0
	s_setprio 1
	v_mfma_f32_16x16x32_bf16 v[30:33], v[102:105], v[66:69], v[30:33]
	v_mfma_f32_16x16x32_bf16 v[26:29], v[118:121], v[66:69], v[26:29]
	v_mfma_f32_16x16x32_bf16 v[14:17], v[102:105], v[176:179], v[14:17]
	v_mfma_f32_16x16x32_bf16 v[10:13], v[118:121], v[176:179], v[10:13]
	v_mfma_f32_16x16x32_bf16 v[30:33], v[110:113], v[74:77], v[30:33]
	v_mfma_f32_16x16x32_bf16 v[26:29], v[200:203], v[74:77], v[26:29]
	v_mfma_f32_16x16x32_bf16 v[22:25], v[102:105], v[94:97], v[22:25]
	v_mfma_f32_16x16x32_bf16 v[18:21], v[118:121], v[94:97], v[18:21]
	v_mfma_f32_16x16x32_bf16 v[14:17], v[110:113], v[180:183], v[14:17]
	v_mfma_f32_16x16x32_bf16 v[10:13], v[200:203], v[180:183], v[10:13]
	v_mfma_f32_16x16x32_bf16 v[6:9], v[102:105], v[184:187], v[6:9]
	v_mfma_f32_16x16x32_bf16 v[2:5], v[118:121], v[184:187], v[2:5]
	v_mfma_f32_16x16x32_bf16 v[152:155], v[110:113], v[172:175], v[22:25]
	v_mfma_f32_16x16x32_bf16 v[156:159], v[200:203], v[172:175], v[18:21]
	v_mfma_f32_16x16x32_bf16 v[172:175], v[110:113], v[188:191], v[6:9]
	v_mfma_f32_16x16x32_bf16 v[176:179], v[200:203], v[188:191], v[2:5]
	s_setprio 0
	s_barrier
	s_nop 1
	ds_read_b128 v[2:5], v151 offset:32768
	ds_read_b128 v[6:9], v151 offset:33792
	ds_read_b128 v[180:183], v151 offset:34816
	ds_read_b128 v[184:187], v151 offset:35840
	ds_read_b128 v[18:21], v0 offset:32768
	ds_read_b128 v[22:25], v0 offset:33792
	ds_read_b128 v[38:41], v0 offset:34816
	ds_read_b128 v[46:49], v0 offset:35840
	ds_read_b128 v[58:61], v0 offset:36864
	ds_read_b128 v[66:69], v0 offset:37888
	ds_read_b128 v[188:191], v0 offset:38912
	ds_read_b128 v[200:203], v0 offset:39936
	s_waitcnt vmcnt(2)
	s_barrier
	s_waitcnt lgkmcnt(0)
	s_setprio 1
	s_waitcnt lgkmcnt(7)
	v_mfma_f32_16x16x32_bf16 v[34:37], v[2:5], v[18:21], v[126:129]
	s_waitcnt lgkmcnt(6)
	v_mfma_f32_16x16x32_bf16 v[118:121], v[6:9], v[22:25], v[34:37]
	v_mfma_f32_16x16x32_bf16 v[34:37], v[180:183], v[18:21], v[122:125]
	v_mfma_f32_16x16x32_bf16 v[110:113], v[184:187], v[22:25], v[34:37]
	s_waitcnt lgkmcnt(5)
	v_mfma_f32_16x16x32_bf16 v[34:37], v[2:5], v[38:41], v[130:133]
	s_waitcnt lgkmcnt(4)
	v_mfma_f32_16x16x32_bf16 v[102:105], v[6:9], v[46:49], v[34:37]
	v_mfma_f32_16x16x32_bf16 v[34:37], v[180:183], v[38:41], v[114:117]
	v_mfma_f32_16x16x32_bf16 v[94:97], v[184:187], v[46:49], v[34:37]
	s_waitcnt lgkmcnt(3)
	v_mfma_f32_16x16x32_bf16 v[34:37], v[2:5], v[58:61], v[160:163]
	s_waitcnt lgkmcnt(2)
	v_mfma_f32_16x16x32_bf16 v[74:77], v[6:9], v[66:69], v[34:37]
	v_mfma_f32_16x16x32_bf16 v[34:37], v[180:183], v[58:61], v[106:109]
	v_mfma_f32_16x16x32_bf16 v[62:65], v[184:187], v[66:69], v[34:37]
	s_waitcnt lgkmcnt(1)
	v_mfma_f32_16x16x32_bf16 v[34:37], v[2:5], v[188:191], v[196:199]
	s_waitcnt lgkmcnt(0)
	v_mfma_f32_16x16x32_bf16 v[42:45], v[6:9], v[200:203], v[34:37]
	v_mfma_f32_16x16x32_bf16 v[34:37], v[180:183], v[188:191], v[98:101]
	v_mfma_f32_16x16x32_bf16 v[34:37], v[184:187], v[200:203], v[34:37]
	s_setprio 0
	s_barrier
	ds_read_b128 v[130:133], v151 offset:49152
	ds_read_b128 v[160:163], v151 offset:50176
	ds_read_b128 v[196:199], v151 offset:51200
	ds_read_b128 v[148:151], v151 offset:52224
	s_waitcnt vmcnt(0)
	s_barrier
	s_waitcnt lgkmcnt(0)
	s_setprio 1
	s_waitcnt lgkmcnt(3)
	v_mfma_f32_16x16x32_bf16 v[98:101], v[130:133], v[18:21], v[222:225]
	s_waitcnt lgkmcnt(1)
	v_mfma_f32_16x16x32_bf16 v[18:21], v[196:199], v[18:21], v[90:93]
	s_waitcnt lgkmcnt(0)
	v_mfma_f32_16x16x32_bf16 v[122:125], v[148:151], v[22:25], v[18:21]
	v_mfma_f32_16x16x32_bf16 v[18:21], v[130:133], v[38:41], v[86:89]
	v_mfma_f32_16x16x32_bf16 v[114:117], v[160:163], v[46:49], v[18:21]
	v_mfma_f32_16x16x32_bf16 v[18:21], v[196:199], v[38:41], v[82:85]
	v_mfma_f32_16x16x32_bf16 v[106:109], v[148:151], v[46:49], v[18:21]
	v_mfma_f32_16x16x32_bf16 v[18:21], v[130:133], v[58:61], v[78:81]
	v_mfma_f32_16x16x32_bf16 v[126:129], v[160:163], v[22:25], v[98:101]
	v_mfma_f32_16x16x32_bf16 v[98:101], v[160:163], v[66:69], v[18:21]
	v_mfma_f32_16x16x32_bf16 v[18:21], v[196:199], v[58:61], v[164:167]
	v_mfma_f32_16x16x32_bf16 v[90:93], v[148:151], v[66:69], v[18:21]
	v_mfma_f32_16x16x32_bf16 v[18:21], v[130:133], v[188:191], v[70:73]
	v_mfma_f32_16x16x32_bf16 v[66:69], v[160:163], v[200:203], v[18:21]
	v_mfma_f32_16x16x32_bf16 v[18:21], v[196:199], v[188:191], v[168:171]
	v_mfma_f32_16x16x32_bf16 v[58:61], v[148:151], v[200:203], v[18:21]
	s_setprio 0
	s_barrier
	ds_read_b128 v[82:85], v0 offset:49152
	ds_read_b128 v[164:167], v0 offset:50176
	ds_read_b128 v[168:171], v0 offset:51200
	ds_read_b128 v[188:191], v0 offset:52224
	ds_read_b128 v[200:203], v0 offset:53248
	ds_read_b128 v[222:225], v0 offset:54272
	ds_read_b128 v[244:247], v0 offset:55296
	ds_read_b128 v[248:251], v0 offset:56320
	s_barrier
	s_waitcnt lgkmcnt(0)
	s_setprio 1
	s_waitcnt lgkmcnt(7)
	v_mfma_f32_16x16x32_bf16 v[18:21], v[2:5], v[82:85], v[192:195]
	s_waitcnt lgkmcnt(6)
	v_mfma_f32_16x16x32_bf16 v[78:81], v[6:9], v[164:167], v[18:21]
	v_mfma_f32_16x16x32_bf16 v[18:21], v[180:183], v[82:85], v[232:235]
	v_mfma_f32_16x16x32_bf16 v[70:73], v[184:187], v[164:167], v[18:21]
	s_waitcnt lgkmcnt(5)
	v_mfma_f32_16x16x32_bf16 v[18:21], v[2:5], v[168:171], v[54:57]
	s_waitcnt lgkmcnt(4)
	v_mfma_f32_16x16x32_bf16 v[46:49], v[6:9], v[188:191], v[18:21]
	v_mfma_f32_16x16x32_bf16 v[18:21], v[180:183], v[168:171], v[50:53]
	v_mfma_f32_16x16x32_bf16 v[38:41], v[184:187], v[188:191], v[18:21]
	s_waitcnt lgkmcnt(3)
	v_mfma_f32_16x16x32_bf16 v[18:21], v[2:5], v[200:203], v[236:239]
	s_waitcnt lgkmcnt(1)
	v_mfma_f32_16x16x32_bf16 v[2:5], v[2:5], v[244:247], v[134:137]
	v_mfma_f32_16x16x32_bf16 v[22:25], v[6:9], v[222:225], v[18:21]
	v_mfma_f32_16x16x32_bf16 v[18:21], v[180:183], v[200:203], v[240:243]
	s_waitcnt lgkmcnt(0)
	v_mfma_f32_16x16x32_bf16 v[6:9], v[6:9], v[248:251], v[2:5]
	v_mfma_f32_16x16x32_bf16 v[2:5], v[180:183], v[244:247], v[138:141]
	v_mfma_f32_16x16x32_bf16 v[18:21], v[184:187], v[222:225], v[18:21]
	v_mfma_f32_16x16x32_bf16 v[2:5], v[184:187], v[248:251], v[2:5]
	s_setprio 0
	s_setprio 1
	v_mfma_f32_16x16x32_bf16 v[26:29], v[196:199], v[82:85], v[26:29]
	v_mfma_f32_16x16x32_bf16 v[30:33], v[130:133], v[82:85], v[30:33]
	v_mfma_f32_16x16x32_bf16 v[82:85], v[148:151], v[164:167], v[26:29]
	v_mfma_f32_16x16x32_bf16 v[26:29], v[130:133], v[168:171], v[152:155]
	v_mfma_f32_16x16x32_bf16 v[54:57], v[160:163], v[188:191], v[26:29]
	v_mfma_f32_16x16x32_bf16 v[26:29], v[196:199], v[168:171], v[156:159]
	v_mfma_f32_16x16x32_bf16 v[10:13], v[196:199], v[200:203], v[10:13]
	v_mfma_f32_16x16x32_bf16 v[50:53], v[148:151], v[188:191], v[26:29]
	v_mfma_f32_16x16x32_bf16 v[14:17], v[130:133], v[200:203], v[14:17]
	v_mfma_f32_16x16x32_bf16 v[26:29], v[148:151], v[222:225], v[10:13]
	v_mfma_f32_16x16x32_bf16 v[10:13], v[130:133], v[244:247], v[172:175]
	v_mfma_f32_16x16x32_bf16 v[86:89], v[160:163], v[164:167], v[30:33]
	v_mfma_f32_16x16x32_bf16 v[30:33], v[160:163], v[222:225], v[14:17]
	v_mfma_f32_16x16x32_bf16 v[14:17], v[160:163], v[248:251], v[10:13]
	v_mfma_f32_16x16x32_bf16 v[10:13], v[196:199], v[244:247], v[176:179]
	v_mfma_f32_16x16x32_bf16 v[10:13], v[148:151], v[248:251], v[10:13]
	s_setprio 0
	s_movk_i32 s0, 0x100
	v_cmp_gt_u32_e32 vcc, s0, v142
	s_barrier
	s_and_saveexec_b64 s[0:1], vcc
	s_cbranch_execz .LBB0_674
	s_barrier
	s_branch .LBB0_674

.LBB0_689:
	ds_read_b128 v[104:107], v95
	ds_read_b128 v[108:111], v95 offset:1024
	ds_read_b128 v[112:115], v95 offset:2048
	ds_read_b128 v[116:119], v95 offset:3072
	v_add_u32_e32 v101, 0xc000, v85
	v_lshl_add_u64 v[152:153], v[72:73], 0, s[10:11]
	v_readfirstlane_b32 s1, v101
	v_lshl_add_u64 v[102:103], v[152:153], 0, s[34:35]
	s_mov_b32 m0, s1
	ds_read_b128 v[120:123], v93
	ds_read_b128 v[124:127], v93 offset:1024
	ds_read_b128 v[128:131], v93 offset:2048
	ds_read_b128 v[132:135], v93 offset:3072
	ds_read_b128 v[136:139], v93 offset:4096
	ds_read_b128 v[140:143], v93 offset:5120
	ds_read_b128 v[144:147], v93 offset:6144
	ds_read_b128 v[148:151], v93 offset:7168
	global_load_lds_dwordx4 v[102:103], off
	v_add_u32_e32 v102, 0xe000, v85
	v_lshl_add_u64 v[154:155], v[74:75], 0, s[10:11]
	v_readfirstlane_b32 s1, v102
	v_lshl_add_u64 v[156:157], v[154:155], 0, s[34:35]
	s_mov_b32 m0, s1
	s_nop 0
	global_load_lds_dwordx4 v[156:157], off
	s_waitcnt lgkmcnt(8)
	s_barrier
	s_waitcnt lgkmcnt(0)
	s_setprio 1
	s_waitcnt lgkmcnt(0)
	v_mfma_f32_16x16x32_bf16 v[62:65], v[104:107], v[120:123], v[62:65]
	v_mfma_f32_16x16x32_bf16 v[58:61], v[112:115], v[120:123], v[58:61]
	v_mfma_f32_16x16x32_bf16 v[54:57], v[104:107], v[128:131], v[54:57]
	v_mfma_f32_16x16x32_bf16 v[50:53], v[112:115], v[128:131], v[50:53]
	v_mfma_f32_16x16x32_bf16 v[46:49], v[104:107], v[136:139], v[46:49]
	v_mfma_f32_16x16x32_bf16 v[42:45], v[112:115], v[136:139], v[42:45]
	v_mfma_f32_16x16x32_bf16 v[38:41], v[104:107], v[144:147], v[38:41]
	v_mfma_f32_16x16x32_bf16 v[34:37], v[112:115], v[144:147], v[34:37]
	v_mfma_f32_16x16x32_bf16 v[62:65], v[108:111], v[124:127], v[62:65]
	v_mfma_f32_16x16x32_bf16 v[58:61], v[116:119], v[124:127], v[58:61]
	v_mfma_f32_16x16x32_bf16 v[54:57], v[108:111], v[132:135], v[54:57]
	v_mfma_f32_16x16x32_bf16 v[50:53], v[116:119], v[132:135], v[50:53]
	v_mfma_f32_16x16x32_bf16 v[46:49], v[108:111], v[140:143], v[46:49]
	v_mfma_f32_16x16x32_bf16 v[42:45], v[116:119], v[140:143], v[42:45]
	v_mfma_f32_16x16x32_bf16 v[38:41], v[108:111], v[148:151], v[38:41]
	v_mfma_f32_16x16x32_bf16 v[34:37], v[116:119], v[148:151], v[34:37]
	s_setprio 0
	s_barrier
	v_lshl_add_u64 v[156:157], v[68:69], 0, s[10:11]
	v_readfirstlane_b32 s1, v87
	v_lshl_add_u64 v[120:121], v[156:157], 0, s[74:75]
	s_mov_b32 m0, s1
	v_lshl_add_u64 v[158:159], v[70:71], 0, s[10:11]
	v_readfirstlane_b32 s1, v88
	global_load_lds_dwordx4 v[120:121], off
	v_lshl_add_u64 v[120:121], v[158:159], 0, s[74:75]
	s_mov_b32 m0, s1
	v_readfirstlane_b32 s1, v85
	global_load_lds_dwordx4 v[120:121], off
	v_lshl_add_u64 v[160:161], v[152:153], 0, s[74:75]
	s_mov_b32 m0, s1
	v_readfirstlane_b32 s1, v86
	s_barrier
	s_waitcnt lgkmcnt(0)
	s_barrier
	ds_read_b128 v[120:123], v93 offset:16384
	ds_read_b128 v[124:127], v93 offset:17408
	ds_read_b128 v[128:131], v93 offset:18432
	ds_read_b128 v[132:135], v93 offset:19456
	ds_read_b128 v[136:139], v93 offset:20480
	ds_read_b128 v[140:143], v93 offset:21504
	ds_read_b128 v[144:147], v93 offset:22528
	ds_read_b128 v[148:151], v93 offset:23552
	global_load_lds_dwordx4 v[160:161], off
	v_lshl_add_u64 v[160:161], v[154:155], 0, s[74:75]
	s_mov_b32 m0, s1
	s_nop 0
	global_load_lds_dwordx4 v[160:161], off
	s_barrier
	s_waitcnt lgkmcnt(0)
	s_setprio 1
	s_waitcnt lgkmcnt(0)
	v_mfma_f32_16x16x32_bf16 v[2:5], v[104:107], v[120:123], v[2:5]
	v_mfma_f32_16x16x32_bf16 v[6:9], v[112:115], v[120:123], v[6:9]
	v_mfma_f32_16x16x32_bf16 v[10:13], v[104:107], v[128:131], v[10:13]
	v_mfma_f32_16x16x32_bf16 v[14:17], v[112:115], v[128:131], v[14:17]
	v_mfma_f32_16x16x32_bf16 v[18:21], v[104:107], v[136:139], v[18:21]
	v_mfma_f32_16x16x32_bf16 v[22:25], v[112:115], v[136:139], v[22:25]
	v_mfma_f32_16x16x32_bf16 v[26:29], v[104:107], v[144:147], v[26:29]
	v_mfma_f32_16x16x32_bf16 v[30:33], v[112:115], v[144:147], v[30:33]
	v_mfma_f32_16x16x32_bf16 v[2:5], v[108:111], v[124:127], v[2:5]
	v_mfma_f32_16x16x32_bf16 v[6:9], v[116:119], v[124:127], v[6:9]
	v_mfma_f32_16x16x32_bf16 v[10:13], v[108:111], v[132:135], v[10:13]
	v_mfma_f32_16x16x32_bf16 v[14:17], v[116:119], v[132:135], v[14:17]
	v_mfma_f32_16x16x32_bf16 v[18:21], v[108:111], v[140:143], v[18:21]
	v_mfma_f32_16x16x32_bf16 v[22:25], v[116:119], v[140:143], v[22:25]
	v_mfma_f32_16x16x32_bf16 v[26:29], v[108:111], v[148:151], v[26:29]
	v_mfma_f32_16x16x32_bf16 v[30:33], v[116:119], v[148:151], v[30:33]
	s_setprio 0
	s_barrier
	v_lshl_add_u64 v[160:161], v[76:77], 0, s[10:11]
	v_readfirstlane_b32 s1, v89
	v_lshl_add_u64 v[104:105], v[160:161], 0, s[74:75]
	s_mov_b32 m0, s1
	v_lshl_add_u64 v[162:163], v[78:79], 0, s[10:11]
	v_readfirstlane_b32 s1, v90
	global_load_lds_dwordx4 v[104:105], off
	v_lshl_add_u64 v[104:105], v[162:163], 0, s[74:75]
	s_mov_b32 m0, s1
	s_nop 0
	global_load_lds_dwordx4 v[104:105], off
	s_waitcnt vmcnt(6)
	s_barrier
	s_barrier
	ds_read_b128 v[104:107], v95 offset:32768
	ds_read_b128 v[108:111], v95 offset:33792
	ds_read_b128 v[112:115], v95 offset:34816
	ds_read_b128 v[116:119], v95 offset:35840
	v_readfirstlane_b32 s1, v91
	v_lshl_add_u64 v[164:165], v[152:153], 0, s[78:79]
	s_mov_b32 m0, s1
	v_readfirstlane_b32 s1, v92
	ds_read_b128 v[120:123], v93 offset:32768
	ds_read_b128 v[124:127], v93 offset:33792
	ds_read_b128 v[128:131], v93 offset:34816
	ds_read_b128 v[132:135], v93 offset:35840
	ds_read_b128 v[136:139], v93 offset:36864
	ds_read_b128 v[140:143], v93 offset:37888
	ds_read_b128 v[144:147], v93 offset:38912
	ds_read_b128 v[148:151], v93 offset:39936
	global_load_lds_dwordx4 v[164:165], off
	v_lshl_add_u64 v[164:165], v[154:155], 0, s[78:79]
	s_mov_b32 m0, s1
	s_nop 0
	global_load_lds_dwordx4 v[164:165], off
	s_waitcnt lgkmcnt(8)
	s_barrier
	s_waitcnt lgkmcnt(0)
	s_setprio 1
	s_waitcnt lgkmcnt(0)
	v_mfma_f32_16x16x32_bf16 v[62:65], v[104:107], v[120:123], v[62:65]
	v_mfma_f32_16x16x32_bf16 v[58:61], v[112:115], v[120:123], v[58:61]
	v_mfma_f32_16x16x32_bf16 v[54:57], v[104:107], v[128:131], v[54:57]
	v_mfma_f32_16x16x32_bf16 v[50:53], v[112:115], v[128:131], v[50:53]
	v_mfma_f32_16x16x32_bf16 v[46:49], v[104:107], v[136:139], v[46:49]
	v_mfma_f32_16x16x32_bf16 v[42:45], v[112:115], v[136:139], v[42:45]
	v_mfma_f32_16x16x32_bf16 v[38:41], v[104:107], v[144:147], v[38:41]
	v_mfma_f32_16x16x32_bf16 v[34:37], v[112:115], v[144:147], v[34:37]
	v_mfma_f32_16x16x32_bf16 v[62:65], v[108:111], v[124:127], v[62:65]
	v_mfma_f32_16x16x32_bf16 v[58:61], v[116:119], v[124:127], v[58:61]
	v_mfma_f32_16x16x32_bf16 v[54:57], v[108:111], v[132:135], v[54:57]
	v_mfma_f32_16x16x32_bf16 v[50:53], v[116:119], v[132:135], v[50:53]
	v_mfma_f32_16x16x32_bf16 v[46:49], v[108:111], v[140:143], v[46:49]
	v_mfma_f32_16x16x32_bf16 v[42:45], v[116:119], v[140:143], v[42:45]
	v_mfma_f32_16x16x32_bf16 v[38:41], v[108:111], v[148:151], v[38:41]
	v_mfma_f32_16x16x32_bf16 v[34:37], v[116:119], v[148:151], v[34:37]
	s_setprio 0
	s_barrier
	v_readfirstlane_b32 s1, v94
	v_lshl_add_u64 v[120:121], v[156:157], 0, s[28:29]
	s_mov_b32 m0, s1
	v_readfirstlane_b32 s1, v96
	global_load_lds_dwordx4 v[120:121], off
	v_lshl_add_u64 v[120:121], v[158:159], 0, s[28:29]
	s_mov_b32 m0, s1
	v_readfirstlane_b32 s1, v97
	global_load_lds_dwordx4 v[120:121], off
	v_lshl_add_u64 v[152:153], v[152:153], 0, s[28:29]
	s_mov_b32 m0, s1
	v_readfirstlane_b32 s1, v98
	s_barrier
	s_waitcnt lgkmcnt(0)
	s_barrier
	ds_read_b128 v[120:123], v93 offset:49152
	ds_read_b128 v[124:127], v93 offset:50176
	ds_read_b128 v[128:131], v93 offset:51200
	ds_read_b128 v[132:135], v93 offset:52224
	ds_read_b128 v[136:139], v93 offset:53248
	ds_read_b128 v[140:143], v93 offset:54272
	ds_read_b128 v[144:147], v93 offset:55296
	ds_read_b128 v[148:151], v93 offset:56320
	global_load_lds_dwordx4 v[152:153], off
	v_lshl_add_u64 v[152:153], v[154:155], 0, s[28:29]
	s_mov_b32 m0, s1
	s_nop 0
	global_load_lds_dwordx4 v[152:153], off
	s_barrier
	s_waitcnt lgkmcnt(0)
	s_setprio 1
	s_waitcnt lgkmcnt(0)
	v_mfma_f32_16x16x32_bf16 v[2:5], v[104:107], v[120:123], v[2:5]
	v_mfma_f32_16x16x32_bf16 v[6:9], v[112:115], v[120:123], v[6:9]
	v_mfma_f32_16x16x32_bf16 v[10:13], v[104:107], v[128:131], v[10:13]
	v_mfma_f32_16x16x32_bf16 v[14:17], v[112:115], v[128:131], v[14:17]
	v_mfma_f32_16x16x32_bf16 v[18:21], v[104:107], v[136:139], v[18:21]
	v_mfma_f32_16x16x32_bf16 v[22:25], v[112:115], v[136:139], v[22:25]
	v_mfma_f32_16x16x32_bf16 v[26:29], v[104:107], v[144:147], v[26:29]
	v_mfma_f32_16x16x32_bf16 v[30:33], v[112:115], v[144:147], v[30:33]
	v_mfma_f32_16x16x32_bf16 v[2:5], v[108:111], v[124:127], v[2:5]
	v_mfma_f32_16x16x32_bf16 v[6:9], v[116:119], v[124:127], v[6:9]
	v_mfma_f32_16x16x32_bf16 v[10:13], v[108:111], v[132:135], v[10:13]
	v_mfma_f32_16x16x32_bf16 v[14:17], v[116:119], v[132:135], v[14:17]
	v_mfma_f32_16x16x32_bf16 v[18:21], v[108:111], v[140:143], v[18:21]
	v_mfma_f32_16x16x32_bf16 v[22:25], v[116:119], v[140:143], v[22:25]
	v_mfma_f32_16x16x32_bf16 v[26:29], v[108:111], v[148:151], v[26:29]
	v_mfma_f32_16x16x32_bf16 v[30:33], v[116:119], v[148:151], v[30:33]
	s_setprio 0
	s_barrier
	v_readfirstlane_b32 s1, v99
	v_lshl_add_u64 v[104:105], v[160:161], 0, s[28:29]
	s_mov_b32 m0, s1
	v_readfirstlane_b32 s1, v100
	global_load_lds_dwordx4 v[104:105], off
	v_lshl_add_u64 v[104:105], v[162:163], 0, s[28:29]
	s_mov_b32 m0, s1
	s_add_i32 s0, s0, 2
	global_load_lds_dwordx4 v[104:105], off
	s_waitcnt vmcnt(6)
	s_add_u32 s10, s10, 0x100
	s_addc_u32 s11, s11, 0
	s_cmpk_lt_u32 s0, 0x54
	s_barrier
	s_barrier
	s_cbranch_scc1 .LBB0_689
	s_add_u32 s0, s8, 0x2b80
	s_addc_u32 s1, s9, 0
	v_readfirstlane_b32 s8, v101
	v_lshl_add_u64 v[90:91], s[0:1], 0, v[0:1]
	s_mov_b32 m0, s8
	v_lshl_add_u64 v[66:67], s[0:1], 0, v[66:67]
	v_readfirstlane_b32 s0, v102
	s_waitcnt vmcnt(0)
	ds_read_b128 v[68:71], v95
	ds_read_b128 v[72:75], v95 offset:1024
	ds_read_b128 v[76:79], v95 offset:2048
	ds_read_b128 v[86:89], v95 offset:3072
	ds_read_b128 v[96:99], v93
	ds_read_b128 v[104:107], v93 offset:1024
	ds_read_b128 v[108:111], v93 offset:2048
	ds_read_b128 v[112:115], v93 offset:3072
	ds_read_b128 v[116:119], v93 offset:4096
	ds_read_b128 v[120:123], v93 offset:5120
	ds_read_b128 v[124:127], v93 offset:6144
	ds_read_b128 v[128:131], v93 offset:7168
	global_load_lds_dwordx4 v[90:91], off
	s_mov_b32 m0, s0
	s_nop 0
	global_load_lds_dwordx4 v[66:67], off
	s_barrier
	s_waitcnt lgkmcnt(0)
	s_setprio 1
	s_waitcnt lgkmcnt(0)
	v_mfma_f32_16x16x32_bf16 v[62:65], v[68:71], v[96:99], v[62:65]
	v_mfma_f32_16x16x32_bf16 v[58:61], v[76:79], v[96:99], v[58:61]
	v_mfma_f32_16x16x32_bf16 v[54:57], v[68:71], v[108:111], v[54:57]
	v_mfma_f32_16x16x32_bf16 v[50:53], v[76:79], v[108:111], v[50:53]
	v_mfma_f32_16x16x32_bf16 v[46:49], v[68:71], v[116:119], v[46:49]
	v_mfma_f32_16x16x32_bf16 v[42:45], v[76:79], v[116:119], v[42:45]
	v_mfma_f32_16x16x32_bf16 v[38:41], v[68:71], v[124:127], v[38:41]
	v_mfma_f32_16x16x32_bf16 v[34:37], v[76:79], v[124:127], v[34:37]
	v_mfma_f32_16x16x32_bf16 v[62:65], v[72:75], v[104:107], v[62:65]
	v_mfma_f32_16x16x32_bf16 v[58:61], v[86:89], v[104:107], v[58:61]
	v_mfma_f32_16x16x32_bf16 v[54:57], v[72:75], v[112:115], v[54:57]
	v_mfma_f32_16x16x32_bf16 v[50:53], v[86:89], v[112:115], v[50:53]
	v_mfma_f32_16x16x32_bf16 v[46:49], v[72:75], v[120:123], v[46:49]
	v_mfma_f32_16x16x32_bf16 v[42:45], v[86:89], v[120:123], v[42:45]
	v_mfma_f32_16x16x32_bf16 v[38:41], v[72:75], v[128:131], v[38:41]
	v_mfma_f32_16x16x32_bf16 v[34:37], v[86:89], v[128:131], v[34:37]
	s_setprio 0
	s_barrier
	s_barrier
	s_waitcnt lgkmcnt(0)
	s_barrier
	s_waitcnt vmcnt(0)
	ds_read_b128 v[96:99], v93 offset:16384
	ds_read_b128 v[100:103], v93 offset:17408
	ds_read_b128 v[104:107], v93 offset:18432
	ds_read_b128 v[108:111], v93 offset:19456
	ds_read_b128 v[112:115], v93 offset:20480
	ds_read_b128 v[116:119], v93 offset:21504
	ds_read_b128 v[120:123], v93 offset:22528
	ds_read_b128 v[124:127], v93 offset:23552
	s_waitcnt vmcnt(4)
	s_barrier
	s_waitcnt lgkmcnt(0)
	s_setprio 1
	s_waitcnt lgkmcnt(3)
	v_mfma_f32_16x16x32_bf16 v[18:21], v[68:71], v[112:115], v[18:21]
	v_mfma_f32_16x16x32_bf16 v[2:5], v[68:71], v[96:99], v[2:5]
	v_mfma_f32_16x16x32_bf16 v[6:9], v[76:79], v[96:99], v[6:9]
	s_waitcnt lgkmcnt(2)
	v_mfma_f32_16x16x32_bf16 v[96:99], v[72:75], v[116:119], v[18:21]
	v_mfma_f32_16x16x32_bf16 v[18:21], v[76:79], v[112:115], v[22:25]
	v_mfma_f32_16x16x32_bf16 v[2:5], v[72:75], v[100:103], v[2:5]
	v_mfma_f32_16x16x32_bf16 v[6:9], v[86:89], v[100:103], v[6:9]
	v_mfma_f32_16x16x32_bf16 v[10:13], v[68:71], v[104:107], v[10:13]
	v_mfma_f32_16x16x32_bf16 v[14:17], v[76:79], v[104:107], v[14:17]
	v_mfma_f32_16x16x32_bf16 v[100:103], v[86:89], v[116:119], v[18:21]
	s_waitcnt lgkmcnt(1)
	v_mfma_f32_16x16x32_bf16 v[18:21], v[68:71], v[120:123], v[26:29]
	v_mfma_f32_16x16x32_bf16 v[10:13], v[72:75], v[108:111], v[10:13]
	v_mfma_f32_16x16x32_bf16 v[14:17], v[86:89], v[108:111], v[14:17]
	s_waitcnt lgkmcnt(0)
	v_mfma_f32_16x16x32_bf16 v[66:69], v[72:75], v[124:127], v[18:21]
	v_mfma_f32_16x16x32_bf16 v[18:21], v[76:79], v[120:123], v[30:33]
	v_mfma_f32_16x16x32_bf16 v[70:73], v[86:89], v[124:127], v[18:21]
	s_setprio 0
	s_barrier
	ds_read_b128 v[74:77], v95 offset:32768
	ds_read_b128 v[86:89], v95 offset:33792
	ds_read_b128 v[104:107], v95 offset:34816
	ds_read_b128 v[108:111], v95 offset:35840
	s_nop 0
	ds_read_b128 v[18:21], v93 offset:32768
	ds_read_b128 v[22:25], v93 offset:33792
	ds_read_b128 v[26:29], v93 offset:34816
	ds_read_b128 v[30:33], v93 offset:35840
	ds_read_b128 v[112:115], v93 offset:36864
	ds_read_b128 v[116:119], v93 offset:37888
	ds_read_b128 v[120:123], v93 offset:38912
	ds_read_b128 v[124:127], v93 offset:39936
	s_waitcnt vmcnt(2)
	s_barrier
	s_waitcnt lgkmcnt(0)
	s_setprio 1
	s_waitcnt lgkmcnt(7)
	v_mfma_f32_16x16x32_bf16 v[62:65], v[74:77], v[18:21], v[62:65]
	v_mfma_f32_16x16x32_bf16 v[18:21], v[104:107], v[18:21], v[58:61]
	s_waitcnt lgkmcnt(6)
	v_mfma_f32_16x16x32_bf16 v[58:61], v[108:111], v[22:25], v[18:21]
	s_waitcnt lgkmcnt(5)
	v_mfma_f32_16x16x32_bf16 v[18:21], v[74:77], v[26:29], v[54:57]
	s_waitcnt lgkmcnt(4)
	v_mfma_f32_16x16x32_bf16 v[54:57], v[86:89], v[30:33], v[18:21]
	v_mfma_f32_16x16x32_bf16 v[18:21], v[104:107], v[26:29], v[50:53]
	v_mfma_f32_16x16x32_bf16 v[50:53], v[108:111], v[30:33], v[18:21]
	s_waitcnt lgkmcnt(3)
	v_mfma_f32_16x16x32_bf16 v[18:21], v[74:77], v[112:115], v[46:49]
	s_waitcnt lgkmcnt(2)
	v_mfma_f32_16x16x32_bf16 v[46:49], v[86:89], v[116:119], v[18:21]
	v_mfma_f32_16x16x32_bf16 v[18:21], v[104:107], v[112:115], v[42:45]
	v_mfma_f32_16x16x32_bf16 v[42:45], v[108:111], v[116:119], v[18:21]
	s_waitcnt lgkmcnt(1)
	v_mfma_f32_16x16x32_bf16 v[18:21], v[74:77], v[120:123], v[38:41]
	s_waitcnt lgkmcnt(0)
	v_mfma_f32_16x16x32_bf16 v[38:41], v[86:89], v[124:127], v[18:21]
	v_mfma_f32_16x16x32_bf16 v[18:21], v[104:107], v[120:123], v[34:37]
	v_mfma_f32_16x16x32_bf16 v[62:65], v[86:89], v[22:25], v[62:65]
	v_mfma_f32_16x16x32_bf16 v[34:37], v[108:111], v[124:127], v[18:21]
	s_setprio 0
	s_barrier
	s_waitcnt vmcnt(0)
	s_barrier
	s_waitcnt lgkmcnt(0)
	s_barrier
	s_nop 1
	ds_read_b128 v[18:21], v93 offset:49152
	ds_read_b128 v[22:25], v93 offset:50176
	ds_read_b128 v[112:115], v93 offset:51200
	ds_read_b128 v[116:119], v93 offset:52224
	ds_read_b128 v[120:123], v93 offset:53248
	ds_read_b128 v[124:127], v93 offset:54272
	ds_read_b128 v[128:131], v93 offset:55296
	ds_read_b128 v[90:93], v93 offset:56320
	s_barrier
	s_waitcnt lgkmcnt(0)
	s_setprio 1
	s_waitcnt lgkmcnt(7)
	v_mfma_f32_16x16x32_bf16 v[2:5], v[74:77], v[18:21], v[2:5]
	s_waitcnt lgkmcnt(6)
	v_mfma_f32_16x16x32_bf16 v[30:33], v[86:89], v[22:25], v[2:5]
	v_mfma_f32_16x16x32_bf16 v[2:5], v[104:107], v[18:21], v[6:9]
	v_mfma_f32_16x16x32_bf16 v[26:29], v[108:111], v[22:25], v[2:5]
	s_waitcnt lgkmcnt(5)
	v_mfma_f32_16x16x32_bf16 v[2:5], v[74:77], v[112:115], v[10:13]
	s_waitcnt lgkmcnt(4)
	v_mfma_f32_16x16x32_bf16 v[22:25], v[86:89], v[116:119], v[2:5]
	v_mfma_f32_16x16x32_bf16 v[2:5], v[104:107], v[112:115], v[14:17]
	v_mfma_f32_16x16x32_bf16 v[18:21], v[108:111], v[116:119], v[2:5]
	s_waitcnt lgkmcnt(3)
	v_mfma_f32_16x16x32_bf16 v[2:5], v[74:77], v[120:123], v[96:99]
	s_waitcnt lgkmcnt(2)
	v_mfma_f32_16x16x32_bf16 v[14:17], v[86:89], v[124:127], v[2:5]
	v_mfma_f32_16x16x32_bf16 v[2:5], v[104:107], v[120:123], v[100:103]
	v_mfma_f32_16x16x32_bf16 v[10:13], v[108:111], v[124:127], v[2:5]
	s_waitcnt lgkmcnt(1)
	v_mfma_f32_16x16x32_bf16 v[2:5], v[74:77], v[128:131], v[66:69]
	s_waitcnt lgkmcnt(0)
	v_mfma_f32_16x16x32_bf16 v[6:9], v[86:89], v[90:93], v[2:5]
	v_mfma_f32_16x16x32_bf16 v[2:5], v[104:107], v[128:131], v[70:73]
	v_mfma_f32_16x16x32_bf16 v[2:5], v[108:111], v[90:93], v[2:5]
	s_setprio 0
	s_movk_i32 s0, 0x100
	v_cmp_gt_u32_e32 vcc, s0, v80
	s_barrier
	s_and_saveexec_b64 s[0:1], vcc
	s_cbranch_execz .LBB0_692
	s_barrier

.LBB0_761:
	ds_read_b128 v[164:167], v148
	ds_read_b128 v[168:171], v148 offset:1024
	ds_read_b128 v[172:175], v148 offset:2048
	ds_read_b128 v[176:179], v148 offset:3072
	v_add_u32_e32 v161, 0xc000, v145
	v_lshl_add_u64 v[204:205], v[136:137], 0, s[10:11]
	v_readfirstlane_b32 s1, v161
	v_lshl_add_u64 v[162:163], v[204:205], 0, s[34:35]
	s_mov_b32 m0, s1
	ds_read_b128 v[180:183], v147
	ds_read_b128 v[184:187], v147 offset:1024
	ds_read_b128 v[188:191], v147 offset:2048
	ds_read_b128 v[192:195], v147 offset:3072
	ds_read_b128 v[196:199], v147 offset:4096
	ds_read_b128 v[200:203], v147 offset:5120
	ds_read_b128 v[222:225], v147 offset:6144
	ds_read_b128 v[232:235], v147 offset:7168
	global_load_lds_dwordx4 v[162:163], off
	v_add_u32_e32 v162, 0xe000, v145
	v_lshl_add_u64 v[210:211], v[138:139], 0, s[10:11]
	v_readfirstlane_b32 s1, v162
	v_lshl_add_u64 v[216:217], v[210:211], 0, s[34:35]
	s_mov_b32 m0, s1
	s_nop 0
	global_load_lds_dwordx4 v[216:217], off
	s_waitcnt lgkmcnt(8)
	s_barrier
	s_waitcnt lgkmcnt(0)
	s_setprio 1
	s_waitcnt lgkmcnt(0)
	v_mfma_f32_16x16x32_bf16 v[126:129], v[164:167], v[180:183], v[126:129]
	v_mfma_f32_16x16x32_bf16 v[122:125], v[172:175], v[180:183], v[122:125]
	v_mfma_f32_16x16x32_bf16 v[118:121], v[164:167], v[188:191], v[118:121]
	v_mfma_f32_16x16x32_bf16 v[114:117], v[172:175], v[188:191], v[114:117]
	v_mfma_f32_16x16x32_bf16 v[110:113], v[164:167], v[196:199], v[110:113]
	v_mfma_f32_16x16x32_bf16 v[106:109], v[172:175], v[196:199], v[106:109]
	v_mfma_f32_16x16x32_bf16 v[102:105], v[164:167], v[222:225], v[102:105]
	v_mfma_f32_16x16x32_bf16 v[98:101], v[172:175], v[222:225], v[98:101]
	v_mfma_f32_16x16x32_bf16 v[126:129], v[168:171], v[184:187], v[126:129]
	v_mfma_f32_16x16x32_bf16 v[122:125], v[176:179], v[184:187], v[122:125]
	v_mfma_f32_16x16x32_bf16 v[118:121], v[168:171], v[192:195], v[118:121]
	v_mfma_f32_16x16x32_bf16 v[114:117], v[176:179], v[192:195], v[114:117]
	v_mfma_f32_16x16x32_bf16 v[110:113], v[168:171], v[200:203], v[110:113]
	v_mfma_f32_16x16x32_bf16 v[106:109], v[176:179], v[200:203], v[106:109]
	v_mfma_f32_16x16x32_bf16 v[102:105], v[168:171], v[232:235], v[102:105]
	v_mfma_f32_16x16x32_bf16 v[98:101], v[176:179], v[232:235], v[98:101]
	s_setprio 0
	s_barrier
	v_lshl_add_u64 v[216:217], v[132:133], 0, s[10:11]
	v_readfirstlane_b32 s1, v149
	v_lshl_add_u64 v[218:219], v[216:217], 0, s[74:75]
	s_mov_b32 m0, s1
	ds_read_b128 v[236:239], v148 offset:16384
	ds_read_b128 v[240:243], v148 offset:17408
	ds_read_b128 v[244:247], v148 offset:18432
	ds_read_b128 v[248:251], v148 offset:19456
	global_load_lds_dwordx4 v[218:219], off
	v_lshl_add_u64 v[218:219], v[134:135], 0, s[10:11]
	v_readfirstlane_b32 s1, v150
	v_lshl_add_u64 v[228:229], v[218:219], 0, s[74:75]
	s_mov_b32 m0, s1
	s_nop 0
	global_load_lds_dwordx4 v[228:229], off
	s_barrier
	s_waitcnt lgkmcnt(0)
	s_setprio 1
	s_waitcnt lgkmcnt(0)
	v_mfma_f32_16x16x32_bf16 v[94:97], v[236:239], v[180:183], v[94:97]
	v_mfma_f32_16x16x32_bf16 v[90:93], v[244:247], v[180:183], v[90:93]
	v_mfma_f32_16x16x32_bf16 v[86:89], v[236:239], v[188:191], v[86:89]
	v_mfma_f32_16x16x32_bf16 v[82:85], v[244:247], v[188:191], v[82:85]
	v_mfma_f32_16x16x32_bf16 v[78:81], v[236:239], v[196:199], v[78:81]
	v_mfma_f32_16x16x32_bf16 v[74:77], v[244:247], v[196:199], v[74:77]
	v_mfma_f32_16x16x32_bf16 v[70:73], v[236:239], v[222:225], v[70:73]
	v_mfma_f32_16x16x32_bf16 v[66:69], v[244:247], v[222:225], v[66:69]
	v_mfma_f32_16x16x32_bf16 v[94:97], v[240:243], v[184:187], v[94:97]
	v_mfma_f32_16x16x32_bf16 v[90:93], v[248:251], v[184:187], v[90:93]
	v_mfma_f32_16x16x32_bf16 v[86:89], v[240:243], v[192:195], v[86:89]
	v_mfma_f32_16x16x32_bf16 v[82:85], v[248:251], v[192:195], v[82:85]
	v_mfma_f32_16x16x32_bf16 v[78:81], v[240:243], v[200:203], v[78:81]
	v_mfma_f32_16x16x32_bf16 v[74:77], v[248:251], v[200:203], v[74:77]
	v_mfma_f32_16x16x32_bf16 v[70:73], v[240:243], v[232:235], v[70:73]
	v_mfma_f32_16x16x32_bf16 v[66:69], v[248:251], v[232:235], v[66:69]
	s_setprio 0
	v_readfirstlane_b32 s1, v145
	v_lshl_add_u64 v[228:229], v[204:205], 0, s[74:75]
	s_mov_b32 m0, s1
	v_readfirstlane_b32 s1, v146
	s_barrier
	ds_read_b128 v[180:183], v147 offset:16384
	ds_read_b128 v[184:187], v147 offset:17408
	ds_read_b128 v[188:191], v147 offset:18432
	ds_read_b128 v[192:195], v147 offset:19456
	ds_read_b128 v[196:199], v147 offset:20480
	ds_read_b128 v[200:203], v147 offset:21504
	ds_read_b128 v[222:225], v147 offset:22528
	ds_read_b128 v[232:235], v147 offset:23552
	global_load_lds_dwordx4 v[228:229], off
	v_lshl_add_u64 v[228:229], v[210:211], 0, s[74:75]
	s_mov_b32 m0, s1
	s_nop 0
	global_load_lds_dwordx4 v[228:229], off
	s_barrier
	s_waitcnt lgkmcnt(0)
	s_setprio 1
	s_waitcnt lgkmcnt(0)
	v_mfma_f32_16x16x32_bf16 v[62:65], v[164:167], v[180:183], v[62:65]
	v_mfma_f32_16x16x32_bf16 v[58:61], v[172:175], v[180:183], v[58:61]
	v_mfma_f32_16x16x32_bf16 v[54:57], v[164:167], v[188:191], v[54:57]
	v_mfma_f32_16x16x32_bf16 v[50:53], v[172:175], v[188:191], v[50:53]
	v_mfma_f32_16x16x32_bf16 v[46:49], v[164:167], v[196:199], v[46:49]
	v_mfma_f32_16x16x32_bf16 v[42:45], v[172:175], v[196:199], v[42:45]
	v_mfma_f32_16x16x32_bf16 v[38:41], v[164:167], v[222:225], v[38:41]
	v_mfma_f32_16x16x32_bf16 v[34:37], v[172:175], v[222:225], v[34:37]
	v_mfma_f32_16x16x32_bf16 v[62:65], v[168:171], v[184:187], v[62:65]
	v_mfma_f32_16x16x32_bf16 v[58:61], v[176:179], v[184:187], v[58:61]
	v_mfma_f32_16x16x32_bf16 v[54:57], v[168:171], v[192:195], v[54:57]
	v_mfma_f32_16x16x32_bf16 v[50:53], v[176:179], v[192:195], v[50:53]
	v_mfma_f32_16x16x32_bf16 v[46:49], v[168:171], v[200:203], v[46:49]
	v_mfma_f32_16x16x32_bf16 v[42:45], v[176:179], v[200:203], v[42:45]
	v_mfma_f32_16x16x32_bf16 v[38:41], v[168:171], v[232:235], v[38:41]
	v_mfma_f32_16x16x32_bf16 v[34:37], v[176:179], v[232:235], v[34:37]
	s_setprio 0
	s_barrier
	v_readfirstlane_b32 s1, v151
	v_lshl_add_u64 v[164:165], v[216:217], 0, s[78:79]
	s_mov_b32 m0, s1
	v_readfirstlane_b32 s1, v152
	global_load_lds_dwordx4 v[164:165], off
	v_lshl_add_u64 v[164:165], v[218:219], 0, s[78:79]
	s_mov_b32 m0, s1
	s_nop 0
	global_load_lds_dwordx4 v[164:165], off
	s_waitcnt vmcnt(6)
	s_barrier
	s_setprio 1
	v_mfma_f32_16x16x32_bf16 v[30:33], v[236:239], v[180:183], v[30:33]
	v_mfma_f32_16x16x32_bf16 v[26:29], v[244:247], v[180:183], v[26:29]
	v_mfma_f32_16x16x32_bf16 v[22:25], v[236:239], v[188:191], v[22:25]
	v_mfma_f32_16x16x32_bf16 v[18:21], v[244:247], v[188:191], v[18:21]
	v_mfma_f32_16x16x32_bf16 v[14:17], v[236:239], v[196:199], v[14:17]
	v_mfma_f32_16x16x32_bf16 v[10:13], v[244:247], v[196:199], v[10:13]
	v_mfma_f32_16x16x32_bf16 v[6:9], v[236:239], v[222:225], v[6:9]
	v_mfma_f32_16x16x32_bf16 v[2:5], v[244:247], v[222:225], v[2:5]
	v_mfma_f32_16x16x32_bf16 v[30:33], v[240:243], v[184:187], v[30:33]
	v_mfma_f32_16x16x32_bf16 v[26:29], v[248:251], v[184:187], v[26:29]
	v_mfma_f32_16x16x32_bf16 v[22:25], v[240:243], v[192:195], v[22:25]
	v_mfma_f32_16x16x32_bf16 v[18:21], v[248:251], v[192:195], v[18:21]
	v_mfma_f32_16x16x32_bf16 v[14:17], v[240:243], v[200:203], v[14:17]
	v_mfma_f32_16x16x32_bf16 v[10:13], v[248:251], v[200:203], v[10:13]
	v_mfma_f32_16x16x32_bf16 v[6:9], v[240:243], v[232:235], v[6:9]
	v_mfma_f32_16x16x32_bf16 v[2:5], v[248:251], v[232:235], v[2:5]
	s_setprio 0
	s_barrier
	ds_read_b128 v[164:167], v148 offset:32768
	ds_read_b128 v[168:171], v148 offset:33792
	ds_read_b128 v[172:175], v148 offset:34816
	ds_read_b128 v[176:179], v148 offset:35840
	v_readfirstlane_b32 s1, v153
	v_lshl_add_u64 v[228:229], v[204:205], 0, s[78:79]
	s_mov_b32 m0, s1
	v_readfirstlane_b32 s1, v154
	ds_read_b128 v[180:183], v147 offset:32768
	ds_read_b128 v[184:187], v147 offset:33792
	ds_read_b128 v[188:191], v147 offset:34816
	ds_read_b128 v[192:195], v147 offset:35840
	ds_read_b128 v[196:199], v147 offset:36864
	ds_read_b128 v[200:203], v147 offset:37888
	ds_read_b128 v[222:225], v147 offset:38912
	ds_read_b128 v[232:235], v147 offset:39936
	global_load_lds_dwordx4 v[228:229], off
	v_lshl_add_u64 v[228:229], v[210:211], 0, s[78:79]
	s_mov_b32 m0, s1
	s_nop 0
	global_load_lds_dwordx4 v[228:229], off
	s_waitcnt lgkmcnt(8)
	s_barrier
	s_waitcnt lgkmcnt(0)
	s_setprio 1
	s_waitcnt lgkmcnt(0)
	v_mfma_f32_16x16x32_bf16 v[126:129], v[164:167], v[180:183], v[126:129]
	v_mfma_f32_16x16x32_bf16 v[122:125], v[172:175], v[180:183], v[122:125]
	v_mfma_f32_16x16x32_bf16 v[118:121], v[164:167], v[188:191], v[118:121]
	v_mfma_f32_16x16x32_bf16 v[114:117], v[172:175], v[188:191], v[114:117]
	v_mfma_f32_16x16x32_bf16 v[110:113], v[164:167], v[196:199], v[110:113]
	v_mfma_f32_16x16x32_bf16 v[106:109], v[172:175], v[196:199], v[106:109]
	v_mfma_f32_16x16x32_bf16 v[102:105], v[164:167], v[222:225], v[102:105]
	v_mfma_f32_16x16x32_bf16 v[98:101], v[172:175], v[222:225], v[98:101]
	v_mfma_f32_16x16x32_bf16 v[126:129], v[168:171], v[184:187], v[126:129]
	v_mfma_f32_16x16x32_bf16 v[122:125], v[176:179], v[184:187], v[122:125]
	v_mfma_f32_16x16x32_bf16 v[118:121], v[168:171], v[192:195], v[118:121]
	v_mfma_f32_16x16x32_bf16 v[114:117], v[176:179], v[192:195], v[114:117]
	v_mfma_f32_16x16x32_bf16 v[110:113], v[168:171], v[200:203], v[110:113]
	v_mfma_f32_16x16x32_bf16 v[106:109], v[176:179], v[200:203], v[106:109]
	v_mfma_f32_16x16x32_bf16 v[102:105], v[168:171], v[232:235], v[102:105]
	v_mfma_f32_16x16x32_bf16 v[98:101], v[176:179], v[232:235], v[98:101]
	s_setprio 0
	s_barrier
	v_readfirstlane_b32 s1, v155
	v_lshl_add_u64 v[228:229], v[216:217], 0, s[28:29]
	s_mov_b32 m0, s1
	v_readfirstlane_b32 s1, v156
	ds_read_b128 v[236:239], v148 offset:49152
	ds_read_b128 v[240:243], v148 offset:50176
	ds_read_b128 v[244:247], v148 offset:51200
	ds_read_b128 v[248:251], v148 offset:52224
	global_load_lds_dwordx4 v[228:229], off
	v_lshl_add_u64 v[228:229], v[218:219], 0, s[28:29]
	s_mov_b32 m0, s1
	s_nop 0
	global_load_lds_dwordx4 v[228:229], off
	s_barrier
	s_waitcnt lgkmcnt(0)
	s_setprio 1
	s_waitcnt lgkmcnt(0)
	v_mfma_f32_16x16x32_bf16 v[94:97], v[236:239], v[180:183], v[94:97]
	v_mfma_f32_16x16x32_bf16 v[90:93], v[244:247], v[180:183], v[90:93]
	v_mfma_f32_16x16x32_bf16 v[86:89], v[236:239], v[188:191], v[86:89]
	v_mfma_f32_16x16x32_bf16 v[82:85], v[244:247], v[188:191], v[82:85]
	v_mfma_f32_16x16x32_bf16 v[78:81], v[236:239], v[196:199], v[78:81]
	v_mfma_f32_16x16x32_bf16 v[74:77], v[244:247], v[196:199], v[74:77]
	v_mfma_f32_16x16x32_bf16 v[70:73], v[236:239], v[222:225], v[70:73]
	v_mfma_f32_16x16x32_bf16 v[66:69], v[244:247], v[222:225], v[66:69]
	v_mfma_f32_16x16x32_bf16 v[94:97], v[240:243], v[184:187], v[94:97]
	v_mfma_f32_16x16x32_bf16 v[90:93], v[248:251], v[184:187], v[90:93]
	v_mfma_f32_16x16x32_bf16 v[86:89], v[240:243], v[192:195], v[86:89]
	v_mfma_f32_16x16x32_bf16 v[82:85], v[248:251], v[192:195], v[82:85]
	v_mfma_f32_16x16x32_bf16 v[78:81], v[240:243], v[200:203], v[78:81]
	v_mfma_f32_16x16x32_bf16 v[74:77], v[248:251], v[200:203], v[74:77]
	v_mfma_f32_16x16x32_bf16 v[70:73], v[240:243], v[232:235], v[70:73]
	v_mfma_f32_16x16x32_bf16 v[66:69], v[248:251], v[232:235], v[66:69]
	s_setprio 0
	v_readfirstlane_b32 s1, v157
	v_lshl_add_u64 v[204:205], v[204:205], 0, s[28:29]
	s_mov_b32 m0, s1
	v_readfirstlane_b32 s1, v158
	s_barrier
	ds_read_b128 v[180:183], v147 offset:49152
	ds_read_b128 v[184:187], v147 offset:50176
	ds_read_b128 v[188:191], v147 offset:51200
	ds_read_b128 v[192:195], v147 offset:52224
	ds_read_b128 v[196:199], v147 offset:53248
	ds_read_b128 v[200:203], v147 offset:54272
	ds_read_b128 v[222:225], v147 offset:55296
	ds_read_b128 v[232:235], v147 offset:56320
	global_load_lds_dwordx4 v[204:205], off
	v_lshl_add_u64 v[204:205], v[210:211], 0, s[28:29]
	s_mov_b32 m0, s1
	s_nop 0
	global_load_lds_dwordx4 v[204:205], off
	s_barrier
	s_waitcnt lgkmcnt(0)
	s_setprio 1
	s_waitcnt lgkmcnt(0)
	v_mfma_f32_16x16x32_bf16 v[62:65], v[164:167], v[180:183], v[62:65]
	v_mfma_f32_16x16x32_bf16 v[58:61], v[172:175], v[180:183], v[58:61]
	v_mfma_f32_16x16x32_bf16 v[54:57], v[164:167], v[188:191], v[54:57]
	v_mfma_f32_16x16x32_bf16 v[50:53], v[172:175], v[188:191], v[50:53]
	v_mfma_f32_16x16x32_bf16 v[46:49], v[164:167], v[196:199], v[46:49]
	v_mfma_f32_16x16x32_bf16 v[42:45], v[172:175], v[196:199], v[42:45]
	v_mfma_f32_16x16x32_bf16 v[38:41], v[164:167], v[222:225], v[38:41]
	v_mfma_f32_16x16x32_bf16 v[34:37], v[172:175], v[222:225], v[34:37]
	v_mfma_f32_16x16x32_bf16 v[62:65], v[168:171], v[184:187], v[62:65]
	v_mfma_f32_16x16x32_bf16 v[58:61], v[176:179], v[184:187], v[58:61]
	v_mfma_f32_16x16x32_bf16 v[54:57], v[168:171], v[192:195], v[54:57]
	v_mfma_f32_16x16x32_bf16 v[50:53], v[176:179], v[192:195], v[50:53]
	v_mfma_f32_16x16x32_bf16 v[46:49], v[168:171], v[200:203], v[46:49]
	v_mfma_f32_16x16x32_bf16 v[42:45], v[176:179], v[200:203], v[42:45]
	v_mfma_f32_16x16x32_bf16 v[38:41], v[168:171], v[232:235], v[38:41]
	v_mfma_f32_16x16x32_bf16 v[34:37], v[176:179], v[232:235], v[34:37]
	s_setprio 0
	s_barrier
	v_readfirstlane_b32 s1, v159
	v_lshl_add_u64 v[164:165], v[216:217], 0, s[68:69]
	s_mov_b32 m0, s1
	v_readfirstlane_b32 s1, v160
	global_load_lds_dwordx4 v[164:165], off
	v_lshl_add_u64 v[164:165], v[218:219], 0, s[68:69]
	s_mov_b32 m0, s1
	s_nop 0
	global_load_lds_dwordx4 v[164:165], off
	s_waitcnt vmcnt(6)
	s_barrier
	s_setprio 1
	v_mfma_f32_16x16x32_bf16 v[30:33], v[236:239], v[180:183], v[30:33]
	v_mfma_f32_16x16x32_bf16 v[26:29], v[244:247], v[180:183], v[26:29]
	v_mfma_f32_16x16x32_bf16 v[22:25], v[236:239], v[188:191], v[22:25]
	v_mfma_f32_16x16x32_bf16 v[18:21], v[244:247], v[188:191], v[18:21]
	v_mfma_f32_16x16x32_bf16 v[14:17], v[236:239], v[196:199], v[14:17]
	v_mfma_f32_16x16x32_bf16 v[10:13], v[244:247], v[196:199], v[10:13]
	v_mfma_f32_16x16x32_bf16 v[6:9], v[236:239], v[222:225], v[6:9]
	v_mfma_f32_16x16x32_bf16 v[2:5], v[244:247], v[222:225], v[2:5]
	v_mfma_f32_16x16x32_bf16 v[30:33], v[240:243], v[184:187], v[30:33]
	v_mfma_f32_16x16x32_bf16 v[26:29], v[248:251], v[184:187], v[26:29]
	v_mfma_f32_16x16x32_bf16 v[22:25], v[240:243], v[192:195], v[22:25]
	v_mfma_f32_16x16x32_bf16 v[18:21], v[248:251], v[192:195], v[18:21]
	v_mfma_f32_16x16x32_bf16 v[14:17], v[240:243], v[200:203], v[14:17]
	v_mfma_f32_16x16x32_bf16 v[10:13], v[248:251], v[200:203], v[10:13]
	v_mfma_f32_16x16x32_bf16 v[6:9], v[240:243], v[232:235], v[6:9]
	v_mfma_f32_16x16x32_bf16 v[2:5], v[248:251], v[232:235], v[2:5]
	s_setprio 0
	s_add_i32 s0, s0, 2
	s_add_u32 s10, s10, 0x100
	s_addc_u32 s11, s11, 0
	s_cmpk_lt_u32 s0, 0x54
	s_barrier
	s_cbranch_scc1 .LBB0_761
	s_add_u32 s0, s8, 0x162b80
	s_addc_u32 s1, s9, 0
	v_readfirstlane_b32 s8, v161
	v_lshl_add_u64 v[158:159], s[0:1], 0, v[0:1]
	s_mov_b32 m0, s8
	v_lshl_add_u64 v[130:131], s[0:1], 0, v[130:131]
	v_readfirstlane_b32 s0, v162
	s_waitcnt vmcnt(0)
	ds_read_b128 v[132:135], v148
	ds_read_b128 v[136:139], v148 offset:1024
	ds_read_b128 v[150:153], v148 offset:2048
	ds_read_b128 v[154:157], v148 offset:3072
	ds_read_b128 v[164:167], v147
	ds_read_b128 v[168:171], v147 offset:1024
	ds_read_b128 v[172:175], v147 offset:2048
	ds_read_b128 v[176:179], v147 offset:3072
	ds_read_b128 v[180:183], v147 offset:4096
	ds_read_b128 v[184:187], v147 offset:5120
	ds_read_b128 v[188:191], v147 offset:6144
	ds_read_b128 v[192:195], v147 offset:7168
	global_load_lds_dwordx4 v[158:159], off
	s_mov_b32 m0, s0
	s_nop 0
	global_load_lds_dwordx4 v[130:131], off
	s_barrier
	s_waitcnt lgkmcnt(0)
	s_setprio 1
	s_waitcnt lgkmcnt(0)
	v_mfma_f32_16x16x32_bf16 v[122:125], v[150:153], v[164:167], v[122:125]
	v_mfma_f32_16x16x32_bf16 v[118:121], v[132:135], v[172:175], v[118:121]
	v_mfma_f32_16x16x32_bf16 v[114:117], v[150:153], v[172:175], v[114:117]
	v_mfma_f32_16x16x32_bf16 v[102:105], v[132:135], v[188:191], v[102:105]
	v_mfma_f32_16x16x32_bf16 v[98:101], v[150:153], v[188:191], v[98:101]
	v_mfma_f32_16x16x32_bf16 v[126:129], v[132:135], v[164:167], v[126:129]
	v_mfma_f32_16x16x32_bf16 v[122:125], v[154:157], v[168:171], v[122:125]
	v_mfma_f32_16x16x32_bf16 v[118:121], v[136:139], v[176:179], v[118:121]
	v_mfma_f32_16x16x32_bf16 v[114:117], v[154:157], v[176:179], v[114:117]
	v_mfma_f32_16x16x32_bf16 v[110:113], v[132:135], v[180:183], v[110:113]
	v_mfma_f32_16x16x32_bf16 v[106:109], v[150:153], v[180:183], v[106:109]
	v_mfma_f32_16x16x32_bf16 v[102:105], v[136:139], v[192:195], v[102:105]
	v_mfma_f32_16x16x32_bf16 v[98:101], v[154:157], v[192:195], v[98:101]
	v_mfma_f32_16x16x32_bf16 v[126:129], v[136:139], v[168:171], v[126:129]
	v_mfma_f32_16x16x32_bf16 v[158:161], v[136:139], v[184:187], v[110:113]
	v_mfma_f32_16x16x32_bf16 v[196:199], v[154:157], v[184:187], v[106:109]
	s_setprio 0
	s_barrier
	s_waitcnt vmcnt(0)
	ds_read_b128 v[106:109], v148 offset:16384
	ds_read_b128 v[110:113], v148 offset:17408
	ds_read_b128 v[200:203], v148 offset:18432
	ds_read_b128 v[222:225], v148 offset:19456
	s_barrier
	s_waitcnt lgkmcnt(0)
	s_setprio 1
	s_waitcnt lgkmcnt(3)
	v_mfma_f32_16x16x32_bf16 v[86:89], v[106:109], v[172:175], v[86:89]
	s_waitcnt lgkmcnt(1)
	v_mfma_f32_16x16x32_bf16 v[82:85], v[200:203], v[172:175], v[82:85]
	v_mfma_f32_16x16x32_bf16 v[70:73], v[106:109], v[188:191], v[70:73]
	v_mfma_f32_16x16x32_bf16 v[66:69], v[200:203], v[188:191], v[66:69]
	v_mfma_f32_16x16x32_bf16 v[94:97], v[106:109], v[164:167], v[94:97]
	v_mfma_f32_16x16x32_bf16 v[90:93], v[200:203], v[164:167], v[90:93]
	v_mfma_f32_16x16x32_bf16 v[86:89], v[110:113], v[176:179], v[86:89]
	s_waitcnt lgkmcnt(0)
	v_mfma_f32_16x16x32_bf16 v[82:85], v[222:225], v[176:179], v[82:85]
	v_mfma_f32_16x16x32_bf16 v[78:81], v[106:109], v[180:183], v[78:81]
	v_mfma_f32_16x16x32_bf16 v[74:77], v[200:203], v[180:183], v[74:77]
	v_mfma_f32_16x16x32_bf16 v[70:73], v[110:113], v[192:195], v[70:73]
	v_mfma_f32_16x16x32_bf16 v[66:69], v[222:225], v[192:195], v[66:69]
	v_mfma_f32_16x16x32_bf16 v[232:235], v[110:113], v[168:171], v[94:97]
	v_mfma_f32_16x16x32_bf16 v[162:165], v[222:225], v[168:171], v[90:93]
	v_mfma_f32_16x16x32_bf16 v[166:169], v[110:113], v[184:187], v[78:81]
	v_mfma_f32_16x16x32_bf16 v[170:173], v[222:225], v[184:187], v[74:77]
	s_setprio 0
	s_barrier
	s_nop 0
	ds_read_b128 v[74:77], v147 offset:16384
	ds_read_b128 v[78:81], v147 offset:17408
	ds_read_b128 v[90:93], v147 offset:18432
	ds_read_b128 v[94:97], v147 offset:19456
	ds_read_b128 v[174:177], v147 offset:20480
	ds_read_b128 v[178:181], v147 offset:21504
	ds_read_b128 v[182:185], v147 offset:22528
	ds_read_b128 v[186:189], v147 offset:23552
	s_waitcnt vmcnt(4)
	s_barrier
	s_waitcnt lgkmcnt(0)
	s_setprio 1
	s_waitcnt lgkmcnt(7)
	v_mfma_f32_16x16x32_bf16 v[62:65], v[132:135], v[74:77], v[62:65]
	v_mfma_f32_16x16x32_bf16 v[58:61], v[150:153], v[74:77], v[58:61]
	s_waitcnt lgkmcnt(5)
	v_mfma_f32_16x16x32_bf16 v[54:57], v[132:135], v[90:93], v[54:57]
	v_mfma_f32_16x16x32_bf16 v[50:53], v[150:153], v[90:93], v[50:53]
	s_waitcnt lgkmcnt(1)
	v_mfma_f32_16x16x32_bf16 v[38:41], v[132:135], v[182:185], v[38:41]
	v_mfma_f32_16x16x32_bf16 v[34:37], v[150:153], v[182:185], v[34:37]
	v_mfma_f32_16x16x32_bf16 v[62:65], v[136:139], v[78:81], v[62:65]
	v_mfma_f32_16x16x32_bf16 v[58:61], v[154:157], v[78:81], v[58:61]
	v_mfma_f32_16x16x32_bf16 v[54:57], v[136:139], v[94:97], v[54:57]
	v_mfma_f32_16x16x32_bf16 v[50:53], v[154:157], v[94:97], v[50:53]
	v_mfma_f32_16x16x32_bf16 v[46:49], v[132:135], v[174:177], v[46:49]
	v_mfma_f32_16x16x32_bf16 v[42:45], v[150:153], v[174:177], v[42:45]
	s_waitcnt lgkmcnt(0)
	v_mfma_f32_16x16x32_bf16 v[38:41], v[136:139], v[186:189], v[38:41]
	v_mfma_f32_16x16x32_bf16 v[34:37], v[154:157], v[186:189], v[34:37]
	v_mfma_f32_16x16x32_bf16 v[190:193], v[136:139], v[178:181], v[46:49]
	v_mfma_f32_16x16x32_bf16 v[236:239], v[154:157], v[178:181], v[42:45]
	s_setprio 0
	s_setprio 1
	v_mfma_f32_16x16x32_bf16 v[22:25], v[106:109], v[90:93], v[22:25]
	v_mfma_f32_16x16x32_bf16 v[18:21], v[200:203], v[90:93], v[18:21]
	v_mfma_f32_16x16x32_bf16 v[6:9], v[106:109], v[182:185], v[6:9]
	v_mfma_f32_16x16x32_bf16 v[2:5], v[200:203], v[182:185], v[2:5]
	v_mfma_f32_16x16x32_bf16 v[30:33], v[106:109], v[74:77], v[30:33]
	v_mfma_f32_16x16x32_bf16 v[26:29], v[200:203], v[74:77], v[26:29]
	v_mfma_f32_16x16x32_bf16 v[22:25], v[110:113], v[94:97], v[22:25]
	v_mfma_f32_16x16x32_bf16 v[18:21], v[222:225], v[94:97], v[18:21]
	v_mfma_f32_16x16x32_bf16 v[14:17], v[106:109], v[174:177], v[14:17]
	v_mfma_f32_16x16x32_bf16 v[10:13], v[200:203], v[174:177], v[10:13]
	v_mfma_f32_16x16x32_bf16 v[6:9], v[110:113], v[186:189], v[6:9]
	v_mfma_f32_16x16x32_bf16 v[2:5], v[222:225], v[186:189], v[2:5]
	v_mfma_f32_16x16x32_bf16 v[134:137], v[110:113], v[78:81], v[30:33]
	v_mfma_f32_16x16x32_bf16 v[150:153], v[222:225], v[78:81], v[26:29]
	v_mfma_f32_16x16x32_bf16 v[154:157], v[110:113], v[178:181], v[14:17]
	v_mfma_f32_16x16x32_bf16 v[174:177], v[222:225], v[178:181], v[10:13]
	s_setprio 0
	s_barrier
	s_nop 0
	ds_read_b128 v[10:13], v148 offset:32768
	ds_read_b128 v[14:17], v148 offset:33792
	ds_read_b128 v[178:181], v148 offset:34816
	ds_read_b128 v[182:185], v148 offset:35840
	ds_read_b128 v[26:29], v147 offset:32768
	ds_read_b128 v[30:33], v147 offset:33792
	ds_read_b128 v[42:45], v147 offset:34816
	ds_read_b128 v[46:49], v147 offset:35840
	ds_read_b128 v[186:189], v147 offset:36864
	ds_read_b128 v[200:203], v147 offset:37888
	ds_read_b128 v[222:225], v147 offset:38912
	ds_read_b128 v[240:243], v147 offset:39936
	s_waitcnt vmcnt(2)
	s_barrier
	s_waitcnt lgkmcnt(0)
	s_setprio 1
	s_waitcnt lgkmcnt(7)
	v_mfma_f32_16x16x32_bf16 v[74:77], v[10:13], v[26:29], v[126:129]
	s_waitcnt lgkmcnt(6)
	v_mfma_f32_16x16x32_bf16 v[130:133], v[14:17], v[30:33], v[74:77]
	v_mfma_f32_16x16x32_bf16 v[74:77], v[178:181], v[26:29], v[122:125]
	v_mfma_f32_16x16x32_bf16 v[122:125], v[182:185], v[30:33], v[74:77]
	s_waitcnt lgkmcnt(5)
	v_mfma_f32_16x16x32_bf16 v[74:77], v[10:13], v[42:45], v[118:121]
	s_waitcnt lgkmcnt(4)
	v_mfma_f32_16x16x32_bf16 v[110:113], v[14:17], v[46:49], v[74:77]
	v_mfma_f32_16x16x32_bf16 v[74:77], v[178:181], v[42:45], v[114:117]
	v_mfma_f32_16x16x32_bf16 v[106:109], v[182:185], v[46:49], v[74:77]
	s_waitcnt lgkmcnt(3)
	v_mfma_f32_16x16x32_bf16 v[74:77], v[10:13], v[186:189], v[158:161]
	s_waitcnt lgkmcnt(2)
	v_mfma_f32_16x16x32_bf16 v[94:97], v[14:17], v[200:203], v[74:77]
	v_mfma_f32_16x16x32_bf16 v[74:77], v[178:181], v[186:189], v[196:199]
	v_mfma_f32_16x16x32_bf16 v[90:93], v[182:185], v[200:203], v[74:77]
	s_waitcnt lgkmcnt(1)
	v_mfma_f32_16x16x32_bf16 v[74:77], v[10:13], v[222:225], v[102:105]
	s_waitcnt lgkmcnt(0)
	v_mfma_f32_16x16x32_bf16 v[78:81], v[14:17], v[240:243], v[74:77]
	v_mfma_f32_16x16x32_bf16 v[74:77], v[178:181], v[222:225], v[98:101]
	v_mfma_f32_16x16x32_bf16 v[74:77], v[182:185], v[240:243], v[74:77]
	s_setprio 0
	s_barrier
	ds_read_b128 v[126:129], v148 offset:49152
	ds_read_b128 v[158:161], v148 offset:50176
	ds_read_b128 v[194:197], v148 offset:51200
	ds_read_b128 v[244:247], v148 offset:52224
	s_waitcnt vmcnt(0)
	s_barrier
	s_waitcnt lgkmcnt(0)
	s_setprio 1
	s_waitcnt lgkmcnt(3)
	v_mfma_f32_16x16x32_bf16 v[98:101], v[126:129], v[26:29], v[232:235]
	s_waitcnt lgkmcnt(1)
	v_mfma_f32_16x16x32_bf16 v[26:29], v[194:197], v[26:29], v[162:165]
	s_waitcnt lgkmcnt(0)
	v_mfma_f32_16x16x32_bf16 v[114:117], v[244:247], v[30:33], v[26:29]
	v_mfma_f32_16x16x32_bf16 v[26:29], v[126:129], v[42:45], v[86:89]
	v_mfma_f32_16x16x32_bf16 v[102:105], v[158:161], v[46:49], v[26:29]
	v_mfma_f32_16x16x32_bf16 v[26:29], v[194:197], v[42:45], v[82:85]
	v_mfma_f32_16x16x32_bf16 v[118:121], v[158:161], v[30:33], v[98:101]
	v_mfma_f32_16x16x32_bf16 v[98:101], v[244:247], v[46:49], v[26:29]
	v_mfma_f32_16x16x32_bf16 v[26:29], v[126:129], v[186:189], v[166:169]
	v_mfma_f32_16x16x32_bf16 v[86:89], v[158:161], v[200:203], v[26:29]
	v_mfma_f32_16x16x32_bf16 v[26:29], v[194:197], v[186:189], v[170:173]
	v_mfma_f32_16x16x32_bf16 v[82:85], v[244:247], v[200:203], v[26:29]
	v_mfma_f32_16x16x32_bf16 v[26:29], v[126:129], v[222:225], v[70:73]
	v_mfma_f32_16x16x32_bf16 v[70:73], v[158:161], v[240:243], v[26:29]
	v_mfma_f32_16x16x32_bf16 v[26:29], v[194:197], v[222:225], v[66:69]
	v_mfma_f32_16x16x32_bf16 v[66:69], v[244:247], v[240:243], v[26:29]
	s_setprio 0
	s_barrier
	ds_read_b128 v[162:165], v147 offset:49152
	ds_read_b128 v[166:169], v147 offset:50176
	ds_read_b128 v[170:173], v147 offset:51200
	ds_read_b128 v[186:189], v147 offset:52224
	ds_read_b128 v[198:201], v147 offset:53248
	ds_read_b128 v[202:205], v147 offset:54272
	ds_read_b128 v[222:225], v147 offset:55296
	ds_read_b128 v[146:149], v147 offset:56320
	s_barrier
	s_waitcnt lgkmcnt(0)
	s_setprio 1
	s_waitcnt lgkmcnt(7)
	v_mfma_f32_16x16x32_bf16 v[26:29], v[10:13], v[162:165], v[62:65]
	s_waitcnt lgkmcnt(6)
	v_mfma_f32_16x16x32_bf16 v[62:65], v[14:17], v[166:169], v[26:29]
	v_mfma_f32_16x16x32_bf16 v[26:29], v[178:181], v[162:165], v[58:61]
	v_mfma_f32_16x16x32_bf16 v[58:61], v[182:185], v[166:169], v[26:29]
	s_waitcnt lgkmcnt(5)
	v_mfma_f32_16x16x32_bf16 v[26:29], v[10:13], v[170:173], v[54:57]
	s_waitcnt lgkmcnt(4)
	v_mfma_f32_16x16x32_bf16 v[46:49], v[14:17], v[186:189], v[26:29]
	v_mfma_f32_16x16x32_bf16 v[26:29], v[178:181], v[170:173], v[50:53]
	v_mfma_f32_16x16x32_bf16 v[42:45], v[182:185], v[186:189], v[26:29]
	s_waitcnt lgkmcnt(3)
	v_mfma_f32_16x16x32_bf16 v[26:29], v[10:13], v[198:201], v[190:193]
	s_waitcnt lgkmcnt(1)
	v_mfma_f32_16x16x32_bf16 v[10:13], v[10:13], v[222:225], v[38:41]
	v_mfma_f32_16x16x32_bf16 v[30:33], v[14:17], v[202:205], v[26:29]
	v_mfma_f32_16x16x32_bf16 v[26:29], v[178:181], v[198:201], v[236:239]
	s_waitcnt lgkmcnt(0)
	v_mfma_f32_16x16x32_bf16 v[14:17], v[14:17], v[146:149], v[10:13]
	v_mfma_f32_16x16x32_bf16 v[10:13], v[178:181], v[222:225], v[34:37]
	v_mfma_f32_16x16x32_bf16 v[26:29], v[182:185], v[202:205], v[26:29]
	v_mfma_f32_16x16x32_bf16 v[10:13], v[182:185], v[146:149], v[10:13]
	s_setprio 0
	s_setprio 1
	v_mfma_f32_16x16x32_bf16 v[34:37], v[126:129], v[162:165], v[134:137]
	v_mfma_f32_16x16x32_bf16 v[54:57], v[158:161], v[166:169], v[34:37]
	v_mfma_f32_16x16x32_bf16 v[34:37], v[194:197], v[162:165], v[150:153]
	v_mfma_f32_16x16x32_bf16 v[18:21], v[194:197], v[170:173], v[18:21]
	v_mfma_f32_16x16x32_bf16 v[50:53], v[244:247], v[166:169], v[34:37]
	v_mfma_f32_16x16x32_bf16 v[22:25], v[126:129], v[170:173], v[22:25]
	v_mfma_f32_16x16x32_bf16 v[34:37], v[244:247], v[186:189], v[18:21]
	v_mfma_f32_16x16x32_bf16 v[18:21], v[126:129], v[198:201], v[154:157]
	v_mfma_f32_16x16x32_bf16 v[38:41], v[158:161], v[186:189], v[22:25]
	v_mfma_f32_16x16x32_bf16 v[22:25], v[158:161], v[202:205], v[18:21]
	v_mfma_f32_16x16x32_bf16 v[18:21], v[194:197], v[198:201], v[174:177]
	v_mfma_f32_16x16x32_bf16 v[6:9], v[126:129], v[222:225], v[6:9]
	v_mfma_f32_16x16x32_bf16 v[2:5], v[194:197], v[222:225], v[2:5]
	v_mfma_f32_16x16x32_bf16 v[18:21], v[244:247], v[202:205], v[18:21]
	v_mfma_f32_16x16x32_bf16 v[6:9], v[158:161], v[146:149], v[6:9]
	v_mfma_f32_16x16x32_bf16 v[2:5], v[244:247], v[146:149], v[2:5]
	s_setprio 0
	s_movk_i32 s0, 0x100
	v_cmp_gt_u32_e32 vcc, s0, v140
	s_barrier
	s_and_saveexec_b64 s[0:1], vcc
	s_cbranch_execz .LBB0_764
	s_barrier
